# attention prompt phase: hand-written tile + table-driven step loop with static vmcnt, 3-deep K/V/Q prefetch; q/k/v bf16 copies stored head-major
# speedup vs baseline: 1.0141x; 1.0141x over previous
; __device__ __forceinline__ void st_bf8(bf16* p, const f32x4 a, const f32x4 b) { *(GAS v4u*)p = (v4u){pk2(a.x, a.y), pk2(a.z, a.w), pk2(b.x, b.y), pk2(b.z, b.w)}; }
; __device__ __forceinline__ float sq4(const f32x4 a) { return (a.x * a.x + a.y * a.y) + (a.z * a.z + a.w * a.w); }
; __device__ __forceinline__ void nt_store4(float* p, f32x4 v) { __builtin_nontemporal_store(v, (f32x4*)p); }
;     template <int NR> __device__ __forceinline__ void rows(const int (&rowb)[NR], int fr, const float (&rstd)[NR], const f32x4 (&a)[NR][2][2], int pn, int wc, int fq) const {
;     ...
;         bf16* dbase = (bf16*)(qkv_base + (size_t)(which * 3 + g) * QKV_STRIDE) + h * 64 + 8 * fq;
;         float* kvp = out + (g == 0 ? O_KV128P : g == 1 ? O_KV512P : O_KV2048P) + (size_t)(which - 1) * 1024 + h * 64 + 8 * fq;
;         float* kvs = out + (g == 0 ? O_KV128S : g == 1 ? O_KV512S : O_KV2048S) + (size_t)(which - 1) * 1024 + h * 64 + 8 * fq;
; #pragma unroll
;         for (int i = 0; i < NR; ++i) {
;             const float rr = rstd[i];
;             f32x4 v[2][2] = {{a[i][0][0] * rr, a[i][0][1] * rr}, {a[i][1][0] * rr, a[i][1][1] * rr}};
;             if (which < 2) {
;                 float ss = sq4(v[0][0]) + sq4(v[0][1]) + sq4(v[1][0]) + sq4(v[1][1]);
;                 ss += __shfl_xor(ss, 16); ss += __shfl_xor(ss, 32);
;                 float sc = rsqrtf(ss * (1.f / 64.f) + EPS); if (which == 0) sc *= QSCALE;
; #pragma unroll
;                 for (int bj = 0; bj < 2; ++bj)
; #pragma unroll
;                     for (int n = 0; n < 2; ++n) v[bj][n] = v[bj][n] * wv[bj][n] * sc;
;             }
;             const int rw = rowb[i] + fr; int arow = rw, b, t = 0; const bool prompt = rw < MP;
;             if (prompt) { b = rw >> 12; t = rw & 4095; arow = (b << 12) + ((t & ((1 << dsh) - 1)) << (12 - dsh)) + (t >> dsh); } else { b = (rw - MP) >> 3; }
;             bf16* dst = dbase + (size_t)arow * DM;
;             st_bf8(dst, v[0][0], v[0][1]); st_bf8(dst + 32, v[1][0], v[1][1]);
;             if (which >= 1) {
;                 float* o = nullptr;
;                 if (prompt) { if (t >= SEQ - W) o = kvp + (size_t)(b * W + (t - (SEQ - W))) * 2048; }
;                 else o = kvs + (size_t)(rw - MP) * 2048;
;                 if (o) { nt_store4(o, v[0][0]); nt_store4(o + 4, v[0][1]); nt_store4(o + 32, v[1][0]); nt_store4(o + 36, v[1][1]); }
.LBB0_1070:
	s_mul_hi_i32 s5, s4, 0x2aaaaaab
	s_lshr_b32 s14, s5, 31
	s_ashr_i32 s5, s5, 1
	s_add_i32 s14, s5, s14
	s_ashr_i32 s5, s18, 4
	s_mul_hi_i32 s15, s5, 0x55555556
	s_lshr_b32 s16, s15, 31
	s_add_i32 s15, s15, s16
	s_mul_i32 s15, s15, 3
	s_add_i32 s36, s20, s19
	s_sub_i32 s19, s5, s15
	s_mul_i32 s5, s14, 3
	s_add_i32 s5, s5, s19
	s_lshl_b32 s37, s19, 1
	s_mul_hi_i32 s15, s5, 0x2100000
	s_mul_i32 s5, s5, 0x2100000
	s_add_u32 s16, s24, s5
	s_addc_u32 s15, s25, s15
	s_lshl_b32 s5, s18, 6
	s_and_b32 s5, s5, 0x3c0
	s_mul_i32 s17, s5, 0x8200
	s_add_u32 s16, s16, s17
	s_addc_u32 s17, s15, 0
	s_waitcnt vmcnt(1)
	v_lshlrev_b32_e32 v2, 1, v146
	v_mov_b32_e32 v3, v149
	s_waitcnt vmcnt(0)
	v_lshl_add_u64 v[6:7], s[16:17], 0, v[2:3]
	v_or_b32_e32 v2, s36, v147
	v_bitop3_b32 v4, s36, v165, v147 bitop3:0xc8
	s_sub_i32 s16, 12, s37
	s_and_b32 s15, s36, 0xfffff000
	v_lshlrev_b32_e32 v3, s16, v2
	v_lshrrev_b32_e32 v5, s37, v4
	v_and_b32_e32 v3, 0xfff, v3
	v_or_b32_e32 v5, s15, v5
	v_add_u32_e32 v3, v5, v3
	v_cmp_gt_i32_e32 vcc, s1, v2
	v_mov_b32_e32 v9, v149
	s_cmp_lt_i32 s4, 12
	v_cndmask_b32_e32 v8, v2, v3, vcc
	v_lshlrev_b64 v[8:9], 7, v[8:9]
	v_lshl_add_u64 v[10:11], v[6:7], 0, v[8:9]
	v_cvt_pk_bf16_f32 v6, v14, v15
	v_cvt_pk_bf16_f32 v7, v16, v17
	v_cvt_pk_bf16_f32 v8, v18, v19
	v_cvt_pk_bf16_f32 v9, v20, v21
	global_store_dwordx4 v[10:11], v[6:9], off
	s_nop 1
	v_cvt_pk_bf16_f32 v6, v22, v23
	v_cvt_pk_bf16_f32 v7, v24, v25
	v_cvt_pk_bf16_f32 v8, v26, v27
	v_cvt_pk_bf16_f32 v9, v28, v29
	global_store_dwordx4 v[10:11], v[6:9], off offset:64
	s_cbranch_scc1 .LBB0_1060
	s_add_i32 s14, s14, -1
	s_ashr_i32 s15, s14, 31
	s_cmp_eq_u32 s19, 1
	s_cselect_b64 s[16:17], -1, 0
	s_and_b64 s[38:39], s[16:17], exec
	s_cselect_b32 s4, s22, 0x2ac0000
	s_cmp_eq_u32 s19, 0
	s_cselect_b64 s[18:19], -1, 0
	s_and_b64 s[38:39], s[18:19], exec
	s_cselect_b32 s4, 0x15c0000, s4
	s_lshl_b32 s4, s4, 2
	s_add_u32 s4, s28, s4
	s_addc_u32 s46, s29, 0
	s_lshl_b64 s[38:39], s[14:15], 12
	s_add_u32 s4, s4, s38
	s_addc_u32 s39, s46, s39
	s_lshl_b32 s38, s5, 2
	s_add_u32 s4, s4, s38
	s_addc_u32 s5, s39, 0
	v_add_u32_e32 v2, 0xffffc000, v2
	v_mov_b32_e32 v3, v149
	v_lshl_add_u64 v[6:7], s[4:5], 0, v[148:149]
	v_lshlrev_b64 v[2:3], 13, v[2:3]
	v_lshl_add_u64 v[2:3], v[6:7], 0, v[2:3]
	s_and_saveexec_b64 s[4:5], vcc
	s_cbranch_execz .LBB0_1073
	s_lshl_b64 s[14:15], s[14:15], 10
	s_lshl_b32 s39, 0xffffff80, s37
	s_and_b64 s[16:17], s[16:17], exec
	s_cselect_b32 s46, s23, 0x1ac0000
	s_and_b64 s[16:17], s[18:19], exec
	s_cselect_b32 s16, 0x14c0000, s46
	s_lshl_b32 s16, s16, 2
	s_add_u32 s16, s28, s16
	s_addc_u32 s17, s29, 0
	s_lshl_b64 s[14:15], s[14:15], 2
	s_add_u32 s14, s16, s14
	s_addc_u32 s15, s17, s15
	s_add_u32 s14, s14, s38
	s_addc_u32 s15, s15, 0
	v_lshl_add_u64 v[2:3], s[14:15], 0, v[148:149]
	s_lshr_b32 s14, s36, 12
	s_add_i32 s37, s37, 7
	s_lshl_b32 s14, s14, s37
	v_subrev_u32_e32 v5, s39, v4
	v_add_u32_e32 v5, s14, v5
	v_add_u32_e32 v6, 0xfffff000, v5
	v_ashrrev_i32_e32 v7, 31, v6
	s_add_i32 s15, s39, 0x1000
	v_lshlrev_b64 v[6:7], 13, v[6:7]
	v_lshl_add_u64 v[2:3], v[2:3], 0, v[6:7]
	v_cmp_le_i32_e32 vcc, s15, v4
	s_nop 1
	v_cndmask_b32_e32 v3, 0, v3, vcc
	v_cndmask_b32_e32 v2, 0, v2, vcc

; __device__ __forceinline__ void st_bf8(bf16* p, const f32x4 a, const f32x4 b) { *(GAS v4u*)p = (v4u){pk2(a.x, a.y), pk2(a.z, a.w), pk2(b.x, b.y), pk2(b.z, b.w)}; }
; __device__ __forceinline__ float sq4(const f32x4 a) { return (a.x * a.x + a.y * a.y) + (a.z * a.z + a.w * a.w); }
; __device__ __forceinline__ void nt_store4(float* p, f32x4 v) { __builtin_nontemporal_store(v, (f32x4*)p); }
;     template <int NR> __device__ __forceinline__ void rows(const int (&rowb)[NR], int fr, const float (&rstd)[NR], const f32x4 (&a)[NR][2][2], int pn, int wc, int fq) const {
;     ...
;         bf16* dbase = (bf16*)(qkv_base + (size_t)(which * 3 + g) * QKV_STRIDE) + h * 64 + 8 * fq;
;         float* kvp = out + (g == 0 ? O_KV128P : g == 1 ? O_KV512P : O_KV2048P) + (size_t)(which - 1) * 1024 + h * 64 + 8 * fq;
;         float* kvs = out + (g == 0 ? O_KV128S : g == 1 ? O_KV512S : O_KV2048S) + (size_t)(which - 1) * 1024 + h * 64 + 8 * fq;
; #pragma unroll
;         for (int i = 0; i < NR; ++i) {
;             const float rr = rstd[i];
;             f32x4 v[2][2] = {{a[i][0][0] * rr, a[i][0][1] * rr}, {a[i][1][0] * rr, a[i][1][1] * rr}};
;             if (which < 2) {
;                 float ss = sq4(v[0][0]) + sq4(v[0][1]) + sq4(v[1][0]) + sq4(v[1][1]);
;                 ss += __shfl_xor(ss, 16); ss += __shfl_xor(ss, 32);
;                 float sc = rsqrtf(ss * (1.f / 64.f) + EPS); if (which == 0) sc *= QSCALE;
; #pragma unroll
;                 for (int bj = 0; bj < 2; ++bj)
; #pragma unroll
;                     for (int n = 0; n < 2; ++n) v[bj][n] = v[bj][n] * wv[bj][n] * sc;
;             }
;             const int rw = rowb[i] + fr; int arow = rw, b, t = 0; const bool prompt = rw < MP;
;             if (prompt) { b = rw >> 12; t = rw & 4095; arow = (b << 12) + ((t & ((1 << dsh) - 1)) << (12 - dsh)) + (t >> dsh); } else { b = (rw - MP) >> 3; }
;             bf16* dst = dbase + (size_t)arow * DM;
;             st_bf8(dst, v[0][0], v[0][1]); st_bf8(dst + 32, v[1][0], v[1][1]);
;             if (which >= 1) {
;                 float* o = nullptr;
;                 if (prompt) { if (t >= SEQ - W) o = kvp + (size_t)(b * W + (t - (SEQ - W))) * 2048; }
;                 else o = kvs + (size_t)(rw - MP) * 2048;
;                 if (o) { nt_store4(o, v[0][0]); nt_store4(o + 4, v[0][1]); nt_store4(o + 32, v[1][0]); nt_store4(o + 36, v[1][1]); }
.LBB0_1144:
	s_mul_hi_i32 s5, s4, 0x2aaaaaab
	s_lshr_b32 s12, s5, 31
	s_ashr_i32 s5, s5, 1
	s_add_i32 s12, s5, s12
	s_ashr_i32 s5, s16, 4
	s_mul_hi_i32 s13, s5, 0x55555556
	s_lshr_b32 s14, s13, 31
	s_add_i32 s13, s13, s14
	s_mul_i32 s13, s13, 3
	s_add_i32 s23, s18, s17
	s_sub_i32 s17, s5, s13
	s_mul_i32 s5, s12, 3
	s_add_i32 s5, s5, s17
	s_lshl_b32 s34, s17, 1
	s_mul_hi_i32 s13, s5, 0x2100000
	s_mul_i32 s5, s5, 0x2100000
	s_add_u32 s14, s24, s5
	s_addc_u32 s13, s25, s13
	s_lshl_b32 s5, s16, 6
	s_and_b32 s5, s5, 0x3c0
	s_mul_i32 s15, s5, 0x8200
	s_add_u32 s14, s14, s15
	s_addc_u32 s15, s13, 0
	s_waitcnt vmcnt(1)
	v_lshlrev_b32_e32 v2, 1, v146
	v_mov_b32_e32 v3, v149
	s_waitcnt vmcnt(0)
	v_lshl_add_u64 v[6:7], s[14:15], 0, v[2:3]
	v_or_b32_e32 v2, s23, v147
	v_bitop3_b32 v4, s23, v165, v147 bitop3:0xc8
	s_sub_i32 s14, 12, s34
	s_and_b32 s13, s23, 0xfffff000
	v_lshlrev_b32_e32 v3, s14, v2
	v_lshrrev_b32_e32 v5, s34, v4
	v_and_b32_e32 v3, 0xfff, v3
	v_or_b32_e32 v5, s13, v5
	v_add_u32_e32 v3, v5, v3
	v_cmp_gt_i32_e32 vcc, s1, v2
	v_mov_b32_e32 v9, v149
	s_cmp_lt_i32 s4, 12
	v_cndmask_b32_e32 v8, v2, v3, vcc
	v_lshlrev_b64 v[8:9], 7, v[8:9]
	v_lshl_add_u64 v[10:11], v[6:7], 0, v[8:9]
	v_cvt_pk_bf16_f32 v6, v14, v15
	v_cvt_pk_bf16_f32 v7, v16, v17
	v_cvt_pk_bf16_f32 v8, v18, v19
	v_cvt_pk_bf16_f32 v9, v20, v21
	global_store_dwordx4 v[10:11], v[6:9], off
	s_nop 1
	v_cvt_pk_bf16_f32 v6, v22, v23
	v_cvt_pk_bf16_f32 v7, v24, v25
	v_cvt_pk_bf16_f32 v8, v26, v27
	v_cvt_pk_bf16_f32 v9, v28, v29
	global_store_dwordx4 v[10:11], v[6:9], off offset:64
	s_cbranch_scc1 .LBB0_1134
	s_add_i32 s12, s12, -1
	s_ashr_i32 s13, s12, 31
	s_cmp_eq_u32 s17, 1
	s_cselect_b64 s[14:15], -1, 0
	s_and_b64 s[36:37], s[14:15], exec
	s_cselect_b32 s4, s21, 0x2ac0000
	s_cmp_eq_u32 s17, 0
	s_cselect_b64 s[16:17], -1, 0
	s_and_b64 s[36:37], s[16:17], exec
	s_cselect_b32 s4, 0x15c0000, s4
	s_lshl_b32 s4, s4, 2
	s_add_u32 s4, s28, s4
	s_addc_u32 s35, s29, 0
	s_lshl_b64 s[36:37], s[12:13], 12
	s_add_u32 s4, s4, s36
	s_addc_u32 s36, s35, s37
	s_lshl_b32 s35, s5, 2
	s_add_u32 s4, s4, s35
	s_addc_u32 s5, s36, 0
	v_add_u32_e32 v2, 0xffffc000, v2
	v_mov_b32_e32 v3, v149
	v_lshl_add_u64 v[6:7], s[4:5], 0, v[148:149]
	v_lshlrev_b64 v[2:3], 13, v[2:3]
	v_lshl_add_u64 v[2:3], v[6:7], 0, v[2:3]
	s_and_saveexec_b64 s[4:5], vcc
	s_cbranch_execz .LBB0_1147
	s_lshl_b64 s[12:13], s[12:13], 10
	s_lshl_b32 s36, 0xffffff80, s34
	s_and_b64 s[14:15], s[14:15], exec
	s_cselect_b32 s37, s22, 0x1ac0000
	s_and_b64 s[14:15], s[16:17], exec
	s_cselect_b32 s14, 0x14c0000, s37
	s_lshl_b32 s14, s14, 2
	s_add_u32 s14, s28, s14
	s_addc_u32 s15, s29, 0
	s_lshl_b64 s[12:13], s[12:13], 2
	s_add_u32 s12, s14, s12
	s_addc_u32 s13, s15, s13
	s_add_u32 s12, s12, s35
	s_addc_u32 s13, s13, 0
	v_lshl_add_u64 v[2:3], s[12:13], 0, v[148:149]
	s_lshr_b32 s12, s23, 12
	s_add_i32 s34, s34, 7
	s_lshl_b32 s12, s12, s34
	v_subrev_u32_e32 v5, s36, v4
	v_add_u32_e32 v5, s12, v5
	v_add_u32_e32 v6, 0xfffff000, v5
	v_ashrrev_i32_e32 v7, 31, v6
	s_add_i32 s13, s36, 0x1000
	v_lshlrev_b64 v[6:7], 13, v[6:7]
	v_lshl_add_u64 v[2:3], v[2:3], 0, v[6:7]
	v_cmp_le_i32_e32 vcc, s13, v4
	s_nop 1
	v_cndmask_b32_e32 v3, 0, v3, vcc
	v_cndmask_b32_e32 v2, 0, v2, vcc

; #define GAS __attribute__((address_space(1)))
; __device__ __forceinline__ float bflo(unsigned w) { return __uint_as_float(w << 16); }
; __device__ __forceinline__ float bfhi(unsigned w) { return __uint_as_float(w & 0xffff0000u); }
; __device__ __forceinline__ float alibi_slope2(int g, int h) { return exp2f(-8.f * (float)(g * 16 + h + 1) / 48.f) * LOG2E; }
; __device__ __forceinline__ void attn_sample(Frame& F, int i_lo, int i_hi) {
;     const int lane = F.lane, ksub = lane >> 5, hh = (lane >> 4) & 1, dc = lane & 15, w = F.wave;
;     float* LSE = WSP(float, WS_LSE);
;     for (int rnd = i_lo; rnd < i_hi; ++rnd) { const int it = F.bid + rnd * F.G;
;         int s, grp, b;
;         if (F.G == 256) {
;             const int x = F.bid & 7, q = F.bid >> 3, u = (x & 1) ? 64 + 8 * (x >> 1) + 4 * rnd + (q >> 3) : 16 * (x >> 1) + 4 * rnd + (q >> 3); s = q & 7; b = u / 3; grp = u % 3; }
;         else { if (it >= 768) break; s = it & 7; grp = (it >> 3) % 3; b = it / 24; }
;         const int dsh = 2 * grp, W = 128 << dsh, dil = 1 << dsh;
;         const float* cache = F.in[3 + grp] + (size_t)b * W * 2048;
;         const float* newkv = F.out + (grp == 0 ? O_KV128S : grp == 1 ? O_KV512S : O_KV2048S) + (size_t)b * 8 * 2048;
;         const bf16* Qg = (const bf16*)(F.ws + WS_QKV + (size_t)grp * QKV_STRIDE);
;         bf16* Og = (bf16*)(F.ws + WS_OG + (size_t)grp * QKV_STRIDE);
;         const size_t row = (size_t)MP + b * 8 + s;
;         const int h = 2 * w + hh, co = h * 64 + 4 * dc;
;         const v2u qw = *(const GAS v2u*)(Qg + row * DM + co);
;         const f32x4 q = (f32x4){bflo(qw.x), bfhi(qw.x), bflo(qw.y), bfhi(qw.y)};
;         const float sl2 = alibi_slope2(grp, h) * (float)dil;
;         float mx = -INFINITY, lsum = 0.f; f32x4 o = (f32x4){0.f, 0.f, 0.f, 0.f};
.LBB0_1207:
	s_bfe_i32 s0, s2, 0x10003
	v_and_b32_e32 v193, s0, v161
	v_cmp_eq_u32_e32 vcc, 0, v193
	v_lshrrev_b32_e32 v195, 5, v160
	s_mov_b32 s33, 0
	s_cbranch_vccnz .LBB0_1224
	v_readlane_b32 s0, v245, 8
	s_waitcnt vmcnt(0)
	v_lshrrev_b32_e32 v2, 4, v160
	s_lshl_b32 s0, s0, 1
	v_and_or_b32 v4, v2, 1, s0
	v_lshlrev_b32_e32 v2, 2, v160
	v_and_b32_e32 v2, 60, v2
	v_mov_b32_e32 v3, 0
	v_and_b32_e32 v5, 47, v160
	v_lshl_or_b32 v2, v4, 6, v2
	v_add_u32_e32 v144, 1, v4
	v_cmp_eq_u32_e64 s[8:9], 0, v5
	v_lshlrev_b32_e32 v4, 2, v4
	v_mov_b32_e32 v5, v3
	v_lshl_add_u64 v[4:5], s[30:31], 0, v[4:5]
	s_mov_b64 s[4:5], 0x29300000
	v_lshl_add_u64 v[128:129], v[4:5], 0, s[4:5]
	s_lshl_b32 s5, s2, 2
	s_and_b32 s3, s2, 7
	s_and_b32 s5, s5, 24
	s_ashr_i32 s10, s2, 6
	s_add_i32 s5, s10, s5
	s_lshl_b32 s3, s3, 3
	s_lshr_b32 s1, s2, 3
	s_and_b32 s4, s2, 1
	s_add_i32 s5, s5, 64
	s_add_i32 s10, s3, s10
	s_add_u32 s3, s30, 0x23000000
	v_lshlrev_b64 v[130:131], 2, v[2:3]
	v_lshlrev_b32_e32 v153, 1, v2
	v_lshrrev_b32_e32 v255, 6, v2
	v_and_b32_e32 v254, 63, v2
	v_lshlrev_b32_e32 v254, 1, v254
	v_mul_u32_u24_e32 v255, 0x208000, v255
	v_add_u32_e32 v254, v255, v254
	v_mbcnt_lo_u32_b32 v2, -1, 0
	s_addc_u32 s34, s31, 0
	v_mbcnt_hi_u32_b32 v156, -1, v2
	v_or_b32_e32 v6, 0x80, v195
	s_cmp_eq_u32 s4, 0
	v_and_b32_e32 v2, 64, v156
	v_cmp_gt_u32_e64 s[6:7], 32, v160
	s_mov_b32 s0, 0
	v_or_b32_e32 v145, 2, v195
	v_or_b32_e32 v146, 4, v195
	v_or_b32_e32 v147, 6, v195
	v_or_b32_e32 v148, 8, v195
	v_or_b32_e32 v149, 10, v195
	v_or_b32_e32 v150, 12, v195
	v_or_b32_e32 v151, 14, v195
	v_cvt_f32_ubyte0_e32 v152, v6
	s_cselect_b32 s35, s10, s5
	s_mov_b32 s45, 0x1a40000
	s_mov_b32 s46, 0x42400000
	s_mov_b32 s47, 0xc2fc0000
	s_movk_i32 s48, 0x1000
	s_movk_i32 s49, 0x81
	s_mov_b32 s60, 0xff800000
	s_movk_i32 s61, 0x7f
	s_movk_i32 s62, 0x7d
	s_movk_i32 s63, 0x7b
	s_movk_i32 s64, 0x79
	s_movk_i32 s65, 0x77
	s_movk_i32 s66, 0x75
	s_movk_i32 s67, 0x73
	v_mov_b32_e32 v154, 0x42800000
	v_not_b32_e32 v155, 63
	v_xor_b32_e32 v157, 1, v156
	v_add_u32_e32 v158, 64, v2
	v_xor_b32_e32 v159, 2, v156
	v_xor_b32_e32 v162, 4, v156
	v_xor_b32_e32 v163, 8, v156
	v_xor_b32_e32 v164, 32, v156
	v_mov_b32_e32 v165, 0xff800000
	s_branch .LBB0_1211

; #define GAS __attribute__((address_space(1)))
; __device__ __forceinline__ float bflo(unsigned w) { return __uint_as_float(w << 16); }
; __device__ __forceinline__ float bfhi(unsigned w) { return __uint_as_float(w & 0xffff0000u); }
; __device__ __forceinline__ float alibi_slope2(int g, int h) { return exp2f(-8.f * (float)(g * 16 + h + 1) / 48.f) * LOG2E; }
; __device__ __forceinline__ void attn_sample(Frame& F, int i_lo, int i_hi) {
;     ...
;         const int dsh = 2 * grp, W = 128 << dsh, dil = 1 << dsh;
;         const float* cache = F.in[3 + grp] + (size_t)b * W * 2048;
;         const float* newkv = F.out + (grp == 0 ? O_KV128S : grp == 1 ? O_KV512S : O_KV2048S) + (size_t)b * 8 * 2048;
;         const bf16* Qg = (const bf16*)(F.ws + WS_QKV + (size_t)grp * QKV_STRIDE);
;         bf16* Og = (bf16*)(F.ws + WS_OG + (size_t)grp * QKV_STRIDE);
;         const size_t row = (size_t)MP + b * 8 + s;
;         const int h = 2 * w + hh, co = h * 64 + 4 * dc;
;         const v2u qw = *(const GAS v2u*)(Qg + row * DM + co);
;         const f32x4 q = (f32x4){bflo(qw.x), bfhi(qw.x), bflo(qw.y), bfhi(qw.y)};
;         const float sl2 = alibi_slope2(grp, h) * (float)dil;
;         float mx = -INFINITY, lsum = 0.f; f32x4 o = (f32x4){0.f, 0.f, 0.f, 0.f};
;     ...
;         f32x4 ka[8], va[8], kb[8], vb[8];
;         SMP_LOAD(ka, va, 0);
; #pragma unroll 1
;         for (int j0 = 0; j0 < 128; j0 += 32) {
;             SMP_LOAD(kb, vb, j0 + 16);
.LBB0_1218:
	s_mul_hi_i32 s10, s5, 0x55555556
	s_lshr_b32 s12, s10, 31
	s_add_i32 s10, s10, s12
	s_mul_i32 s10, s10, 3
	s_sub_i32 s54, s5, s10
	s_lshl_b32 s69, s54, 1
	s_ashr_i32 s55, s54, 31
	s_and_b32 s11, s14, 7
	s_lshl_b32 s70, 0x80, s69
	s_lshl_b32 s10, 1, s69
	s_lshl_b64 s[12:13], s[54:55], 3
	s_add_u32 s12, s88, s12
	s_addc_u32 s13, s89, s13
	s_load_dwordx2 s[12:13], s[12:13], 0x18
	s_ashr_i32 s5, s4, 31
	s_add_i32 s14, s69, 7
	s_lshl_b64 s[14:15], s[4:5], s14
	s_lshl_b64 s[14:15], s[14:15], 13
	s_waitcnt lgkmcnt(0)
	s_add_u32 s71, s12, s14
	s_addc_u32 s72, s13, s15
	s_cmp_eq_u32 s54, 1
	s_cselect_b32 s12, s45, 0x2ac0000
	s_cmp_lg_u32 s54, 0
	s_cselect_b32 s12, s12, 0x15c0000
	s_lshl_b32 s12, s12, 2
	s_add_u32 s14, s28, s12
	s_addc_u32 s15, s29, 0
	s_lshl_b64 s[12:13], s[4:5], 16
	s_add_u32 s5, s14, s12
	s_addc_u32 s73, s15, s13
	s_mul_i32 s68, s54, 0x2100000
	s_mul_hi_i32 s55, s54, 0x2100000
	s_add_u32 s14, s24, s68
	s_addc_u32 s15, s25, s55
	s_lshl_b32 s4, s4, 3
	s_ashr_i32 s12, s4, 31
	s_or_b32 s4, s4, s11
	s_add_u32 s56, s4, 0x4000
	s_addc_u32 s57, s12, 0
	s_lshl_b64 s[58:59], s[56:57], 10
	s_lshl_b64 s[12:13], s[56:57], 7
	s_add_u32 s12, s14, s12
	s_addc_u32 s13, s15, s13
	s_or_b32 s4, s70, s11
	v_lshlrev_b32_e32 v2, s69, v195
	v_sub_u32_e32 v2, s4, v2
	v_ashrrev_i32_e32 v3, 31, v2
	v_subrev_u32_e32 v4, s70, v2
	v_cmp_gt_i32_e32 vcc, s70, v2
	v_mov_b32_e32 v32, s73
	v_mov_b32_e32 v33, s72
	v_cndmask_b32_e32 v3, 0, v3, vcc
	v_cndmask_b32_e32 v2, v4, v2, vcc
	v_mov_b32_e32 v58, s5
	v_mov_b32_e32 v59, s71
	v_cndmask_b32_e32 v5, v32, v33, vcc
	v_cndmask_b32_e32 v4, v58, v59, vcc
	v_lshlrev_b64 v[2:3], 13, v[2:3]
	v_lshl_add_u64 v[2:3], v[4:5], 0, v[2:3]
	v_lshl_add_u64 v[2:3], v[2:3], 0, v[130:131]
	v_add_co_u32_e32 v4, vcc, s48, v2
	v_lshlrev_b32_e32 v6, s69, v145
	s_nop 0
	v_addc_co_u32_e32 v5, vcc, 0, v3, vcc
	v_sub_u32_e32 v6, s4, v6
	v_ashrrev_i32_e32 v7, 31, v6
	v_subrev_u32_e32 v8, s70, v6
	v_cmp_gt_i32_e32 vcc, s70, v6
	v_lshlrev_b32_e32 v10, s69, v146
	v_sub_u32_e32 v10, s4, v10
	v_cndmask_b32_e32 v7, 0, v7, vcc
	v_cndmask_b32_e32 v6, v8, v6, vcc
	v_cndmask_b32_e32 v9, v32, v33, vcc
	v_cndmask_b32_e32 v8, v58, v59, vcc
	v_lshlrev_b64 v[6:7], 13, v[6:7]
	v_lshl_add_u64 v[6:7], v[8:9], 0, v[6:7]
	v_lshl_add_u64 v[6:7], v[6:7], 0, v[130:131]
	v_add_co_u32_e32 v8, vcc, s48, v6
	v_ashrrev_i32_e32 v11, 31, v10
	s_nop 0
	v_addc_co_u32_e32 v9, vcc, 0, v7, vcc
	v_subrev_u32_e32 v12, s70, v10
	v_cmp_gt_i32_e32 vcc, s70, v10
	v_lshlrev_b32_e32 v14, s69, v147
	v_sub_u32_e32 v14, s4, v14
	v_cndmask_b32_e32 v11, 0, v11, vcc
	v_cndmask_b32_e32 v10, v12, v10, vcc
	v_cndmask_b32_e32 v13, v32, v33, vcc
	v_cndmask_b32_e32 v12, v58, v59, vcc
	v_lshlrev_b64 v[10:11], 13, v[10:11]
	v_lshl_add_u64 v[10:11], v[12:13], 0, v[10:11]
	v_lshl_add_u64 v[10:11], v[10:11], 0, v[130:131]
	v_add_co_u32_e32 v12, vcc, s48, v10
	v_ashrrev_i32_e32 v15, 31, v14
	s_nop 0
	v_addc_co_u32_e32 v13, vcc, 0, v11, vcc
	v_subrev_u32_e32 v16, s70, v14
	v_cmp_gt_i32_e32 vcc, s70, v14
	v_lshlrev_b32_e32 v18, s69, v148
	v_sub_u32_e32 v18, s4, v18
	v_cndmask_b32_e32 v15, 0, v15, vcc
	v_cndmask_b32_e32 v14, v16, v14, vcc
	v_cndmask_b32_e32 v17, v32, v33, vcc
	v_cndmask_b32_e32 v16, v58, v59, vcc
	v_lshlrev_b64 v[14:15], 13, v[14:15]
	v_lshl_add_u64 v[14:15], v[16:17], 0, v[14:15]
	v_lshl_add_u64 v[14:15], v[14:15], 0, v[130:131]
	v_add_co_u32_e32 v16, vcc, s48, v14
	v_ashrrev_i32_e32 v19, 31, v18
	s_nop 0
	v_addc_co_u32_e32 v17, vcc, 0, v15, vcc
	v_subrev_u32_e32 v20, s70, v18
	v_cmp_gt_i32_e32 vcc, s70, v18
	global_load_dwordx2 v[66:67], v254, s[12:13]
	v_lshlrev_b32_e32 v22, s69, v149
	v_cndmask_b32_e32 v19, 0, v19, vcc
	v_cndmask_b32_e32 v18, v20, v18, vcc
	v_cndmask_b32_e32 v21, v32, v33, vcc
	v_cndmask_b32_e32 v20, v58, v59, vcc
	v_lshlrev_b64 v[18:19], 13, v[18:19]
	v_lshl_add_u64 v[18:19], v[20:21], 0, v[18:19]
	v_lshl_add_u64 v[18:19], v[18:19], 0, v[130:131]
	v_add_co_u32_e32 v20, vcc, s48, v18
	v_sub_u32_e32 v22, s4, v22
	s_nop 0
	v_addc_co_u32_e32 v21, vcc, 0, v19, vcc
	v_ashrrev_i32_e32 v23, 31, v22
	v_subrev_u32_e32 v24, s70, v22
	v_cmp_gt_i32_e32 vcc, s70, v22
	v_lshlrev_b32_e32 v26, s69, v150
	v_sub_u32_e32 v26, s4, v26
	v_cndmask_b32_e32 v23, 0, v23, vcc
	v_cndmask_b32_e32 v22, v24, v22, vcc
	v_cndmask_b32_e32 v25, v32, v33, vcc
	v_cndmask_b32_e32 v24, v58, v59, vcc
	v_lshlrev_b64 v[22:23], 13, v[22:23]
	v_lshl_add_u64 v[22:23], v[24:25], 0, v[22:23]
	v_lshl_add_u64 v[22:23], v[22:23], 0, v[130:131]
	v_add_co_u32_e32 v24, vcc, s48, v22
	v_ashrrev_i32_e32 v27, 31, v26
	s_nop 0
	v_addc_co_u32_e32 v25, vcc, 0, v23, vcc
	v_subrev_u32_e32 v28, s70, v26
	v_cmp_gt_i32_e32 vcc, s70, v26
	v_lshlrev_b32_e32 v30, s69, v151
	v_sub_u32_e32 v30, s4, v30
	v_cndmask_b32_e32 v27, 0, v27, vcc
	v_cndmask_b32_e32 v26, v28, v26, vcc
	v_cndmask_b32_e32 v29, v32, v33, vcc
	v_cndmask_b32_e32 v28, v58, v59, vcc
	v_lshlrev_b64 v[26:27], 13, v[26:27]
	v_lshl_add_u64 v[26:27], v[28:29], 0, v[26:27]
	v_lshl_add_u64 v[26:27], v[26:27], 0, v[130:131]
	v_add_co_u32_e32 v28, vcc, s48, v26
	v_ashrrev_i32_e32 v31, 31, v30
	s_nop 0
	v_addc_co_u32_e32 v29, vcc, 0, v27, vcc
	v_subrev_u32_e32 v60, s70, v30
	v_cmp_gt_i32_e32 vcc, s70, v30
	global_load_dwordx4 v[62:65], v[2:3], off nt
	s_nop 0
	global_load_dwordx4 v[2:5], v[4:5], off nt
	v_cndmask_b32_e32 v31, 0, v31, vcc
	v_cndmask_b32_e32 v30, v60, v30, vcc
	v_cndmask_b32_e32 v33, v32, v33, vcc
	v_cndmask_b32_e32 v32, v58, v59, vcc
	v_lshlrev_b64 v[30:31], 13, v[30:31]
	v_lshl_add_u64 v[30:31], v[32:33], 0, v[30:31]
	v_lshl_add_u64 v[30:31], v[30:31], 0, v[130:131]
	global_load_dwordx4 v[42:45], v[6:7], off nt
	s_nop 0
	global_load_dwordx4 v[6:9], v[8:9], off nt
	s_nop 0
	global_load_dwordx4 v[34:37], v[10:11], off nt
	s_nop 0
	global_load_dwordx4 v[10:13], v[12:13], off nt
	s_nop 0
	global_load_dwordx4 v[38:41], v[14:15], off nt
	s_nop 0
	global_load_dwordx4 v[14:17], v[16:17], off nt
	s_nop 0
	global_load_dwordx4 v[46:49], v[18:19], off nt
	s_nop 0
	global_load_dwordx4 v[18:21], v[20:21], off nt
	s_nop 0
	global_load_dwordx4 v[50:53], v[22:23], off nt
	s_nop 0
	global_load_dwordx4 v[22:25], v[24:25], off nt
	s_nop 0
	global_load_dwordx4 v[54:57], v[26:27], off nt
	s_nop 0
	global_load_dwordx4 v[26:29], v[28:29], off nt
	v_lshl_add_u32 v68, s54, 4, v144
	global_load_dwordx4 v[58:61], v[30:31], off nt
	v_add_co_u32_e32 v30, vcc, s48, v30
	v_cvt_f32_i32_e32 v68, v68
	s_nop 0
	v_addc_co_u32_e32 v31, vcc, 0, v31, vcc
	global_load_dwordx4 v[30:33], v[30:31], off nt
	v_mul_f32_e32 v68, 0xc1000000, v68
	v_div_scale_f32 v69, s[12:13], s46, s46, v68
	v_rcp_f32_e32 v70, v69
	v_mov_b32_e32 v172, 0
	v_mov_b32_e32 v173, 0xff800000
	s_movk_i32 s74, 0xffe0
	v_mov_b32_e32 v138, 0
	v_mov_b32_e32 v139, v172
	s_waitcnt vmcnt(16)
; __device__ __forceinline__ float alibi_slope2(int g, int h) { return exp2f(-8.f * (float)(g * 16 + h + 1) / 48.f) * LOG2E; }
; __device__ __forceinline__ void attn_sample(Frame& F, int i_lo, int i_hi) {
;     ...
;         const float sl2 = alibi_slope2(grp, h) * (float)dil;
;         float mx = -INFINITY, lsum = 0.f; f32x4 o = (f32x4){0.f, 0.f, 0.f, 0.f};
	v_and_b32_e32 v132, 0xffff0000, v66
	v_lshlrev_b32_e32 v134, 16, v66
	v_fma_f32 v66, -v69, v70, 1.0
	v_fmac_f32_e32 v70, v66, v70
	v_div_scale_f32 v66, vcc, v68, s46, v68
	v_lshlrev_b32_e32 v133, 16, v67
	v_and_b32_e32 v135, 0xffff0000, v67
	v_mul_f32_e32 v67, v66, v70
	v_fma_f32 v71, -v69, v67, v66
	v_fmac_f32_e32 v67, v71, v70
	v_fma_f32 v66, -v69, v67, v66
	v_div_fmas_f32 v66, v66, v70, v67
	v_div_fixup_f32 v66, v66, s46, v68
	v_cmp_gt_f32_e32 vcc, s47, v66
	v_mov_b32_e32 v136, 0
	v_mov_b32_e32 v137, v172
	v_cndmask_b32_e32 v67, 0, v154, vcc
	v_add_f32_e32 v66, v66, v67
	v_exp_f32_e32 v66, v66
	v_cvt_f32_u32_e32 v67, s10
	v_cndmask_b32_e32 v68, 0, v155, vcc
	v_cmp_lt_i32_e32 vcc, v157, v158
	v_ldexp_f32 v66, v66, v68
	v_mul_f32_e32 v66, 0x3fb8aa3b, v66
	v_mul_f32_e32 v167, v66, v67
	v_cndmask_b32_e32 v66, v156, v157, vcc
	v_cmp_lt_i32_e32 vcc, v159, v158
	v_lshlrev_b32_e32 v168, 2, v66
	s_waitcnt vmcnt(15)
	v_mov_b32_e32 v140, v63
	v_cndmask_b32_e32 v66, v156, v159, vcc
	v_cmp_lt_i32_e32 vcc, v162, v158
	v_lshlrev_b32_e32 v169, 2, v66
	v_mov_b32_e32 v141, v64
	v_cndmask_b32_e32 v66, v156, v162, vcc
	v_cmp_lt_i32_e32 vcc, v163, v158
	v_lshlrev_b32_e32 v170, 2, v66
	v_mov_b32_e32 v63, v65
	v_cndmask_b32_e32 v66, v156, v163, vcc
	v_cmp_lt_i32_e32 vcc, v164, v158
	v_lshlrev_b32_e32 v171, 2, v66
	s_waitcnt vmcnt(13)
	v_mov_b32_e32 v142, v43
	v_cndmask_b32_e32 v66, v156, v164, vcc
	v_lshlrev_b32_e32 v166, 2, v66
	v_mov_b32_e32 v143, v44
	v_mov_b32_e32 v43, v45
	s_waitcnt vmcnt(11)
	v_mov_b32_e32 v44, v35
	v_mov_b32_e32 v45, v36
	v_mov_b32_e32 v35, v37
	s_waitcnt vmcnt(9)
	v_mov_b32_e32 v36, v39
	v_mov_b32_e32 v37, v40
	v_mov_b32_e32 v39, v41
	s_waitcnt vmcnt(7)
	v_mov_b32_e32 v40, v47
	v_mov_b32_e32 v41, v48
	v_mov_b32_e32 v47, v49
	s_waitcnt vmcnt(5)
	v_mov_b32_e32 v48, v51
	v_mov_b32_e32 v49, v52
	v_mov_b32_e32 v51, v53
	s_waitcnt vmcnt(3)
	v_mov_b32_e32 v52, v55
	v_mov_b32_e32 v53, v56
	v_mov_b32_e32 v55, v57
	s_waitcnt vmcnt(1)
	v_mov_b32_e32 v56, v59
	v_mov_b32_e32 v57, v60
	v_mov_b32_e32 v59, v61

; #define GAS __attribute__((address_space(1)))
; __device__ __forceinline__ float bflo(unsigned w) { return __uint_as_float(w << 16); }
; __device__ __forceinline__ float bfhi(unsigned w) { return __uint_as_float(w & 0xffff0000u); }
; __device__ __forceinline__ float alibi_slope2(int g, int h) { return exp2f(-8.f * (float)(g * 16 + h + 1) / 48.f) * LOG2E; }
; __device__ __forceinline__ void attn_sample(Frame& F, int i_lo, int i_hi) {
;     const int lane = F.lane, ksub = lane >> 5, hh = (lane >> 4) & 1, dc = lane & 15, w = F.wave;
;     float* LSE = WSP(float, WS_LSE);
;     for (int rnd = i_lo; rnd < i_hi; ++rnd) { const int it = F.bid + rnd * F.G;
;         int s, grp, b;
;         if (F.G == 256) {
;             const int x = F.bid & 7, q = F.bid >> 3, u = (x & 1) ? 64 + 8 * (x >> 1) + 4 * rnd + (q >> 3) : 16 * (x >> 1) + 4 * rnd + (q >> 3); s = q & 7; b = u / 3; grp = u % 3; }
;         else { if (it >= 768) break; s = it & 7; grp = (it >> 3) % 3; b = it / 24; }
;         const int dsh = 2 * grp, W = 128 << dsh, dil = 1 << dsh;
;         const float* cache = F.in[3 + grp] + (size_t)b * W * 2048;
;         const float* newkv = F.out + (grp == 0 ? O_KV128S : grp == 1 ? O_KV512S : O_KV2048S) + (size_t)b * 8 * 2048;
;         const bf16* Qg = (const bf16*)(F.ws + WS_QKV + (size_t)grp * QKV_STRIDE);
;         bf16* Og = (bf16*)(F.ws + WS_OG + (size_t)grp * QKV_STRIDE);
;         const size_t row = (size_t)MP + b * 8 + s;
;         const int h = 2 * w + hh, co = h * 64 + 4 * dc;
;         const v2u qw = *(const GAS v2u*)(Qg + row * DM + co);
;         const f32x4 q = (f32x4){bflo(qw.x), bfhi(qw.x), bflo(qw.y), bfhi(qw.y)};
;         const float sl2 = alibi_slope2(grp, h) * (float)dil;
;         float mx = -INFINITY, lsum = 0.f; f32x4 o = (f32x4){0.f, 0.f, 0.f, 0.f};
.LBB0_1288:
	v_cmp_ge_u32_e32 vcc, v193, v161
	s_cbranch_vccnz .LBB0_1305
	v_readlane_b32 s0, v245, 8
	v_lshrrev_b32_e32 v2, 4, v160
	s_lshl_b32 s0, s0, 1
	s_waitcnt lgkmcnt(0)
	v_lshlrev_b32_e32 v3, 2, v160
	v_and_or_b32 v2, v2, 1, s0
	v_and_b32_e32 v3, 60, v3
	v_lshl_or_b32 v162, v2, 6, v3
	v_mov_b32_e32 v163, 0
	v_and_b32_e32 v3, 47, v160
	v_add_u32_e32 v197, 1, v2
	v_cmp_eq_u32_e64 s[8:9], 0, v3
	v_lshlrev_b32_e32 v2, 2, v2
	v_mov_b32_e32 v3, v163
	v_lshl_add_u64 v[2:3], s[30:31], 0, v[2:3]
	s_mov_b64 s[0:1], 0x29300000
	s_lshl_b32 s4, s2, 2
	v_lshl_add_u64 v[164:165], v[2:3], 0, s[0:1]
	s_and_b32 s0, s2, 7
	s_and_b32 s4, s4, 24
	s_ashr_i32 s5, s2, 6
	s_add_i32 s4, s5, s4
	s_lshl_b32 s0, s0, 3
	s_lshr_b32 s18, s2, 3
	s_and_b32 s1, s2, 1
	s_add_i32 s4, s4, 64
	s_add_i32 s0, s0, s5
	s_add_u32 s12, s30, 0x23000000
	v_mbcnt_lo_u32_b32 v2, -1, 0
	s_addc_u32 s13, s31, 0
	v_mbcnt_hi_u32_b32 v216, -1, v2
	v_or_b32_e32 v4, 0x80, v195
	s_cmp_eq_u32 s1, 0
	v_and_b32_e32 v2, 64, v216
	s_movk_i32 s3, 0x80
	v_cmp_gt_u32_e64 s[6:7], 32, v160
	v_or_b32_e32 v199, 2, v195
	v_or_b32_e32 v201, 4, v195
	v_or_b32_e32 v204, 6, v195
	v_or_b32_e32 v205, 8, v195
	v_or_b32_e32 v206, 10, v195
	v_or_b32_e32 v207, 12, v195
	v_or_b32_e32 v208, 14, v195
	v_cmp_eq_u32_e64 s[10:11], 0, v195
	v_cvt_f32_ubyte0_e32 v209, v4
	s_cselect_b32 s19, s0, s4
	s_movk_i32 s20, 0x300
	s_mov_b32 s21, 0x2aaaaaab
	s_mov_b32 s22, 0x55555556
	s_mov_b32 s23, 0x2100000
	s_mov_b64 s[14:15], 0x4000
	s_mov_b32 s33, 0x42400000
	s_mov_b32 s34, 0xc2fc0000
	v_lshlrev_b64 v[166:167], 2, v[162:163]
	s_movk_i32 s35, 0x1000
	s_movk_i32 s45, 0x81
	s_mov_b32 s46, 0xff800000
	s_movk_i32 s47, 0x7f
	s_movk_i32 s48, 0x7d
	s_movk_i32 s49, 0x7b
	s_movk_i32 s54, 0x79
	s_movk_i32 s55, 0x77
	s_movk_i32 s56, 0x75
	s_movk_i32 s57, 0x73
	s_movk_i32 s58, 0x4100
	v_mov_b32_e32 v210, 0x2ac0000
	v_mov_b32_e32 v211, 0x1a40000
	v_mov_b32_e32 v212, 0x15c0000
	v_lshlrev_b32_e32 v213, 1, v162
	v_lshrrev_b32_e32 v255, 6, v162
	v_and_b32_e32 v254, 63, v162
	v_lshlrev_b32_e32 v254, 1, v254
	v_mul_u32_u24_e32 v255, 0x208000, v255
	v_add_u32_e32 v254, v255, v254
	v_mov_b32_e32 v214, 0x42800000
	v_not_b32_e32 v215, 63
	v_xor_b32_e32 v217, 1, v216
	v_add_u32_e32 v218, 64, v2
	v_xor_b32_e32 v219, 2, v216
	v_xor_b32_e32 v220, 4, v216
	v_xor_b32_e32 v221, 8, v216
	v_xor_b32_e32 v222, 32, v216
	v_mov_b32_e32 v223, 0xff800000
	s_branch .LBB0_1292

; #define GAS __attribute__((address_space(1)))
; __device__ __forceinline__ float bflo(unsigned w) { return __uint_as_float(w << 16); }
; __device__ __forceinline__ float bfhi(unsigned w) { return __uint_as_float(w & 0xffff0000u); }
; __device__ __forceinline__ float alibi_slope2(int g, int h) { return exp2f(-8.f * (float)(g * 16 + h + 1) / 48.f) * LOG2E; }
; __device__ __forceinline__ void attn_sample(Frame& F, int i_lo, int i_hi) {
;     ...
;         const int dsh = 2 * grp, W = 128 << dsh, dil = 1 << dsh;
;         const float* cache = F.in[3 + grp] + (size_t)b * W * 2048;
;         const float* newkv = F.out + (grp == 0 ? O_KV128S : grp == 1 ? O_KV512S : O_KV2048S) + (size_t)b * 8 * 2048;
;         const bf16* Qg = (const bf16*)(F.ws + WS_QKV + (size_t)grp * QKV_STRIDE);
;         bf16* Og = (bf16*)(F.ws + WS_OG + (size_t)grp * QKV_STRIDE);
;         const size_t row = (size_t)MP + b * 8 + s;
;         const int h = 2 * w + hh, co = h * 64 + 4 * dc;
;         const v2u qw = *(const GAS v2u*)(Qg + row * DM + co);
;         const f32x4 q = (f32x4){bflo(qw.x), bfhi(qw.x), bflo(qw.y), bfhi(qw.y)};
;         const float sl2 = alibi_slope2(grp, h) * (float)dil;
;         float mx = -INFINITY, lsum = 0.f; f32x4 o = (f32x4){0.f, 0.f, 0.f, 0.f};
;     ...
;         f32x4 ka[8], va[8], kb[8], vb[8];
;         SMP_LOAD(ka, va, 0);
; #pragma unroll 1
;         for (int j0 = 0; j0 < 128; j0 += 32) {
;             SMP_LOAD(kb, vb, j0 + 16);
.LBB0_1297:
	s_andn2_b64 vcc, exec, s[4:5]
	s_mov_b64 s[4:5], -1
	s_cbranch_vccnz .LBB0_1291
	s_waitcnt lgkmcnt(1)
	v_and_b32_e32 v8, 7, v4
	v_mul_hi_i32 v4, v3, s22
	s_waitcnt lgkmcnt(0)
	v_lshrrev_b32_e32 v5, 31, v4
	v_add_u32_e32 v4, v4, v5
	v_mul_lo_u32 v4, v4, 3
	v_sub_u32_e32 v168, v3, v4
	v_ashrrev_i32_e32 v169, 31, v168
	v_lshlrev_b64 v[4:5], 3, v[168:169]
	v_lshl_add_u64 v[4:5], s[88:89], 0, v[4:5]
	v_lshlrev_b32_e32 v224, 1, v168
	v_readfirstlane_b32 s0, v4
	v_readfirstlane_b32 s1, v5
	s_load_dwordx2 s[0:1], s[0:1], 0x18
	v_ashrrev_i32_e32 v3, 31, v2
	v_add_u32_e32 v4, 7, v224
	v_lshlrev_b64 v[4:5], v4, v[2:3]
	v_lshlrev_b64 v[4:5], 13, v[4:5]
	v_cmp_eq_u32_e32 vcc, 1, v168
	s_waitcnt lgkmcnt(0)
	v_lshl_add_u64 v[174:175], s[0:1], 0, v[4:5]
	v_lshlrev_b64 v[6:7], 16, v[2:3]
	v_cndmask_b32_e32 v4, v210, v211, vcc
	v_cmp_ne_u32_e32 vcc, 0, v168
	v_lshlrev_b32_e32 v2, 3, v2
	v_ashrrev_i32_e32 v3, 31, v2
	v_cndmask_b32_e32 v4, v212, v4, vcc
	v_lshlrev_b32_e32 v162, 2, v4
	v_or_b32_e32 v2, v2, v8
	v_lshl_add_u64 v[4:5], s[28:29], 0, v[162:163]
	v_mul_hi_i32 v173, v168, s23
	v_mul_lo_u32 v172, v168, s23
	v_lshl_add_u64 v[170:171], v[2:3], 0, s[14:15]
	v_lshl_add_u64 v[176:177], v[4:5], 0, v[6:7]
	v_lshl_add_u64 v[4:5], s[24:25], 0, v[172:173]
	v_lshlrev_b64 v[2:3], 7, v[170:171]
	v_lshlrev_b32_e64 v225, v224, s3
	v_lshl_add_u64 v[2:3], v[4:5], 0, v[2:3]
	v_or_b32_e32 v169, v225, v8
	v_readfirstlane_b32 s0, v2
	v_lshlrev_b32_e32 v2, v224, v195
	v_sub_u32_e32 v2, v169, v2
	v_readfirstlane_b32 s1, v3
	v_ashrrev_i32_e32 v3, 31, v2
	v_sub_u32_e32 v4, v2, v225
	v_cmp_lt_i32_e32 vcc, v2, v225
	v_lshlrev_b32_e32 v6, v224, v199
	v_sub_u32_e32 v6, v169, v6
	v_cndmask_b32_e32 v3, 0, v3, vcc
	v_cndmask_b32_e32 v2, v4, v2, vcc
	v_cndmask_b32_e32 v5, v177, v175, vcc
	v_cndmask_b32_e32 v4, v176, v174, vcc
	v_lshlrev_b64 v[2:3], 13, v[2:3]
	v_lshl_add_u64 v[2:3], v[4:5], 0, v[2:3]
	v_lshl_add_u64 v[2:3], v[2:3], 0, v[166:167]
	v_add_co_u32_e32 v4, vcc, s35, v2
	v_ashrrev_i32_e32 v7, 31, v6
	s_nop 0
	v_addc_co_u32_e32 v5, vcc, 0, v3, vcc
	v_sub_u32_e32 v8, v6, v225
	v_cmp_lt_i32_e32 vcc, v6, v225
	global_load_dwordx2 v[34:35], v254, s[0:1]
	global_load_dwordx4 v[94:97], v[2:3], off nt
	s_nop 0
	global_load_dwordx4 v[2:5], v[4:5], off nt
	v_cndmask_b32_e32 v7, 0, v7, vcc
	v_cndmask_b32_e32 v6, v8, v6, vcc
	v_cndmask_b32_e32 v9, v177, v175, vcc
	v_cndmask_b32_e32 v8, v176, v174, vcc
	v_lshlrev_b64 v[6:7], 13, v[6:7]
	v_lshl_add_u64 v[6:7], v[8:9], 0, v[6:7]
	v_lshl_add_u64 v[6:7], v[6:7], 0, v[166:167]
	v_add_co_u32_e32 v8, vcc, s35, v6
	v_mov_b32_e32 v232, 0
	s_nop 0
	v_addc_co_u32_e32 v9, vcc, 0, v7, vcc
	global_load_dwordx4 v[30:33], v[6:7], off nt
	global_load_dwordx4 v[66:69], v[8:9], off nt
	v_lshlrev_b32_e32 v6, v224, v201
	v_sub_u32_e32 v6, v169, v6
	v_ashrrev_i32_e32 v7, 31, v6
	v_sub_u32_e32 v8, v6, v225
	v_cmp_lt_i32_e32 vcc, v6, v225
	v_lshlrev_b64 v[178:179], 10, v[170:171]
	v_mov_b32_e32 v162, 0xff800000
	v_cndmask_b32_e32 v7, 0, v7, vcc
	v_cndmask_b32_e32 v6, v8, v6, vcc
	v_cndmask_b32_e32 v9, v177, v175, vcc
	v_cndmask_b32_e32 v8, v176, v174, vcc
	v_lshlrev_b64 v[6:7], 13, v[6:7]
	v_lshl_add_u64 v[6:7], v[8:9], 0, v[6:7]
	v_lshl_add_u64 v[6:7], v[6:7], 0, v[166:167]
	v_add_co_u32_e32 v8, vcc, s35, v6
	s_movk_i32 s4, 0xffe0
	s_nop 0
	v_addc_co_u32_e32 v9, vcc, 0, v7, vcc
	global_load_dwordx4 v[26:29], v[6:7], off nt
	global_load_dwordx4 v[70:73], v[8:9], off nt
	v_lshlrev_b32_e32 v6, v224, v204
	v_sub_u32_e32 v6, v169, v6
	v_ashrrev_i32_e32 v7, 31, v6
	v_sub_u32_e32 v8, v6, v225
	v_cmp_lt_i32_e32 vcc, v6, v225
	v_mov_b32_e32 v186, 0
	v_mov_b32_e32 v187, v232
	v_cndmask_b32_e32 v7, 0, v7, vcc
	v_cndmask_b32_e32 v6, v8, v6, vcc
	v_cndmask_b32_e32 v9, v177, v175, vcc
	v_cndmask_b32_e32 v8, v176, v174, vcc
	v_lshlrev_b64 v[6:7], 13, v[6:7]
	v_lshl_add_u64 v[6:7], v[8:9], 0, v[6:7]
	v_lshl_add_u64 v[6:7], v[6:7], 0, v[166:167]
	v_add_co_u32_e32 v8, vcc, s35, v6
	v_mov_b32_e32 v184, 0
	s_nop 0
	v_addc_co_u32_e32 v9, vcc, 0, v7, vcc
	global_load_dwordx4 v[22:25], v[6:7], off nt
	global_load_dwordx4 v[74:77], v[8:9], off nt
	v_lshlrev_b32_e32 v6, v224, v205
	v_sub_u32_e32 v6, v169, v6
	v_ashrrev_i32_e32 v7, 31, v6
	v_sub_u32_e32 v8, v6, v225
	v_cmp_lt_i32_e32 vcc, v6, v225
	v_mov_b32_e32 v185, v232
	s_waitcnt vmcnt(8)
; __device__ __forceinline__ float alibi_slope2(int g, int h) { return exp2f(-8.f * (float)(g * 16 + h + 1) / 48.f) * LOG2E; }
; __device__ __forceinline__ void attn_sample(Frame& F, int i_lo, int i_hi) {
;     ...
;         const float sl2 = alibi_slope2(grp, h) * (float)dil;
;         float mx = -INFINITY, lsum = 0.f; f32x4 o = (f32x4){0.f, 0.f, 0.f, 0.f};
	v_and_b32_e32 v180, 0xffff0000, v34
	v_cndmask_b32_e32 v7, 0, v7, vcc
	v_cndmask_b32_e32 v6, v8, v6, vcc
	v_cndmask_b32_e32 v9, v177, v175, vcc
	v_cndmask_b32_e32 v8, v176, v174, vcc
	v_lshlrev_b64 v[6:7], 13, v[6:7]
	v_lshl_add_u64 v[6:7], v[8:9], 0, v[6:7]
	v_lshl_add_u64 v[6:7], v[6:7], 0, v[166:167]
	v_add_co_u32_e32 v8, vcc, s35, v6
	v_lshlrev_b32_e32 v182, 16, v34
	s_nop 0
	v_addc_co_u32_e32 v9, vcc, 0, v7, vcc
	global_load_dwordx4 v[18:21], v[6:7], off nt
	global_load_dwordx4 v[78:81], v[8:9], off nt
	v_lshlrev_b32_e32 v6, v224, v206
	v_sub_u32_e32 v6, v169, v6
	v_ashrrev_i32_e32 v7, 31, v6
	v_sub_u32_e32 v8, v6, v225
	v_cmp_lt_i32_e32 vcc, v6, v225
	v_lshlrev_b32_e32 v181, 16, v35
	v_and_b32_e32 v183, 0xffff0000, v35
	v_cndmask_b32_e32 v7, 0, v7, vcc
	v_cndmask_b32_e32 v6, v8, v6, vcc
	v_cndmask_b32_e32 v9, v177, v175, vcc
	v_cndmask_b32_e32 v8, v176, v174, vcc
	v_lshlrev_b64 v[6:7], 13, v[6:7]
	v_lshl_add_u64 v[6:7], v[8:9], 0, v[6:7]
	v_lshl_add_u64 v[6:7], v[6:7], 0, v[166:167]
	v_add_co_u32_e32 v8, vcc, s35, v6
	s_waitcnt vmcnt(9)
	v_mov_b32_e32 v190, v95
	v_addc_co_u32_e32 v9, vcc, 0, v7, vcc
	global_load_dwordx4 v[14:17], v[6:7], off nt
	global_load_dwordx4 v[82:85], v[8:9], off nt
	v_lshlrev_b32_e32 v6, v224, v207
	v_sub_u32_e32 v6, v169, v6
	v_ashrrev_i32_e32 v7, 31, v6
	v_sub_u32_e32 v8, v6, v225
	v_cmp_lt_i32_e32 vcc, v6, v225
	v_mov_b32_e32 v191, v96
	v_mov_b32_e32 v95, v97
	v_cndmask_b32_e32 v7, 0, v7, vcc
	v_cndmask_b32_e32 v6, v8, v6, vcc
	v_cndmask_b32_e32 v9, v177, v175, vcc
	v_cndmask_b32_e32 v8, v176, v174, vcc
	v_lshlrev_b64 v[6:7], 13, v[6:7]
	v_lshl_add_u64 v[6:7], v[8:9], 0, v[6:7]
	v_lshl_add_u64 v[6:7], v[6:7], 0, v[166:167]
	v_add_co_u32_e32 v8, vcc, s35, v6
	s_waitcnt vmcnt(9)
	v_mov_b32_e32 v188, v31
	v_addc_co_u32_e32 v9, vcc, 0, v7, vcc
	global_load_dwordx4 v[10:13], v[6:7], off nt
	global_load_dwordx4 v[86:89], v[8:9], off nt
	v_lshlrev_b32_e32 v6, v224, v208
	v_sub_u32_e32 v6, v169, v6
	v_ashrrev_i32_e32 v7, 31, v6
	v_sub_u32_e32 v8, v6, v225
	v_cmp_lt_i32_e32 vcc, v6, v225
	v_mov_b32_e32 v189, v32
	v_mov_b32_e32 v31, v33
	v_cndmask_b32_e32 v7, 0, v7, vcc
	v_cndmask_b32_e32 v6, v8, v6, vcc
	v_cndmask_b32_e32 v9, v177, v175, vcc
	v_cndmask_b32_e32 v8, v176, v174, vcc
	v_lshlrev_b64 v[6:7], 13, v[6:7]
	v_lshl_add_u64 v[6:7], v[8:9], 0, v[6:7]
	v_lshl_add_u64 v[36:37], v[6:7], 0, v[166:167]
	global_load_dwordx4 v[6:9], v[36:37], off nt
	v_add_co_u32_e32 v36, vcc, s35, v36
	s_waitcnt vmcnt(10)
	v_mov_b32_e32 v32, v27
	v_addc_co_u32_e32 v37, vcc, 0, v37, vcc
	global_load_dwordx4 v[90:93], v[36:37], off nt
	v_lshl_add_u32 v36, v168, 4, v197
	v_cvt_f32_i32_e32 v36, v36
	v_lshlrev_b32_e64 v37, v224, 1
	v_mov_b32_e32 v33, v28
	v_mov_b32_e32 v27, v29
	v_mul_f32_e32 v36, 0xc1000000, v36
	v_div_scale_f32 v38, s[0:1], s33, s33, v36
	v_rcp_f32_e32 v39, v38
	s_waitcnt vmcnt(9)
	v_mov_b32_e32 v28, v23
	v_mov_b32_e32 v29, v24
	v_mov_b32_e32 v23, v25
	v_fma_f32 v34, -v38, v39, 1.0
	v_fmac_f32_e32 v39, v34, v39
	v_div_scale_f32 v34, vcc, v36, s33, v36
	v_mul_f32_e32 v35, v34, v39
	v_fma_f32 v40, -v38, v35, v34
	v_fmac_f32_e32 v35, v40, v39
	v_fma_f32 v34, -v38, v35, v34
	v_div_fmas_f32 v34, v34, v39, v35
	v_div_fixup_f32 v34, v34, s33, v36
	v_cmp_gt_f32_e32 vcc, s34, v34
	s_waitcnt vmcnt(7)
	v_mov_b32_e32 v24, v19
	v_mov_b32_e32 v25, v20
	v_cndmask_b32_e32 v35, 0, v214, vcc
	v_add_f32_e32 v34, v34, v35
	v_exp_f32_e32 v34, v34
	v_cvt_f32_u32_e32 v35, v37
	v_cndmask_b32_e32 v36, 0, v215, vcc
	v_cmp_lt_i32_e32 vcc, v217, v218
	v_ldexp_f32 v34, v34, v36
	v_mul_f32_e32 v34, 0x3fb8aa3b, v34
	v_mul_f32_e32 v227, v34, v35
	v_cndmask_b32_e32 v34, v216, v217, vcc
	v_cmp_lt_i32_e32 vcc, v219, v218
	v_lshlrev_b32_e32 v228, 2, v34
	v_mov_b32_e32 v19, v21
	v_cndmask_b32_e32 v34, v216, v219, vcc
	v_cmp_lt_i32_e32 vcc, v220, v218
	v_lshlrev_b32_e32 v229, 2, v34
	s_waitcnt vmcnt(5)
	v_mov_b32_e32 v20, v15
	v_cndmask_b32_e32 v34, v216, v220, vcc
	v_cmp_lt_i32_e32 vcc, v221, v218
	v_lshlrev_b32_e32 v230, 2, v34
	v_mov_b32_e32 v21, v16
	v_cndmask_b32_e32 v34, v216, v221, vcc
	v_cmp_lt_i32_e32 vcc, v222, v218
	v_lshlrev_b32_e32 v231, 2, v34
	v_mov_b32_e32 v15, v17
	v_cndmask_b32_e32 v34, v216, v222, vcc
	v_lshlrev_b32_e32 v226, 2, v34
	s_waitcnt vmcnt(3)
	v_mov_b32_e32 v16, v11
	v_mov_b32_e32 v17, v12
	v_mov_b32_e32 v11, v13
	s_waitcnt vmcnt(1)
	v_mov_b32_e32 v12, v7
	v_mov_b32_e32 v13, v8
	v_mov_b32_e32 v7, v9

; #define GAS __attribute__((address_space(1)))
; __device__ __forceinline__ float bflo(unsigned w) { return __uint_as_float(w << 16); }
; __device__ __forceinline__ float bfhi(unsigned w) { return __uint_as_float(w & 0xffff0000u); }
; __device__ __forceinline__ float alibi_slope2(int g, int h) { return exp2f(-8.f * (float)(g * 16 + h + 1) / 48.f) * LOG2E; }
; __device__ __forceinline__ void attn_sample(Frame& F, int i_lo, int i_hi) {
;     const int lane = F.lane, ksub = lane >> 5, hh = (lane >> 4) & 1, dc = lane & 15, w = F.wave;
;     float* LSE = WSP(float, WS_LSE);
;     for (int rnd = i_lo; rnd < i_hi; ++rnd) { const int it = F.bid + rnd * F.G;
;         int s, grp, b;
;         if (F.G == 256) {
;             const int x = F.bid & 7, q = F.bid >> 3, u = (x & 1) ? 64 + 8 * (x >> 1) + 4 * rnd + (q >> 3) : 16 * (x >> 1) + 4 * rnd + (q >> 3); s = q & 7; b = u / 3; grp = u % 3; }
;         else { if (it >= 768) break; s = it & 7; grp = (it >> 3) % 3; b = it / 24; }
;         const int dsh = 2 * grp, W = 128 << dsh, dil = 1 << dsh;
;         const float* cache = F.in[3 + grp] + (size_t)b * W * 2048;
;         const float* newkv = F.out + (grp == 0 ? O_KV128S : grp == 1 ? O_KV512S : O_KV2048S) + (size_t)b * 8 * 2048;
;         const bf16* Qg = (const bf16*)(F.ws + WS_QKV + (size_t)grp * QKV_STRIDE);
;         bf16* Og = (bf16*)(F.ws + WS_OG + (size_t)grp * QKV_STRIDE);
;         const size_t row = (size_t)MP + b * 8 + s;
;         const int h = 2 * w + hh, co = h * 64 + 4 * dc;
;         const v2u qw = *(const GAS v2u*)(Qg + row * DM + co);
;         const f32x4 q = (f32x4){bflo(qw.x), bfhi(qw.x), bflo(qw.y), bfhi(qw.y)};
;         const float sl2 = alibi_slope2(grp, h) * (float)dil;
;         float mx = -INFINITY, lsum = 0.f; f32x4 o = (f32x4){0.f, 0.f, 0.f, 0.f};
.LBB0_1366:
	v_add_u32_e32 v166, -2, v193
	s_bfe_u32 s0, s2, 0x20006
	s_waitcnt vmcnt(0)
	v_mul_lo_u32 v2, v166, s0
	v_add_u32_e32 v3, 1, v2
	v_and_b32_e32 v3, 0xff, v3
	s_movk_i32 s0, 0xab
	v_mul_lo_u32 v3, v3, s0
	v_bfe_u32 v167, v3, 9, 7
	v_cmp_gt_u32_e32 vcc, 2, v2
	s_mov_b32 s0, 2
	v_add_u32_e32 v195, 2, v167
	v_lshrrev_b32_e32 v161, 5, v160
	s_cbranch_vccnz .LBB0_1383
	v_readlane_b32 s1, v245, 8
	v_lshrrev_b32_e32 v2, 4, v160
	s_lshl_b32 s1, s1, 1
	v_and_or_b32 v4, v2, 1, s1
	v_lshlrev_b32_e32 v2, 2, v160
	v_and_b32_e32 v2, 60, v2
	v_mov_b32_e32 v3, 0
	v_and_b32_e32 v5, 47, v160
	v_lshl_or_b32 v2, v4, 6, v2
	v_add_u32_e32 v144, 1, v4
	v_cmp_eq_u32_e64 s[8:9], 0, v5
	v_lshlrev_b32_e32 v4, 2, v4
	v_mov_b32_e32 v5, v3
	v_lshl_add_u64 v[4:5], s[30:31], 0, v[4:5]
	s_mov_b64 s[4:5], 0x29300000
	v_lshl_add_u64 v[128:129], v[4:5], 0, s[4:5]
	s_lshl_b32 s5, s2, 2
	s_and_b32 s3, s2, 7
	s_and_b32 s5, s5, 24
	s_ashr_i32 s10, s2, 6
	s_add_i32 s5, s10, s5
	s_lshl_b32 s3, s3, 3
	s_lshr_b32 s1, s2, 3
	s_and_b32 s4, s2, 1
	s_add_i32 s5, s5, 64
	s_add_i32 s10, s3, s10
	s_add_u32 s3, s30, 0x23000000
	v_lshlrev_b64 v[130:131], 2, v[2:3]
	v_lshlrev_b32_e32 v154, 1, v2
	v_lshrrev_b32_e32 v255, 6, v2
	v_and_b32_e32 v254, 63, v2
	v_lshlrev_b32_e32 v254, 1, v254
	v_mul_u32_u24_e32 v255, 0x208000, v255
	v_add_u32_e32 v254, v255, v254
	v_mbcnt_lo_u32_b32 v2, -1, 0
	s_addc_u32 s33, s31, 0
	v_mbcnt_hi_u32_b32 v157, -1, v2
	v_or_b32_e32 v6, 0x80, v161
	s_cmp_eq_u32 s4, 0
	v_and_b32_e32 v2, 64, v157
	v_cmp_gt_u32_e64 s[6:7], 32, v160
	v_or_b32_e32 v145, 2, v161
	v_or_b32_e32 v146, 4, v161
	v_or_b32_e32 v147, 6, v161
	v_or_b32_e32 v148, 8, v161
	v_or_b32_e32 v149, 10, v161
	v_or_b32_e32 v150, 12, v161
	v_or_b32_e32 v151, 14, v161
	v_cvt_f32_ubyte0_e32 v152, v6
	v_max_u32_e32 v153, 3, v195
	s_cselect_b32 s34, s10, s5
	s_mov_b32 s35, 0x1a40000
	s_mov_b32 s45, 0x42400000
	s_mov_b32 s46, 0xc2fc0000
	s_movk_i32 s47, 0x1000
	s_movk_i32 s48, 0x81
	s_mov_b32 s49, 0xff800000
	s_movk_i32 s60, 0x7f
	s_movk_i32 s61, 0x7d
	s_movk_i32 s62, 0x7b
	s_movk_i32 s63, 0x79
	s_movk_i32 s64, 0x77
	s_movk_i32 s65, 0x75
	s_movk_i32 s66, 0x73
	v_mov_b32_e32 v155, 0x42800000
	v_not_b32_e32 v156, 63
	v_xor_b32_e32 v158, 1, v157
	v_add_u32_e32 v159, 64, v2
	v_xor_b32_e32 v162, 2, v157
	v_xor_b32_e32 v163, 4, v157
	v_xor_b32_e32 v164, 8, v157
	v_xor_b32_e32 v165, 32, v157
	v_mov_b32_e32 v168, 0xff800000
	s_branch .LBB0_1370

; #define GAS __attribute__((address_space(1)))
; __device__ __forceinline__ float bflo(unsigned w) { return __uint_as_float(w << 16); }
; __device__ __forceinline__ float bfhi(unsigned w) { return __uint_as_float(w & 0xffff0000u); }
; __device__ __forceinline__ float alibi_slope2(int g, int h) { return exp2f(-8.f * (float)(g * 16 + h + 1) / 48.f) * LOG2E; }
; __device__ __forceinline__ void attn_sample(Frame& F, int i_lo, int i_hi) {
;     ...
;         const int dsh = 2 * grp, W = 128 << dsh, dil = 1 << dsh;
;         const float* cache = F.in[3 + grp] + (size_t)b * W * 2048;
;         const float* newkv = F.out + (grp == 0 ? O_KV128S : grp == 1 ? O_KV512S : O_KV2048S) + (size_t)b * 8 * 2048;
;         const bf16* Qg = (const bf16*)(F.ws + WS_QKV + (size_t)grp * QKV_STRIDE);
;         bf16* Og = (bf16*)(F.ws + WS_OG + (size_t)grp * QKV_STRIDE);
;         const size_t row = (size_t)MP + b * 8 + s;
;         const int h = 2 * w + hh, co = h * 64 + 4 * dc;
;         const v2u qw = *(const GAS v2u*)(Qg + row * DM + co);
;         const f32x4 q = (f32x4){bflo(qw.x), bfhi(qw.x), bflo(qw.y), bfhi(qw.y)};
;         const float sl2 = alibi_slope2(grp, h) * (float)dil;
;         float mx = -INFINITY, lsum = 0.f; f32x4 o = (f32x4){0.f, 0.f, 0.f, 0.f};
;     ...
;         f32x4 ka[8], va[8], kb[8], vb[8];
;         SMP_LOAD(ka, va, 0);
; #pragma unroll 1
;         for (int j0 = 0; j0 < 128; j0 += 32) {
;             SMP_LOAD(kb, vb, j0 + 16);
.LBB0_1377:
	s_mul_hi_i32 s10, s5, 0x55555556
	s_lshr_b32 s12, s10, 31
	s_add_i32 s10, s10, s12
	s_mul_i32 s10, s10, 3
	s_sub_i32 s54, s5, s10
	s_lshl_b32 s68, s54, 1
	s_ashr_i32 s55, s54, 31
	s_and_b32 s11, s14, 7
	s_lshl_b32 s69, 0x80, s68
	s_lshl_b32 s10, 1, s68
	s_lshl_b64 s[12:13], s[54:55], 3
	s_add_u32 s12, s88, s12
	s_addc_u32 s13, s89, s13
	s_load_dwordx2 s[12:13], s[12:13], 0x18
	s_ashr_i32 s5, s4, 31
	s_add_i32 s14, s68, 7
	s_lshl_b64 s[14:15], s[4:5], s14
	s_lshl_b64 s[14:15], s[14:15], 13
	s_waitcnt lgkmcnt(0)
	s_add_u32 s70, s12, s14
	s_addc_u32 s71, s13, s15
	s_cmp_eq_u32 s54, 1
	s_cselect_b32 s12, s35, 0x2ac0000
	s_cmp_lg_u32 s54, 0
	s_cselect_b32 s12, s12, 0x15c0000
	s_lshl_b32 s12, s12, 2
	s_add_u32 s14, s28, s12
	s_addc_u32 s15, s29, 0
	s_lshl_b64 s[12:13], s[4:5], 16
	s_add_u32 s5, s14, s12
	s_addc_u32 s72, s15, s13
	s_mul_i32 s67, s54, 0x2100000
	s_mul_hi_i32 s55, s54, 0x2100000
	s_add_u32 s14, s24, s67
	s_addc_u32 s15, s25, s55
	s_lshl_b32 s4, s4, 3
	s_ashr_i32 s12, s4, 31
	s_or_b32 s4, s4, s11
	s_add_u32 s56, s4, 0x4000
	s_addc_u32 s57, s12, 0
	s_lshl_b64 s[58:59], s[56:57], 10
	s_lshl_b64 s[12:13], s[56:57], 7
	s_add_u32 s12, s14, s12
	s_addc_u32 s13, s15, s13
	s_or_b32 s4, s69, s11
	v_lshlrev_b32_e32 v2, s68, v161
	v_sub_u32_e32 v2, s4, v2
	v_ashrrev_i32_e32 v3, 31, v2
	v_subrev_u32_e32 v4, s69, v2
	v_cmp_gt_i32_e32 vcc, s69, v2
	v_mov_b32_e32 v32, s72
	v_mov_b32_e32 v33, s71
	v_cndmask_b32_e32 v3, 0, v3, vcc
	v_cndmask_b32_e32 v2, v4, v2, vcc
	v_mov_b32_e32 v58, s5
	v_mov_b32_e32 v59, s70
	v_cndmask_b32_e32 v5, v32, v33, vcc
	v_cndmask_b32_e32 v4, v58, v59, vcc
	v_lshlrev_b64 v[2:3], 13, v[2:3]
	v_lshl_add_u64 v[2:3], v[4:5], 0, v[2:3]
	v_lshl_add_u64 v[2:3], v[2:3], 0, v[130:131]
	v_add_co_u32_e32 v4, vcc, s47, v2
	v_lshlrev_b32_e32 v6, s68, v145
	s_nop 0
	v_addc_co_u32_e32 v5, vcc, 0, v3, vcc
	v_sub_u32_e32 v6, s4, v6
	v_ashrrev_i32_e32 v7, 31, v6
	v_subrev_u32_e32 v8, s69, v6
	v_cmp_gt_i32_e32 vcc, s69, v6
	v_lshlrev_b32_e32 v10, s68, v146
	v_sub_u32_e32 v10, s4, v10
	v_cndmask_b32_e32 v7, 0, v7, vcc
	v_cndmask_b32_e32 v6, v8, v6, vcc
	v_cndmask_b32_e32 v9, v32, v33, vcc
	v_cndmask_b32_e32 v8, v58, v59, vcc
	v_lshlrev_b64 v[6:7], 13, v[6:7]
	v_lshl_add_u64 v[6:7], v[8:9], 0, v[6:7]
	v_lshl_add_u64 v[6:7], v[6:7], 0, v[130:131]
	v_add_co_u32_e32 v8, vcc, s47, v6
	v_ashrrev_i32_e32 v11, 31, v10
	s_nop 0
	v_addc_co_u32_e32 v9, vcc, 0, v7, vcc
	v_subrev_u32_e32 v12, s69, v10
	v_cmp_gt_i32_e32 vcc, s69, v10
	v_lshlrev_b32_e32 v14, s68, v147
	v_sub_u32_e32 v14, s4, v14
	v_cndmask_b32_e32 v11, 0, v11, vcc
	v_cndmask_b32_e32 v10, v12, v10, vcc
	v_cndmask_b32_e32 v13, v32, v33, vcc
	v_cndmask_b32_e32 v12, v58, v59, vcc
	v_lshlrev_b64 v[10:11], 13, v[10:11]
	v_lshl_add_u64 v[10:11], v[12:13], 0, v[10:11]
	v_lshl_add_u64 v[10:11], v[10:11], 0, v[130:131]
	v_add_co_u32_e32 v12, vcc, s47, v10
	v_ashrrev_i32_e32 v15, 31, v14
	s_nop 0
	v_addc_co_u32_e32 v13, vcc, 0, v11, vcc
	v_subrev_u32_e32 v16, s69, v14
	v_cmp_gt_i32_e32 vcc, s69, v14
	v_lshlrev_b32_e32 v18, s68, v148
	v_sub_u32_e32 v18, s4, v18
	v_cndmask_b32_e32 v15, 0, v15, vcc
	v_cndmask_b32_e32 v14, v16, v14, vcc
	v_cndmask_b32_e32 v17, v32, v33, vcc
	v_cndmask_b32_e32 v16, v58, v59, vcc
	v_lshlrev_b64 v[14:15], 13, v[14:15]
	v_lshl_add_u64 v[14:15], v[16:17], 0, v[14:15]
	v_lshl_add_u64 v[14:15], v[14:15], 0, v[130:131]
	v_add_co_u32_e32 v16, vcc, s47, v14
	v_ashrrev_i32_e32 v19, 31, v18
	s_nop 0
	v_addc_co_u32_e32 v17, vcc, 0, v15, vcc
	v_subrev_u32_e32 v20, s69, v18
	v_cmp_gt_i32_e32 vcc, s69, v18
	global_load_dwordx2 v[66:67], v254, s[12:13]
	v_lshlrev_b32_e32 v22, s68, v149
	v_cndmask_b32_e32 v19, 0, v19, vcc
	v_cndmask_b32_e32 v18, v20, v18, vcc
	v_cndmask_b32_e32 v21, v32, v33, vcc
	v_cndmask_b32_e32 v20, v58, v59, vcc
	v_lshlrev_b64 v[18:19], 13, v[18:19]
	v_lshl_add_u64 v[18:19], v[20:21], 0, v[18:19]
	v_lshl_add_u64 v[18:19], v[18:19], 0, v[130:131]
	v_add_co_u32_e32 v20, vcc, s47, v18
	v_sub_u32_e32 v22, s4, v22
	s_nop 0
	v_addc_co_u32_e32 v21, vcc, 0, v19, vcc
	v_ashrrev_i32_e32 v23, 31, v22
	v_subrev_u32_e32 v24, s69, v22
	v_cmp_gt_i32_e32 vcc, s69, v22
	v_lshlrev_b32_e32 v26, s68, v150
	v_sub_u32_e32 v26, s4, v26
	v_cndmask_b32_e32 v23, 0, v23, vcc
	v_cndmask_b32_e32 v22, v24, v22, vcc
	v_cndmask_b32_e32 v25, v32, v33, vcc
	v_cndmask_b32_e32 v24, v58, v59, vcc
	v_lshlrev_b64 v[22:23], 13, v[22:23]
	v_lshl_add_u64 v[22:23], v[24:25], 0, v[22:23]
	v_lshl_add_u64 v[22:23], v[22:23], 0, v[130:131]
	v_add_co_u32_e32 v24, vcc, s47, v22
	v_ashrrev_i32_e32 v27, 31, v26
	s_nop 0
	v_addc_co_u32_e32 v25, vcc, 0, v23, vcc
	v_subrev_u32_e32 v28, s69, v26
	v_cmp_gt_i32_e32 vcc, s69, v26
	v_lshlrev_b32_e32 v30, s68, v151
	v_sub_u32_e32 v30, s4, v30
	v_cndmask_b32_e32 v27, 0, v27, vcc
	v_cndmask_b32_e32 v26, v28, v26, vcc
	v_cndmask_b32_e32 v29, v32, v33, vcc
	v_cndmask_b32_e32 v28, v58, v59, vcc
	v_lshlrev_b64 v[26:27], 13, v[26:27]
	v_lshl_add_u64 v[26:27], v[28:29], 0, v[26:27]
	v_lshl_add_u64 v[26:27], v[26:27], 0, v[130:131]
	v_add_co_u32_e32 v28, vcc, s47, v26
	v_ashrrev_i32_e32 v31, 31, v30
	s_nop 0
	v_addc_co_u32_e32 v29, vcc, 0, v27, vcc
	v_subrev_u32_e32 v60, s69, v30
	v_cmp_gt_i32_e32 vcc, s69, v30
	global_load_dwordx4 v[62:65], v[2:3], off nt
	s_nop 0
	global_load_dwordx4 v[2:5], v[4:5], off nt
	v_cndmask_b32_e32 v31, 0, v31, vcc
	v_cndmask_b32_e32 v30, v60, v30, vcc
	v_cndmask_b32_e32 v33, v32, v33, vcc
	v_cndmask_b32_e32 v32, v58, v59, vcc
	v_lshlrev_b64 v[30:31], 13, v[30:31]
	v_lshl_add_u64 v[30:31], v[32:33], 0, v[30:31]
	v_lshl_add_u64 v[30:31], v[30:31], 0, v[130:131]
	global_load_dwordx4 v[42:45], v[6:7], off nt
	s_nop 0
	global_load_dwordx4 v[6:9], v[8:9], off nt
	s_nop 0
	global_load_dwordx4 v[34:37], v[10:11], off nt
	s_nop 0
	global_load_dwordx4 v[10:13], v[12:13], off nt
	s_nop 0
	global_load_dwordx4 v[38:41], v[14:15], off nt
	s_nop 0
	global_load_dwordx4 v[14:17], v[16:17], off nt
	s_nop 0
	global_load_dwordx4 v[46:49], v[18:19], off nt
	s_nop 0
	global_load_dwordx4 v[18:21], v[20:21], off nt
	s_nop 0
	global_load_dwordx4 v[50:53], v[22:23], off nt
	s_nop 0
	global_load_dwordx4 v[22:25], v[24:25], off nt
	s_nop 0
	global_load_dwordx4 v[54:57], v[26:27], off nt
	s_nop 0
	global_load_dwordx4 v[26:29], v[28:29], off nt
	v_lshl_add_u32 v68, s54, 4, v144
	global_load_dwordx4 v[58:61], v[30:31], off nt
	v_add_co_u32_e32 v30, vcc, s47, v30
	v_cvt_f32_i32_e32 v68, v68
	s_nop 0
	v_addc_co_u32_e32 v31, vcc, 0, v31, vcc
	global_load_dwordx4 v[30:33], v[30:31], off nt
	v_mul_f32_e32 v68, 0xc1000000, v68
	v_div_scale_f32 v69, s[12:13], s45, s45, v68
	v_rcp_f32_e32 v70, v69
	v_mov_b32_e32 v175, 0
	v_mov_b32_e32 v176, 0xff800000
	s_movk_i32 s73, 0xffe0
	v_mov_b32_e32 v138, 0
	v_mov_b32_e32 v139, v175
	s_waitcnt vmcnt(16)
; __device__ __forceinline__ float alibi_slope2(int g, int h) { return exp2f(-8.f * (float)(g * 16 + h + 1) / 48.f) * LOG2E; }
; __device__ __forceinline__ void attn_sample(Frame& F, int i_lo, int i_hi) {
;     ...
;         const float sl2 = alibi_slope2(grp, h) * (float)dil;
;         float mx = -INFINITY, lsum = 0.f; f32x4 o = (f32x4){0.f, 0.f, 0.f, 0.f};
	v_and_b32_e32 v132, 0xffff0000, v66
	v_lshlrev_b32_e32 v134, 16, v66
	v_fma_f32 v66, -v69, v70, 1.0
	v_fmac_f32_e32 v70, v66, v70
	v_div_scale_f32 v66, vcc, v68, s45, v68
	v_lshlrev_b32_e32 v133, 16, v67
	v_and_b32_e32 v135, 0xffff0000, v67
	v_mul_f32_e32 v67, v66, v70
	v_fma_f32 v71, -v69, v67, v66
	v_fmac_f32_e32 v67, v71, v70
	v_fma_f32 v66, -v69, v67, v66
	v_div_fmas_f32 v66, v66, v70, v67
	v_div_fixup_f32 v66, v66, s45, v68
	v_cmp_gt_f32_e32 vcc, s46, v66
	v_mov_b32_e32 v136, 0
	v_mov_b32_e32 v137, v175
	v_cndmask_b32_e32 v67, 0, v155, vcc
	v_add_f32_e32 v66, v66, v67
	v_exp_f32_e32 v66, v66
	v_cvt_f32_u32_e32 v67, s10
	v_cndmask_b32_e32 v68, 0, v156, vcc
	v_cmp_lt_i32_e32 vcc, v158, v159
	v_ldexp_f32 v66, v66, v68
	v_mul_f32_e32 v66, 0x3fb8aa3b, v66
	v_mul_f32_e32 v170, v66, v67
	v_cndmask_b32_e32 v66, v157, v158, vcc
	v_cmp_lt_i32_e32 vcc, v162, v159
	v_lshlrev_b32_e32 v171, 2, v66
	s_waitcnt vmcnt(15)
	v_mov_b32_e32 v140, v63
	v_cndmask_b32_e32 v66, v157, v162, vcc
	v_cmp_lt_i32_e32 vcc, v163, v159
	v_lshlrev_b32_e32 v172, 2, v66
	v_mov_b32_e32 v141, v64
	v_cndmask_b32_e32 v66, v157, v163, vcc
	v_cmp_lt_i32_e32 vcc, v164, v159
	v_lshlrev_b32_e32 v173, 2, v66
	v_mov_b32_e32 v63, v65
	v_cndmask_b32_e32 v66, v157, v164, vcc
	v_cmp_lt_i32_e32 vcc, v165, v159
	v_lshlrev_b32_e32 v174, 2, v66
	s_waitcnt vmcnt(13)
	v_mov_b32_e32 v142, v43
	v_cndmask_b32_e32 v66, v157, v165, vcc
	v_lshlrev_b32_e32 v169, 2, v66
	v_mov_b32_e32 v143, v44
	v_mov_b32_e32 v43, v45
	s_waitcnt vmcnt(11)
	v_mov_b32_e32 v44, v35
	v_mov_b32_e32 v45, v36
	v_mov_b32_e32 v35, v37
	s_waitcnt vmcnt(9)
	v_mov_b32_e32 v36, v39
	v_mov_b32_e32 v37, v40
	v_mov_b32_e32 v39, v41
	s_waitcnt vmcnt(7)
	v_mov_b32_e32 v40, v47
	v_mov_b32_e32 v41, v48
	v_mov_b32_e32 v47, v49
	s_waitcnt vmcnt(5)
	v_mov_b32_e32 v48, v51
	v_mov_b32_e32 v49, v52
	v_mov_b32_e32 v51, v53
	s_waitcnt vmcnt(3)
	v_mov_b32_e32 v52, v55
	v_mov_b32_e32 v53, v56
	v_mov_b32_e32 v55, v57
	s_waitcnt vmcnt(1)
	v_mov_b32_e32 v56, v59
	v_mov_b32_e32 v57, v60
	v_mov_b32_e32 v59, v61

; __device__ __forceinline__ void st_bf8(bf16* p, const f32x4 a, const f32x4 b) { *(GAS v4u*)p = (v4u){pk2(a.x, a.y), pk2(a.z, a.w), pk2(b.x, b.y), pk2(b.z, b.w)}; }
; __device__ __forceinline__ float sq4(const f32x4 a) { return (a.x * a.x + a.y * a.y) + (a.z * a.z + a.w * a.w); }
; __device__ __forceinline__ void nt_store4(float* p, f32x4 v) { __builtin_nontemporal_store(v, (f32x4*)p); }
;     template <int NR> __device__ __forceinline__ void rows(const int (&rowb)[NR], int fr, const float (&rstd)[NR], const f32x4 (&a)[NR][2][2], int pn, int wc, int fq) const {
;     ...
;         bf16* dbase = (bf16*)(qkv_base + (size_t)(which * 3 + g) * QKV_STRIDE) + h * 64 + 8 * fq;
;         float* kvp = out + (g == 0 ? O_KV128P : g == 1 ? O_KV512P : O_KV2048P) + (size_t)(which - 1) * 1024 + h * 64 + 8 * fq;
;         float* kvs = out + (g == 0 ? O_KV128S : g == 1 ? O_KV512S : O_KV2048S) + (size_t)(which - 1) * 1024 + h * 64 + 8 * fq;
; #pragma unroll
;         for (int i = 0; i < NR; ++i) {
;             const float rr = rstd[i];
;             f32x4 v[2][2] = {{a[i][0][0] * rr, a[i][0][1] * rr}, {a[i][1][0] * rr, a[i][1][1] * rr}};
;             if (which < 2) {
;                 float ss = sq4(v[0][0]) + sq4(v[0][1]) + sq4(v[1][0]) + sq4(v[1][1]);
;                 ss += __shfl_xor(ss, 16); ss += __shfl_xor(ss, 32);
;                 float sc = rsqrtf(ss * (1.f / 64.f) + EPS); if (which == 0) sc *= QSCALE;
; #pragma unroll
;                 for (int bj = 0; bj < 2; ++bj)
; #pragma unroll
;                     for (int n = 0; n < 2; ++n) v[bj][n] = v[bj][n] * wv[bj][n] * sc;
;             }
;             const int rw = rowb[i] + fr; int arow = rw, b, t = 0; const bool prompt = rw < MP;
;             if (prompt) { b = rw >> 12; t = rw & 4095; arow = (b << 12) + ((t & ((1 << dsh) - 1)) << (12 - dsh)) + (t >> dsh); } else { b = (rw - MP) >> 3; }
;             bf16* dst = dbase + (size_t)arow * DM;
;             st_bf8(dst, v[0][0], v[0][1]); st_bf8(dst + 32, v[1][0], v[1][1]);
;             if (which >= 1) {
;                 float* o = nullptr;
;                 if (prompt) { if (t >= SEQ - W) o = kvp + (size_t)(b * W + (t - (SEQ - W))) * 2048; }
;                 else o = kvs + (size_t)(rw - MP) * 2048;
;                 if (o) { nt_store4(o, v[0][0]); nt_store4(o + 4, v[0][1]); nt_store4(o + 32, v[1][0]); nt_store4(o + 36, v[1][1]); }
.LBB0_1436:
	s_lshl_b32 s36, s14, 8
	s_add_i32 s67, s36, s90
	v_or_b32_e32 v176, s67, v174
	v_cmp_lt_i32_e32 vcc, s76, v176
	s_and_saveexec_b64 s[0:1], vcc
	s_xor_b64 s[4:5], exec, s[0:1]
	v_add_u32_e32 v152, 0xffffc000, v176
	v_lshrrev_b32_e32 v162, 3, v152
	s_or_saveexec_b64 s[4:5], s[4:5]
	s_ashr_i32 s0, s12, 2
	s_mul_hi_i32 s1, s0, 0x55555556
	s_lshr_b32 s13, s1, 31
	s_add_i32 s1, s1, s13
	s_mul_i32 s1, s1, 3
	s_sub_i32 s13, s0, s1
	s_lshl_b32 s0, s13, 1
	s_sub_i32 s1, 12, s0
	v_mov_b32_e32 v177, 0
	v_mov_b32_e32 v164, v176
	s_xor_b64 exec, exec, s[4:5]
	v_and_b32_e32 v177, 0xfcf, v176
	v_lshlrev_b32_e32 v152, s1, v176
	v_mov_b32_e32 v153, s67
	s_ashr_i32 s14, s67, 12
	v_bfi_b32 v152, s77, v152, v153
	v_lshrrev_b32_e32 v153, s0, v177
	v_add_u32_e32 v164, v152, v153
	v_mov_b32_e32 v162, s14
	s_or_b64 exec, exec, s[4:5]
	s_mul_hi_i32 s4, s12, 0x2aaaaaab
	s_lshr_b32 s5, s4, 31
	s_ashr_i32 s4, s4, 1
	s_add_i32 s4, s4, s5
	s_lshl_b32 s5, s12, 2
	s_and_b32 s5, s5, 12
	s_or_b32 s14, s5, s89
	s_mul_i32 s5, s4, 3
	s_add_i32 s5, s5, s13
	s_mul_hi_i32 s15, s5, 0x2100000
	s_mul_i32 s37, s5, 0x2100000
	s_ashr_i32 s5, s4, 31
	s_lshl_b64 s[4:5], s[4:5], 12
	s_add_u32 s69, s4, 0xfffff000
	s_addc_u32 s96, s5, -1
	s_cmp_eq_u32 s13, 1
	s_mov_b32 s4, 0x1640000
	s_cselect_b32 s97, s4, 0x1ac0000
	s_mov_b32 s4, 0x1a40000
	s_cselect_b32 s38, s4, 0x2ac0000
	s_add_u32 s4, s24, s37
	s_addc_u32 s5, s25, s15
	s_mul_i32 s15, s14, 0x208000
	s_add_u32 s4, s4, s15
	s_addc_u32 s5, s5, 0
	s_cmp_eq_u32 s13, 0
	v_lshlrev_b32_e32 v148, 1, v148
	v_lshl_add_u64 v[156:157], s[4:5], 0, v[148:149]
	s_cselect_b32 s4, 0x14c0000, s97
	s_cselect_b32 s13, 0x15c0000, s38
	s_lshl_b32 s4, s4, 2
	s_add_u32 s4, s28, s4
	s_addc_u32 s5, s29, 0
	s_add_u32 s4, s4, s69
	s_addc_u32 s5, s5, s96
	s_lshl_b32 s14, s14, 8
	s_add_u32 s4, s4, s14
	s_addc_u32 s5, s5, 0
	v_mov_b32_e32 v159, v149
	v_lshl_add_u64 v[152:153], s[4:5], 0, v[158:159]
	s_lshl_b32 s4, s13, 2
	s_add_u32 s4, s28, s4
	s_addc_u32 s5, s29, 0
	s_add_u32 s4, s4, s69
	s_addc_u32 s5, s5, s96
	s_add_u32 s4, s4, s14
	s_addc_u32 s5, s5, 0
	s_lshl_b32 s96, 0xffffff80, s0
	v_ashrrev_i32_e32 v165, 31, v164
	s_cmp_gt_i32 s12, 11
	v_lshlrev_b64 v[164:165], 7, v[164:165]
	v_lshl_add_u64 v[154:155], s[4:5], 0, v[158:159]
	s_cselect_b64 s[4:5], -1, 0
	s_add_i32 s69, s96, 0x1000
	s_add_i32 s97, s0, 7
	v_lshl_add_u64 v[164:165], v[156:157], 0, v[164:165]
	v_cvt_pk_bf16_f32 v178, v142, v143
	v_cvt_pk_bf16_f32 v179, v144, v145
	v_cvt_pk_bf16_f32 v180, v138, v139
	v_cvt_pk_bf16_f32 v181, v140, v141
	s_cmp_lt_i32 s12, 12
	global_store_dwordx4 v[164:165], v[178:181], off
	s_nop 1
	v_cvt_pk_bf16_f32 v178, v134, v135
	v_cvt_pk_bf16_f32 v179, v136, v137
	v_cvt_pk_bf16_f32 v180, v130, v131
	v_cvt_pk_bf16_f32 v181, v132, v133
	global_store_dwordx4 v[164:165], v[178:181], off offset:64
	s_cbranch_scc1 .LBB0_1446
	s_and_saveexec_b64 s[12:13], vcc
	s_xor_b64 s[12:13], exec, s[12:13]
	s_cbranch_execnz .LBB0_1535
	s_andn2_saveexec_b64 s[12:13], s[12:13]
	s_cbranch_execnz .LBB0_1536

; __device__ __forceinline__ void st_bf8(bf16* p, const f32x4 a, const f32x4 b) { *(GAS v4u*)p = (v4u){pk2(a.x, a.y), pk2(a.z, a.w), pk2(b.x, b.y), pk2(b.z, b.w)}; }
; __device__ __forceinline__ float sq4(const f32x4 a) { return (a.x * a.x + a.y * a.y) + (a.z * a.z + a.w * a.w); }
; __device__ __forceinline__ void nt_store4(float* p, f32x4 v) { __builtin_nontemporal_store(v, (f32x4*)p); }
;     template <int NR> __device__ __forceinline__ void rows(const int (&rowb)[NR], int fr, const float (&rstd)[NR], const f32x4 (&a)[NR][2][2], int pn, int wc, int fq) const {
;     ...
;         bf16* dbase = (bf16*)(qkv_base + (size_t)(which * 3 + g) * QKV_STRIDE) + h * 64 + 8 * fq;
;         float* kvp = out + (g == 0 ? O_KV128P : g == 1 ? O_KV512P : O_KV2048P) + (size_t)(which - 1) * 1024 + h * 64 + 8 * fq;
;         float* kvs = out + (g == 0 ? O_KV128S : g == 1 ? O_KV512S : O_KV2048S) + (size_t)(which - 1) * 1024 + h * 64 + 8 * fq;
; #pragma unroll
;         for (int i = 0; i < NR; ++i) {
;             const float rr = rstd[i];
;             f32x4 v[2][2] = {{a[i][0][0] * rr, a[i][0][1] * rr}, {a[i][1][0] * rr, a[i][1][1] * rr}};
;             if (which < 2) {
;                 float ss = sq4(v[0][0]) + sq4(v[0][1]) + sq4(v[1][0]) + sq4(v[1][1]);
;                 ss += __shfl_xor(ss, 16); ss += __shfl_xor(ss, 32);
;                 float sc = rsqrtf(ss * (1.f / 64.f) + EPS); if (which == 0) sc *= QSCALE;
; #pragma unroll
;                 for (int bj = 0; bj < 2; ++bj)
; #pragma unroll
;                     for (int n = 0; n < 2; ++n) v[bj][n] = v[bj][n] * wv[bj][n] * sc;
;             }
;             const int rw = rowb[i] + fr; int arow = rw, b, t = 0; const bool prompt = rw < MP;
;             if (prompt) { b = rw >> 12; t = rw & 4095; arow = (b << 12) + ((t & ((1 << dsh) - 1)) << (12 - dsh)) + (t >> dsh); } else { b = (rw - MP) >> 3; }
;             bf16* dst = dbase + (size_t)arow * DM;
;             st_bf8(dst, v[0][0], v[0][1]); st_bf8(dst + 32, v[1][0], v[1][1]);
;             if (which >= 1) {
;                 float* o = nullptr;
;                 if (prompt) { if (t >= SEQ - W) o = kvp + (size_t)(b * W + (t - (SEQ - W))) * 2048; }
;                 else o = kvs + (size_t)(rw - MP) * 2048;
;                 if (o) { nt_store4(o, v[0][0]); nt_store4(o + 4, v[0][1]); nt_store4(o + 32, v[1][0]); nt_store4(o + 36, v[1][1]); }
.LBB0_1448:
	s_add_i32 s37, s36, s91
	v_or_b32_e32 v133, s37, v174
	v_cmp_lt_i32_e64 s[14:15], s76, v133
	s_and_saveexec_b64 s[12:13], s[14:15]
	s_xor_b64 s[12:13], exec, s[12:13]
	v_add_u32_e32 v130, 0xffffc000, v133
	v_lshrrev_b32_e32 v134, 3, v130
	s_or_saveexec_b64 s[12:13], s[12:13]
	v_mov_b32_e32 v132, 0
	v_mov_b32_e32 v130, v133
	s_xor_b64 exec, exec, s[12:13]
	v_and_b32_e32 v132, 0xfdf, v133
	v_lshlrev_b32_e32 v130, s1, v133
	v_mov_b32_e32 v131, s37
	s_ashr_i32 s38, s37, 12
	v_bfi_b32 v130, s77, v130, v131
	v_lshrrev_b32_e32 v131, s0, v132
	v_add_u32_e32 v130, v130, v131
	v_mov_b32_e32 v134, s38
	s_or_b64 exec, exec, s[12:13]
	v_ashrrev_i32_e32 v131, 31, v130
	v_lshlrev_b64 v[130:131], 7, v[130:131]
	v_lshl_add_u64 v[130:131], v[156:157], 0, v[130:131]
	v_cvt_pk_bf16_f32 v136, v110, v111
	v_cvt_pk_bf16_f32 v137, v112, v113
	v_cvt_pk_bf16_f32 v138, v106, v107
	v_cvt_pk_bf16_f32 v139, v108, v109
	global_store_dwordx4 v[130:131], v[136:139], off
	s_andn2_b64 vcc, exec, s[4:5]
	s_nop 0
	v_cvt_pk_bf16_f32 v136, v102, v103
	v_cvt_pk_bf16_f32 v137, v104, v105
	v_cvt_pk_bf16_f32 v138, v98, v99
	v_cvt_pk_bf16_f32 v139, v100, v101
	global_store_dwordx4 v[130:131], v[136:139], off offset:64
	v_cndmask_b32_e64 v130, 0, 1, s[4:5]
	v_cmp_ne_u32_e64 s[12:13], 1, v130
	s_cbranch_vccnz .LBB0_1458
	s_and_saveexec_b64 s[4:5], s[14:15]
	s_xor_b64 s[4:5], exec, s[4:5]
	s_cbranch_execnz .LBB0_1537
	s_andn2_saveexec_b64 s[4:5], s[4:5]
	s_cbranch_execnz .LBB0_1538

; __device__ __forceinline__ void st_bf8(bf16* p, const f32x4 a, const f32x4 b) { *(GAS v4u*)p = (v4u){pk2(a.x, a.y), pk2(a.z, a.w), pk2(b.x, b.y), pk2(b.z, b.w)}; }
; __device__ __forceinline__ float sq4(const f32x4 a) { return (a.x * a.x + a.y * a.y) + (a.z * a.z + a.w * a.w); }
; __device__ __forceinline__ void nt_store4(float* p, f32x4 v) { __builtin_nontemporal_store(v, (f32x4*)p); }
;     template <int NR> __device__ __forceinline__ void rows(const int (&rowb)[NR], int fr, const float (&rstd)[NR], const f32x4 (&a)[NR][2][2], int pn, int wc, int fq) const {
;     ...
;         bf16* dbase = (bf16*)(qkv_base + (size_t)(which * 3 + g) * QKV_STRIDE) + h * 64 + 8 * fq;
;         float* kvp = out + (g == 0 ? O_KV128P : g == 1 ? O_KV512P : O_KV2048P) + (size_t)(which - 1) * 1024 + h * 64 + 8 * fq;
;         float* kvs = out + (g == 0 ? O_KV128S : g == 1 ? O_KV512S : O_KV2048S) + (size_t)(which - 1) * 1024 + h * 64 + 8 * fq;
; #pragma unroll
;         for (int i = 0; i < NR; ++i) {
;             const float rr = rstd[i];
;             f32x4 v[2][2] = {{a[i][0][0] * rr, a[i][0][1] * rr}, {a[i][1][0] * rr, a[i][1][1] * rr}};
;             if (which < 2) {
;                 float ss = sq4(v[0][0]) + sq4(v[0][1]) + sq4(v[1][0]) + sq4(v[1][1]);
;                 ss += __shfl_xor(ss, 16); ss += __shfl_xor(ss, 32);
;                 float sc = rsqrtf(ss * (1.f / 64.f) + EPS); if (which == 0) sc *= QSCALE;
; #pragma unroll
;                 for (int bj = 0; bj < 2; ++bj)
; #pragma unroll
;                     for (int n = 0; n < 2; ++n) v[bj][n] = v[bj][n] * wv[bj][n] * sc;
;             }
;             const int rw = rowb[i] + fr; int arow = rw, b, t = 0; const bool prompt = rw < MP;
;             if (prompt) { b = rw >> 12; t = rw & 4095; arow = (b << 12) + ((t & ((1 << dsh) - 1)) << (12 - dsh)) + (t >> dsh); } else { b = (rw - MP) >> 3; }
;             bf16* dst = dbase + (size_t)arow * DM;
;             st_bf8(dst, v[0][0], v[0][1]); st_bf8(dst + 32, v[1][0], v[1][1]);
;             if (which >= 1) {
;                 float* o = nullptr;
;                 if (prompt) { if (t >= SEQ - W) o = kvp + (size_t)(b * W + (t - (SEQ - W))) * 2048; }
;                 else o = kvs + (size_t)(rw - MP) * 2048;
;                 if (o) { nt_store4(o, v[0][0]); nt_store4(o + 4, v[0][1]); nt_store4(o + 32, v[1][0]); nt_store4(o + 36, v[1][1]); }
.LBB0_1460:
	s_add_i32 s37, s36, s92
	v_or_b32_e32 v101, s37, v174
	v_cmp_lt_i32_e64 s[14:15], s76, v101
	s_and_saveexec_b64 s[4:5], s[14:15]
	s_xor_b64 s[4:5], exec, s[4:5]
	v_add_u32_e32 v98, 0xffffc000, v101
	v_lshrrev_b32_e32 v102, 3, v98
	s_or_saveexec_b64 s[4:5], s[4:5]
	v_mov_b32_e32 v100, 0
	v_mov_b32_e32 v98, v101
	s_xor_b64 exec, exec, s[4:5]
	v_and_b32_e32 v100, 0xfef, v101
	v_lshlrev_b32_e32 v98, s1, v101
	v_mov_b32_e32 v99, s37
	s_ashr_i32 s38, s37, 12
	v_bfi_b32 v98, s77, v98, v99
	v_lshrrev_b32_e32 v99, s0, v100
	v_add_u32_e32 v98, v98, v99
	v_mov_b32_e32 v102, s38
	s_or_b64 exec, exec, s[4:5]
	v_ashrrev_i32_e32 v99, 31, v98
	v_lshlrev_b64 v[98:99], 7, v[98:99]
	v_lshl_add_u64 v[98:99], v[156:157], 0, v[98:99]
	v_cvt_pk_bf16_f32 v104, v94, v95
	v_cvt_pk_bf16_f32 v105, v96, v97
	v_cvt_pk_bf16_f32 v106, v90, v91
	v_cvt_pk_bf16_f32 v107, v92, v93
	global_store_dwordx4 v[98:99], v[104:107], off
	s_and_b64 vcc, exec, s[12:13]
	s_nop 0
	v_cvt_pk_bf16_f32 v104, v86, v87
	v_cvt_pk_bf16_f32 v105, v88, v89
	v_cvt_pk_bf16_f32 v106, v82, v83
	v_cvt_pk_bf16_f32 v107, v84, v85
	global_store_dwordx4 v[98:99], v[104:107], off offset:64
	s_cbranch_vccnz .LBB0_1470
	s_and_saveexec_b64 s[4:5], s[14:15]
	s_xor_b64 s[4:5], exec, s[4:5]
	s_cbranch_execnz .LBB0_1539
	s_andn2_saveexec_b64 s[4:5], s[4:5]
	s_cbranch_execnz .LBB0_1540

; __device__ __forceinline__ void st_bf8(bf16* p, const f32x4 a, const f32x4 b) { *(GAS v4u*)p = (v4u){pk2(a.x, a.y), pk2(a.z, a.w), pk2(b.x, b.y), pk2(b.z, b.w)}; }
; __device__ __forceinline__ float sq4(const f32x4 a) { return (a.x * a.x + a.y * a.y) + (a.z * a.z + a.w * a.w); }
; __device__ __forceinline__ void nt_store4(float* p, f32x4 v) { __builtin_nontemporal_store(v, (f32x4*)p); }
;     template <int NR> __device__ __forceinline__ void rows(const int (&rowb)[NR], int fr, const float (&rstd)[NR], const f32x4 (&a)[NR][2][2], int pn, int wc, int fq) const {
;     ...
;         bf16* dbase = (bf16*)(qkv_base + (size_t)(which * 3 + g) * QKV_STRIDE) + h * 64 + 8 * fq;
;         float* kvp = out + (g == 0 ? O_KV128P : g == 1 ? O_KV512P : O_KV2048P) + (size_t)(which - 1) * 1024 + h * 64 + 8 * fq;
;         float* kvs = out + (g == 0 ? O_KV128S : g == 1 ? O_KV512S : O_KV2048S) + (size_t)(which - 1) * 1024 + h * 64 + 8 * fq;
; #pragma unroll
;         for (int i = 0; i < NR; ++i) {
;             const float rr = rstd[i];
;             f32x4 v[2][2] = {{a[i][0][0] * rr, a[i][0][1] * rr}, {a[i][1][0] * rr, a[i][1][1] * rr}};
;             if (which < 2) {
;                 float ss = sq4(v[0][0]) + sq4(v[0][1]) + sq4(v[1][0]) + sq4(v[1][1]);
;                 ss += __shfl_xor(ss, 16); ss += __shfl_xor(ss, 32);
;                 float sc = rsqrtf(ss * (1.f / 64.f) + EPS); if (which == 0) sc *= QSCALE;
; #pragma unroll
;                 for (int bj = 0; bj < 2; ++bj)
; #pragma unroll
;                     for (int n = 0; n < 2; ++n) v[bj][n] = v[bj][n] * wv[bj][n] * sc;
;             }
;             const int rw = rowb[i] + fr; int arow = rw, b, t = 0; const bool prompt = rw < MP;
;             if (prompt) { b = rw >> 12; t = rw & 4095; arow = (b << 12) + ((t & ((1 << dsh) - 1)) << (12 - dsh)) + (t >> dsh); } else { b = (rw - MP) >> 3; }
;             bf16* dst = dbase + (size_t)arow * DM;
;             st_bf8(dst, v[0][0], v[0][1]); st_bf8(dst + 32, v[1][0], v[1][1]);
;             if (which >= 1) {
;                 float* o = nullptr;
;                 if (prompt) { if (t >= SEQ - W) o = kvp + (size_t)(b * W + (t - (SEQ - W))) * 2048; }
;                 else o = kvs + (size_t)(rw - MP) * 2048;
;                 if (o) { nt_store4(o, v[0][0]); nt_store4(o + 4, v[0][1]); nt_store4(o + 32, v[1][0]); nt_store4(o + 36, v[1][1]); }
.LBB0_1472:
	s_add_i32 s36, s36, s93
	v_or_b32_e32 v85, s36, v174
	v_cmp_lt_i32_e64 s[14:15], s76, v85
	s_and_saveexec_b64 s[4:5], s[14:15]
	s_xor_b64 s[4:5], exec, s[4:5]
	v_add_u32_e32 v82, 0xffffc000, v85
	v_lshrrev_b32_e32 v86, 3, v82
	s_or_saveexec_b64 s[4:5], s[4:5]
	v_mov_b32_e32 v84, 0
	v_mov_b32_e32 v82, v85
	s_xor_b64 exec, exec, s[4:5]
	v_and_b32_e32 v84, 0xfff, v85
	v_lshlrev_b32_e32 v82, s1, v85
	v_mov_b32_e32 v83, s36
	s_ashr_i32 s37, s36, 12
	v_bfi_b32 v82, s77, v82, v83
	v_lshrrev_b32_e32 v83, s0, v84
	v_add_u32_e32 v82, v82, v83
	v_mov_b32_e32 v86, s37
	s_or_b64 exec, exec, s[4:5]
	v_ashrrev_i32_e32 v83, 31, v82
	v_lshlrev_b64 v[82:83], 7, v[82:83]
	v_lshl_add_u64 v[82:83], v[156:157], 0, v[82:83]
	v_cvt_pk_bf16_f32 v88, v78, v79
	v_cvt_pk_bf16_f32 v89, v80, v81
	v_cvt_pk_bf16_f32 v90, v74, v75
	v_cvt_pk_bf16_f32 v91, v76, v77
	global_store_dwordx4 v[82:83], v[88:91], off
	s_and_b64 vcc, exec, s[12:13]
	s_nop 0
	v_cvt_pk_bf16_f32 v88, v70, v71
	v_cvt_pk_bf16_f32 v89, v72, v73
	v_cvt_pk_bf16_f32 v90, v66, v67
	v_cvt_pk_bf16_f32 v91, v68, v69
	global_store_dwordx4 v[82:83], v[88:91], off offset:64
	s_cbranch_vccnz .LBB0_1482
	s_and_saveexec_b64 s[4:5], s[14:15]
	s_xor_b64 s[4:5], exec, s[4:5]
	s_cbranch_execnz .LBB0_1541
	s_andn2_saveexec_b64 s[4:5], s[4:5]
	s_cbranch_execnz .LBB0_1542

; __device__ __forceinline__ void st_bf8(bf16* p, const f32x4 a, const f32x4 b) { *(GAS v4u*)p = (v4u){pk2(a.x, a.y), pk2(a.z, a.w), pk2(b.x, b.y), pk2(b.z, b.w)}; }
; __device__ __forceinline__ float sq4(const f32x4 a) { return (a.x * a.x + a.y * a.y) + (a.z * a.z + a.w * a.w); }
; __device__ __forceinline__ void nt_store4(float* p, f32x4 v) { __builtin_nontemporal_store(v, (f32x4*)p); }
;     template <int NR> __device__ __forceinline__ void rows(const int (&rowb)[NR], int fr, const float (&rstd)[NR], const f32x4 (&a)[NR][2][2], int pn, int wc, int fq) const {
;     ...
;         bf16* dbase = (bf16*)(qkv_base + (size_t)(which * 3 + g) * QKV_STRIDE) + h * 64 + 8 * fq;
;         float* kvp = out + (g == 0 ? O_KV128P : g == 1 ? O_KV512P : O_KV2048P) + (size_t)(which - 1) * 1024 + h * 64 + 8 * fq;
;         float* kvs = out + (g == 0 ? O_KV128S : g == 1 ? O_KV512S : O_KV2048S) + (size_t)(which - 1) * 1024 + h * 64 + 8 * fq;
; #pragma unroll
;         for (int i = 0; i < NR; ++i) {
;             const float rr = rstd[i];
;             f32x4 v[2][2] = {{a[i][0][0] * rr, a[i][0][1] * rr}, {a[i][1][0] * rr, a[i][1][1] * rr}};
;             if (which < 2) {
;                 float ss = sq4(v[0][0]) + sq4(v[0][1]) + sq4(v[1][0]) + sq4(v[1][1]);
;                 ss += __shfl_xor(ss, 16); ss += __shfl_xor(ss, 32);
;                 float sc = rsqrtf(ss * (1.f / 64.f) + EPS); if (which == 0) sc *= QSCALE;
; #pragma unroll
;                 for (int bj = 0; bj < 2; ++bj)
; #pragma unroll
;                     for (int n = 0; n < 2; ++n) v[bj][n] = v[bj][n] * wv[bj][n] * sc;
;             }
;             const int rw = rowb[i] + fr; int arow = rw, b, t = 0; const bool prompt = rw < MP;
;             if (prompt) { b = rw >> 12; t = rw & 4095; arow = (b << 12) + ((t & ((1 << dsh) - 1)) << (12 - dsh)) + (t >> dsh); } else { b = (rw - MP) >> 3; }
;             bf16* dst = dbase + (size_t)arow * DM;
;             st_bf8(dst, v[0][0], v[0][1]); st_bf8(dst + 32, v[1][0], v[1][1]);
;             if (which >= 1) {
;                 float* o = nullptr;
;                 if (prompt) { if (t >= SEQ - W) o = kvp + (size_t)(b * W + (t - (SEQ - W))) * 2048; }
;                 else o = kvs + (size_t)(rw - MP) * 2048;
;                 if (o) { nt_store4(o, v[0][0]); nt_store4(o + 4, v[0][1]); nt_store4(o + 32, v[1][0]); nt_store4(o + 36, v[1][1]); }
.LBB0_1486:
	s_add_i32 s36, s67, 0x80
	v_or_b32_e32 v88, s36, v174
	v_cmp_lt_i32_e64 s[14:15], s76, v88
	s_and_saveexec_b64 s[4:5], s[14:15]
	s_xor_b64 s[4:5], exec, s[4:5]
	v_add_u32_e32 v84, 0xffffc000, v88
	v_lshrrev_b32_e32 v89, 3, v84
	s_or_saveexec_b64 s[4:5], s[4:5]
	v_mov_b32_e32 v84, 0
	v_mov_b32_e32 v86, v88
	s_xor_b64 exec, exec, s[4:5]
	v_and_b32_e32 v84, 0xfcf, v88
	v_lshlrev_b32_e32 v86, s1, v88
	v_mov_b32_e32 v87, s36
	s_ashr_i32 s37, s36, 12
	v_bfi_b32 v86, s77, v86, v87
	v_lshrrev_b32_e32 v87, s0, v84
	v_add_u32_e32 v86, v86, v87
	v_mov_b32_e32 v89, s37
	s_or_b64 exec, exec, s[4:5]
	v_ashrrev_i32_e32 v87, 31, v86
	v_lshlrev_b64 v[86:87], 7, v[86:87]
	v_lshl_add_u64 v[86:87], v[156:157], 0, v[86:87]
	v_cvt_pk_bf16_f32 v90, v62, v63
	v_cvt_pk_bf16_f32 v91, v64, v65
	v_cvt_pk_bf16_f32 v92, v58, v59
	v_cvt_pk_bf16_f32 v93, v60, v61
	global_store_dwordx4 v[86:87], v[90:93], off
	s_and_b64 vcc, exec, s[12:13]
	s_nop 0
	v_cvt_pk_bf16_f32 v90, v54, v55
	v_cvt_pk_bf16_f32 v91, v56, v57
	v_cvt_pk_bf16_f32 v92, v50, v51
	v_cvt_pk_bf16_f32 v93, v52, v53
	global_store_dwordx4 v[86:87], v[90:93], off offset:64
	s_cbranch_vccnz .LBB0_1496
	s_and_saveexec_b64 s[4:5], s[14:15]
	s_xor_b64 s[4:5], exec, s[4:5]
	s_cbranch_execnz .LBB0_1543
	s_andn2_saveexec_b64 s[4:5], s[4:5]
	s_cbranch_execnz .LBB0_1544

; __device__ __forceinline__ void st_bf8(bf16* p, const f32x4 a, const f32x4 b) { *(GAS v4u*)p = (v4u){pk2(a.x, a.y), pk2(a.z, a.w), pk2(b.x, b.y), pk2(b.z, b.w)}; }
; __device__ __forceinline__ float sq4(const f32x4 a) { return (a.x * a.x + a.y * a.y) + (a.z * a.z + a.w * a.w); }
; __device__ __forceinline__ void nt_store4(float* p, f32x4 v) { __builtin_nontemporal_store(v, (f32x4*)p); }
;     template <int NR> __device__ __forceinline__ void rows(const int (&rowb)[NR], int fr, const float (&rstd)[NR], const f32x4 (&a)[NR][2][2], int pn, int wc, int fq) const {
;     ...
;         bf16* dbase = (bf16*)(qkv_base + (size_t)(which * 3 + g) * QKV_STRIDE) + h * 64 + 8 * fq;
;         float* kvp = out + (g == 0 ? O_KV128P : g == 1 ? O_KV512P : O_KV2048P) + (size_t)(which - 1) * 1024 + h * 64 + 8 * fq;
;         float* kvs = out + (g == 0 ? O_KV128S : g == 1 ? O_KV512S : O_KV2048S) + (size_t)(which - 1) * 1024 + h * 64 + 8 * fq;
; #pragma unroll
;         for (int i = 0; i < NR; ++i) {
;             const float rr = rstd[i];
;             f32x4 v[2][2] = {{a[i][0][0] * rr, a[i][0][1] * rr}, {a[i][1][0] * rr, a[i][1][1] * rr}};
;             if (which < 2) {
;                 float ss = sq4(v[0][0]) + sq4(v[0][1]) + sq4(v[1][0]) + sq4(v[1][1]);
;                 ss += __shfl_xor(ss, 16); ss += __shfl_xor(ss, 32);
;                 float sc = rsqrtf(ss * (1.f / 64.f) + EPS); if (which == 0) sc *= QSCALE;
; #pragma unroll
;                 for (int bj = 0; bj < 2; ++bj)
; #pragma unroll
;                     for (int n = 0; n < 2; ++n) v[bj][n] = v[bj][n] * wv[bj][n] * sc;
;             }
;             const int rw = rowb[i] + fr; int arow = rw, b, t = 0; const bool prompt = rw < MP;
;             if (prompt) { b = rw >> 12; t = rw & 4095; arow = (b << 12) + ((t & ((1 << dsh) - 1)) << (12 - dsh)) + (t >> dsh); } else { b = (rw - MP) >> 3; }
;             bf16* dst = dbase + (size_t)arow * DM;
;             st_bf8(dst, v[0][0], v[0][1]); st_bf8(dst + 32, v[1][0], v[1][1]);
;             if (which >= 1) {
;                 float* o = nullptr;
;                 if (prompt) { if (t >= SEQ - W) o = kvp + (size_t)(b * W + (t - (SEQ - W))) * 2048; }
;                 else o = kvs + (size_t)(rw - MP) * 2048;
;                 if (o) { nt_store4(o, v[0][0]); nt_store4(o + 4, v[0][1]); nt_store4(o + 32, v[1][0]); nt_store4(o + 36, v[1][1]); }
.LBB0_1498:
	s_add_i32 s36, s67, 0x90
	v_or_b32_e32 v53, s36, v174
	v_cmp_lt_i32_e64 s[14:15], s76, v53
	s_and_saveexec_b64 s[4:5], s[14:15]
	s_xor_b64 s[4:5], exec, s[4:5]
	v_add_u32_e32 v50, 0xffffc000, v53
	v_lshrrev_b32_e32 v54, 3, v50
	s_or_saveexec_b64 s[4:5], s[4:5]
	v_mov_b32_e32 v52, 0
	v_mov_b32_e32 v50, v53
	s_xor_b64 exec, exec, s[4:5]
	v_and_b32_e32 v52, 0xfdf, v53
	v_lshlrev_b32_e32 v50, s1, v53
	v_mov_b32_e32 v51, s36
	s_ashr_i32 s37, s36, 12
	v_bfi_b32 v50, s77, v50, v51
	v_lshrrev_b32_e32 v51, s0, v52
	v_add_u32_e32 v50, v50, v51
	v_mov_b32_e32 v54, s37
	s_or_b64 exec, exec, s[4:5]
	v_ashrrev_i32_e32 v51, 31, v50
	v_lshlrev_b64 v[50:51], 7, v[50:51]
	v_lshl_add_u64 v[50:51], v[156:157], 0, v[50:51]
	v_cvt_pk_bf16_f32 v56, v46, v47
	v_cvt_pk_bf16_f32 v57, v48, v49
	v_cvt_pk_bf16_f32 v58, v42, v43
	v_cvt_pk_bf16_f32 v59, v44, v45
	global_store_dwordx4 v[50:51], v[56:59], off
	s_and_b64 vcc, exec, s[12:13]
	s_nop 0
	v_cvt_pk_bf16_f32 v56, v38, v39
	v_cvt_pk_bf16_f32 v57, v40, v41
	v_cvt_pk_bf16_f32 v58, v34, v35
	v_cvt_pk_bf16_f32 v59, v36, v37
	global_store_dwordx4 v[50:51], v[56:59], off offset:64
	s_cbranch_vccnz .LBB0_1508
	s_and_saveexec_b64 s[4:5], s[14:15]
	s_xor_b64 s[4:5], exec, s[4:5]
	s_cbranch_execnz .LBB0_1545
	s_andn2_saveexec_b64 s[4:5], s[4:5]
	s_cbranch_execnz .LBB0_1546

; __device__ __forceinline__ void st_bf8(bf16* p, const f32x4 a, const f32x4 b) { *(GAS v4u*)p = (v4u){pk2(a.x, a.y), pk2(a.z, a.w), pk2(b.x, b.y), pk2(b.z, b.w)}; }
; __device__ __forceinline__ float sq4(const f32x4 a) { return (a.x * a.x + a.y * a.y) + (a.z * a.z + a.w * a.w); }
; __device__ __forceinline__ void nt_store4(float* p, f32x4 v) { __builtin_nontemporal_store(v, (f32x4*)p); }
;     template <int NR> __device__ __forceinline__ void rows(const int (&rowb)[NR], int fr, const float (&rstd)[NR], const f32x4 (&a)[NR][2][2], int pn, int wc, int fq) const {
;     ...
;         bf16* dbase = (bf16*)(qkv_base + (size_t)(which * 3 + g) * QKV_STRIDE) + h * 64 + 8 * fq;
;         float* kvp = out + (g == 0 ? O_KV128P : g == 1 ? O_KV512P : O_KV2048P) + (size_t)(which - 1) * 1024 + h * 64 + 8 * fq;
;         float* kvs = out + (g == 0 ? O_KV128S : g == 1 ? O_KV512S : O_KV2048S) + (size_t)(which - 1) * 1024 + h * 64 + 8 * fq;
; #pragma unroll
;         for (int i = 0; i < NR; ++i) {
;             const float rr = rstd[i];
;             f32x4 v[2][2] = {{a[i][0][0] * rr, a[i][0][1] * rr}, {a[i][1][0] * rr, a[i][1][1] * rr}};
;             if (which < 2) {
;                 float ss = sq4(v[0][0]) + sq4(v[0][1]) + sq4(v[1][0]) + sq4(v[1][1]);
;                 ss += __shfl_xor(ss, 16); ss += __shfl_xor(ss, 32);
;                 float sc = rsqrtf(ss * (1.f / 64.f) + EPS); if (which == 0) sc *= QSCALE;
; #pragma unroll
;                 for (int bj = 0; bj < 2; ++bj)
; #pragma unroll
;                     for (int n = 0; n < 2; ++n) v[bj][n] = v[bj][n] * wv[bj][n] * sc;
;             }
;             const int rw = rowb[i] + fr; int arow = rw, b, t = 0; const bool prompt = rw < MP;
;             if (prompt) { b = rw >> 12; t = rw & 4095; arow = (b << 12) + ((t & ((1 << dsh) - 1)) << (12 - dsh)) + (t >> dsh); } else { b = (rw - MP) >> 3; }
;             bf16* dst = dbase + (size_t)arow * DM;
;             st_bf8(dst, v[0][0], v[0][1]); st_bf8(dst + 32, v[1][0], v[1][1]);
;             if (which >= 1) {
;                 float* o = nullptr;
;                 if (prompt) { if (t >= SEQ - W) o = kvp + (size_t)(b * W + (t - (SEQ - W))) * 2048; }
;                 else o = kvs + (size_t)(rw - MP) * 2048;
;                 if (o) { nt_store4(o, v[0][0]); nt_store4(o + 4, v[0][1]); nt_store4(o + 32, v[1][0]); nt_store4(o + 36, v[1][1]); }
.LBB0_1510:
	s_add_i32 s36, s67, 0xa0
	v_or_b32_e32 v37, s36, v174
	v_cmp_lt_i32_e64 s[14:15], s76, v37
	s_and_saveexec_b64 s[4:5], s[14:15]
	s_xor_b64 s[4:5], exec, s[4:5]
	v_add_u32_e32 v34, 0xffffc000, v37
	v_lshrrev_b32_e32 v38, 3, v34
	s_or_saveexec_b64 s[4:5], s[4:5]
	v_mov_b32_e32 v36, 0
	v_mov_b32_e32 v34, v37
	s_xor_b64 exec, exec, s[4:5]
	v_and_b32_e32 v36, 0xfef, v37
	v_lshlrev_b32_e32 v34, s1, v37
	v_mov_b32_e32 v35, s36
	s_ashr_i32 s37, s36, 12
	v_bfi_b32 v34, s77, v34, v35
	v_lshrrev_b32_e32 v35, s0, v36
	v_add_u32_e32 v34, v34, v35
	v_mov_b32_e32 v38, s37
	s_or_b64 exec, exec, s[4:5]
	v_ashrrev_i32_e32 v35, 31, v34
	v_lshlrev_b64 v[34:35], 7, v[34:35]
	v_lshl_add_u64 v[34:35], v[156:157], 0, v[34:35]
	v_cvt_pk_bf16_f32 v40, v30, v31
	v_cvt_pk_bf16_f32 v41, v32, v33
	v_cvt_pk_bf16_f32 v42, v26, v27
	v_cvt_pk_bf16_f32 v43, v28, v29
	global_store_dwordx4 v[34:35], v[40:43], off
	s_and_b64 vcc, exec, s[12:13]
	s_nop 0
	v_cvt_pk_bf16_f32 v40, v22, v23
	v_cvt_pk_bf16_f32 v41, v24, v25
	v_cvt_pk_bf16_f32 v42, v18, v19
	v_cvt_pk_bf16_f32 v43, v20, v21
	global_store_dwordx4 v[34:35], v[40:43], off offset:64
	s_cbranch_vccnz .LBB0_1520
	s_and_saveexec_b64 s[4:5], s[14:15]
	s_xor_b64 s[4:5], exec, s[4:5]
	s_cbranch_execnz .LBB0_1547
	s_andn2_saveexec_b64 s[4:5], s[4:5]
	s_cbranch_execnz .LBB0_1548

; __device__ __forceinline__ void st_bf8(bf16* p, const f32x4 a, const f32x4 b) { *(GAS v4u*)p = (v4u){pk2(a.x, a.y), pk2(a.z, a.w), pk2(b.x, b.y), pk2(b.z, b.w)}; }
; __device__ __forceinline__ float sq4(const f32x4 a) { return (a.x * a.x + a.y * a.y) + (a.z * a.z + a.w * a.w); }
; __device__ __forceinline__ void nt_store4(float* p, f32x4 v) { __builtin_nontemporal_store(v, (f32x4*)p); }
;     template <int NR> __device__ __forceinline__ void rows(const int (&rowb)[NR], int fr, const float (&rstd)[NR], const f32x4 (&a)[NR][2][2], int pn, int wc, int fq) const {
;     ...
;         bf16* dbase = (bf16*)(qkv_base + (size_t)(which * 3 + g) * QKV_STRIDE) + h * 64 + 8 * fq;
;         float* kvp = out + (g == 0 ? O_KV128P : g == 1 ? O_KV512P : O_KV2048P) + (size_t)(which - 1) * 1024 + h * 64 + 8 * fq;
;         float* kvs = out + (g == 0 ? O_KV128S : g == 1 ? O_KV512S : O_KV2048S) + (size_t)(which - 1) * 1024 + h * 64 + 8 * fq;
; #pragma unroll
;         for (int i = 0; i < NR; ++i) {
;             const float rr = rstd[i];
;             f32x4 v[2][2] = {{a[i][0][0] * rr, a[i][0][1] * rr}, {a[i][1][0] * rr, a[i][1][1] * rr}};
;             if (which < 2) {
;                 float ss = sq4(v[0][0]) + sq4(v[0][1]) + sq4(v[1][0]) + sq4(v[1][1]);
;                 ss += __shfl_xor(ss, 16); ss += __shfl_xor(ss, 32);
;                 float sc = rsqrtf(ss * (1.f / 64.f) + EPS); if (which == 0) sc *= QSCALE;
; #pragma unroll
;                 for (int bj = 0; bj < 2; ++bj)
; #pragma unroll
;                     for (int n = 0; n < 2; ++n) v[bj][n] = v[bj][n] * wv[bj][n] * sc;
;             }
;             const int rw = rowb[i] + fr; int arow = rw, b, t = 0; const bool prompt = rw < MP;
;             if (prompt) { b = rw >> 12; t = rw & 4095; arow = (b << 12) + ((t & ((1 << dsh) - 1)) << (12 - dsh)) + (t >> dsh); } else { b = (rw - MP) >> 3; }
;             bf16* dst = dbase + (size_t)arow * DM;
;             st_bf8(dst, v[0][0], v[0][1]); st_bf8(dst + 32, v[1][0], v[1][1]);
;             if (which >= 1) {
;                 float* o = nullptr;
;                 if (prompt) { if (t >= SEQ - W) o = kvp + (size_t)(b * W + (t - (SEQ - W))) * 2048; }
;                 else o = kvs + (size_t)(rw - MP) * 2048;
;                 if (o) { nt_store4(o, v[0][0]); nt_store4(o + 4, v[0][1]); nt_store4(o + 32, v[1][0]); nt_store4(o + 36, v[1][1]); }
.LBB0_1522:
	s_add_i32 s10, s67, 0xb0
	v_or_b32_e32 v22, s10, v174
	v_cmp_lt_i32_e64 s[8:9], s76, v22
	s_and_saveexec_b64 s[4:5], s[8:9]
	s_xor_b64 s[4:5], exec, s[4:5]
	v_add_u32_e32 v18, 0xffffc000, v22
	v_lshrrev_b32_e32 v21, 3, v18
	s_or_saveexec_b64 s[4:5], s[4:5]
	v_mov_b32_e32 v20, 0
	v_mov_b32_e32 v18, v22
	s_xor_b64 exec, exec, s[4:5]
	v_and_b32_e32 v20, 0xfff, v22
	v_lshlrev_b32_e32 v18, s1, v22
	v_mov_b32_e32 v19, s10
	s_ashr_i32 s11, s10, 12
	v_bfi_b32 v18, s77, v18, v19
	v_lshrrev_b32_e32 v19, s0, v20
	v_add_u32_e32 v18, v18, v19
	v_mov_b32_e32 v21, s11
	s_or_b64 exec, exec, s[4:5]
	v_ashrrev_i32_e32 v19, 31, v18
	v_lshlrev_b64 v[18:19], 7, v[18:19]
	v_lshl_add_u64 v[18:19], v[156:157], 0, v[18:19]
	v_cvt_pk_bf16_f32 v24, v14, v15
	v_cvt_pk_bf16_f32 v25, v16, v17
	v_cvt_pk_bf16_f32 v26, v10, v11
	v_cvt_pk_bf16_f32 v27, v12, v13
	global_store_dwordx4 v[18:19], v[24:27], off
	s_and_b64 vcc, exec, s[12:13]
	s_nop 0
	v_cvt_pk_bf16_f32 v24, v6, v7
	v_cvt_pk_bf16_f32 v25, v8, v9
	v_cvt_pk_bf16_f32 v26, v2, v3
	v_cvt_pk_bf16_f32 v27, v4, v5
	global_store_dwordx4 v[18:19], v[24:27], off offset:64
	s_cbranch_vccnz .LBB0_1532
	s_and_saveexec_b64 s[0:1], s[8:9]
	s_xor_b64 s[4:5], exec, s[0:1]
	s_cbranch_execnz .LBB0_1549
	s_andn2_saveexec_b64 s[4:5], s[4:5]
	s_cbranch_execnz .LBB0_1550

; #define GAS __attribute__((address_space(1)))
; __device__ __forceinline__ float bflo(unsigned w) { return __uint_as_float(w << 16); }
; __device__ __forceinline__ float bfhi(unsigned w) { return __uint_as_float(w & 0xffff0000u); }
; __device__ __forceinline__ float alibi_slope2(int g, int h) { return exp2f(-8.f * (float)(g * 16 + h + 1) / 48.f) * LOG2E; }
; __device__ __forceinline__ void attn_sample(Frame& F, int i_lo, int i_hi) {
;     const int lane = F.lane, ksub = lane >> 5, hh = (lane >> 4) & 1, dc = lane & 15, w = F.wave;
;     float* LSE = WSP(float, WS_LSE);
;     for (int rnd = i_lo; rnd < i_hi; ++rnd) { const int it = F.bid + rnd * F.G;
;         int s, grp, b;
;         if (F.G == 256) {
;             const int x = F.bid & 7, q = F.bid >> 3, u = (x & 1) ? 64 + 8 * (x >> 1) + 4 * rnd + (q >> 3) : 16 * (x >> 1) + 4 * rnd + (q >> 3); s = q & 7; b = u / 3; grp = u % 3; }
;         else { if (it >= 768) break; s = it & 7; grp = (it >> 3) % 3; b = it / 24; }
;         const int dsh = 2 * grp, W = 128 << dsh, dil = 1 << dsh;
;         const float* cache = F.in[3 + grp] + (size_t)b * W * 2048;
;         const float* newkv = F.out + (grp == 0 ? O_KV128S : grp == 1 ? O_KV512S : O_KV2048S) + (size_t)b * 8 * 2048;
;         const bf16* Qg = (const bf16*)(F.ws + WS_QKV + (size_t)grp * QKV_STRIDE);
;         bf16* Og = (bf16*)(F.ws + WS_OG + (size_t)grp * QKV_STRIDE);
;         const size_t row = (size_t)MP + b * 8 + s;
;         const int h = 2 * w + hh, co = h * 64 + 4 * dc;
;         const v2u qw = *(const GAS v2u*)(Qg + row * DM + co);
;         const f32x4 q = (f32x4){bflo(qw.x), bfhi(qw.x), bflo(qw.y), bfhi(qw.y)};
;         const float sl2 = alibi_slope2(grp, h) * (float)dil;
;         float mx = -INFINITY, lsum = 0.f; f32x4 o = (f32x4){0.f, 0.f, 0.f, 0.f};
.LBB0_1552:
	v_readlane_b32 s36, v245, 27
	v_readlane_b32 s37, v245, 28
	v_cmp_le_i32_e32 vcc, v166, v167
	s_cbranch_vccnz .LBB0_1570
	v_readlane_b32 s0, v245, 8
	v_lshrrev_b32_e32 v2, 4, v160
	s_lshl_b32 s0, s0, 1
	v_lshlrev_b32_e32 v3, 2, v160
	v_and_or_b32 v2, v2, 1, s0
	v_and_b32_e32 v3, 60, v3
	v_lshl_or_b32 v162, v2, 6, v3
	v_mov_b32_e32 v163, 0
	v_and_b32_e32 v3, 47, v160
	v_add_u32_e32 v197, 1, v2
	v_cmp_eq_u32_e64 s[8:9], 0, v3
	v_lshlrev_b32_e32 v2, 2, v2
	v_mov_b32_e32 v3, v163
	v_lshl_add_u64 v[2:3], s[30:31], 0, v[2:3]
	s_mov_b64 s[0:1], 0x29300000
	s_lshl_b32 s4, s2, 2
	v_lshl_add_u64 v[164:165], v[2:3], 0, s[0:1]
	s_and_b32 s0, s2, 7
	s_and_b32 s4, s4, 24
	s_ashr_i32 s5, s2, 6
	s_add_i32 s4, s5, s4
	s_lshl_b32 s0, s0, 3
	s_lshr_b32 s18, s2, 3
	s_and_b32 s1, s2, 1
	s_add_i32 s4, s4, 64
	s_add_i32 s0, s0, s5
	s_add_u32 s12, s30, 0x23000000
	v_mbcnt_lo_u32_b32 v2, -1, 0
	s_addc_u32 s13, s31, 0
	v_mbcnt_hi_u32_b32 v216, -1, v2
	s_waitcnt lgkmcnt(0)
	v_or_b32_e32 v4, 0x80, v161
	s_cmp_eq_u32 s1, 0
	v_and_b32_e32 v2, 64, v216
	s_movk_i32 s3, 0x80
	v_cmp_gt_u32_e64 s[6:7], 32, v160
	v_or_b32_e32 v199, 2, v161
	v_or_b32_e32 v201, 4, v161
	v_or_b32_e32 v204, 6, v161
	v_or_b32_e32 v205, 8, v161
	v_or_b32_e32 v206, 10, v161
	v_or_b32_e32 v207, 12, v161
	v_or_b32_e32 v208, 14, v161
	v_cmp_eq_u32_e64 s[10:11], 0, v161
	v_cvt_f32_ubyte0_e32 v209, v4
	s_cselect_b32 s19, s0, s4
	s_movk_i32 s20, 0x300
	s_mov_b32 s21, 0x2aaaaaab
	s_mov_b32 s22, 0x55555556
	s_mov_b32 s23, 0x2100000
	s_mov_b64 s[14:15], 0x4000
	s_mov_b32 s26, 0x42400000
	s_mov_b32 s27, 0xc2fc0000
	v_lshlrev_b64 v[166:167], 2, v[162:163]
	s_movk_i32 s33, 0x1000
	s_movk_i32 s34, 0x81
	s_mov_b32 s35, 0xff800000
	s_movk_i32 s40, 0x7f
	s_movk_i32 s41, 0x7d
	s_movk_i32 s42, 0x7b
	s_movk_i32 s43, 0x79
	s_movk_i32 s45, 0x77
	s_movk_i32 s46, 0x75
	s_movk_i32 s47, 0x73
	s_movk_i32 s48, 0x4100
	v_mov_b32_e32 v210, 0x2ac0000
	v_mov_b32_e32 v211, 0x1a40000
	v_mov_b32_e32 v212, 0x15c0000
	v_lshlrev_b32_e32 v213, 1, v162
	v_lshrrev_b32_e32 v255, 6, v162
	v_and_b32_e32 v254, 63, v162
	v_lshlrev_b32_e32 v254, 1, v254
	v_mul_u32_u24_e32 v255, 0x208000, v255
	v_add_u32_e32 v254, v255, v254
	v_mov_b32_e32 v214, 0x42800000
	v_not_b32_e32 v215, 63
	v_xor_b32_e32 v217, 1, v216
	v_add_u32_e32 v218, 64, v2
	v_xor_b32_e32 v219, 2, v216
	v_xor_b32_e32 v220, 4, v216
	v_xor_b32_e32 v221, 8, v216
	v_xor_b32_e32 v222, 32, v216
	v_mov_b32_e32 v223, 0xff800000
	s_branch .LBB0_1556

; #define GAS __attribute__((address_space(1)))
; __device__ __forceinline__ float bflo(unsigned w) { return __uint_as_float(w << 16); }
; __device__ __forceinline__ float bfhi(unsigned w) { return __uint_as_float(w & 0xffff0000u); }
; __device__ __forceinline__ float alibi_slope2(int g, int h) { return exp2f(-8.f * (float)(g * 16 + h + 1) / 48.f) * LOG2E; }
; __device__ __forceinline__ void attn_sample(Frame& F, int i_lo, int i_hi) {
;     ...
;         const int dsh = 2 * grp, W = 128 << dsh, dil = 1 << dsh;
;         const float* cache = F.in[3 + grp] + (size_t)b * W * 2048;
;         const float* newkv = F.out + (grp == 0 ? O_KV128S : grp == 1 ? O_KV512S : O_KV2048S) + (size_t)b * 8 * 2048;
;         const bf16* Qg = (const bf16*)(F.ws + WS_QKV + (size_t)grp * QKV_STRIDE);
;         bf16* Og = (bf16*)(F.ws + WS_OG + (size_t)grp * QKV_STRIDE);
;         const size_t row = (size_t)MP + b * 8 + s;
;         const int h = 2 * w + hh, co = h * 64 + 4 * dc;
;         const v2u qw = *(const GAS v2u*)(Qg + row * DM + co);
;         const f32x4 q = (f32x4){bflo(qw.x), bfhi(qw.x), bflo(qw.y), bfhi(qw.y)};
;         const float sl2 = alibi_slope2(grp, h) * (float)dil;
;         float mx = -INFINITY, lsum = 0.f; f32x4 o = (f32x4){0.f, 0.f, 0.f, 0.f};
;     ...
;         f32x4 ka[8], va[8], kb[8], vb[8];
;         SMP_LOAD(ka, va, 0);
; #pragma unroll 1
;         for (int j0 = 0; j0 < 128; j0 += 32) {
;             SMP_LOAD(kb, vb, j0 + 16);
.LBB0_1561:
	s_andn2_b64 vcc, exec, s[4:5]
	s_cbranch_vccnz .LBB0_1555
	s_waitcnt lgkmcnt(0)
	v_and_b32_e32 v8, 7, v4
	v_mul_hi_i32 v4, v3, s22
	v_lshrrev_b32_e32 v5, 31, v4
	v_add_u32_e32 v4, v4, v5
	v_mul_lo_u32 v4, v4, 3
	v_sub_u32_e32 v168, v3, v4
	v_ashrrev_i32_e32 v169, 31, v168
	v_lshlrev_b64 v[4:5], 3, v[168:169]
	v_lshl_add_u64 v[4:5], s[88:89], 0, v[4:5]
	v_lshlrev_b32_e32 v224, 1, v168
	v_readfirstlane_b32 s0, v4
	v_readfirstlane_b32 s1, v5
	s_load_dwordx2 s[0:1], s[0:1], 0x18
	v_ashrrev_i32_e32 v3, 31, v2
	v_add_u32_e32 v4, 7, v224
	v_lshlrev_b64 v[4:5], v4, v[2:3]
	v_lshlrev_b64 v[4:5], 13, v[4:5]
	v_cmp_eq_u32_e32 vcc, 1, v168
	s_waitcnt lgkmcnt(0)
	v_lshl_add_u64 v[174:175], s[0:1], 0, v[4:5]
	v_lshlrev_b64 v[6:7], 16, v[2:3]
	v_cndmask_b32_e32 v4, v210, v211, vcc
	v_cmp_ne_u32_e32 vcc, 0, v168
	v_lshlrev_b32_e32 v2, 3, v2
	v_ashrrev_i32_e32 v3, 31, v2
	v_cndmask_b32_e32 v4, v212, v4, vcc
	v_lshlrev_b32_e32 v162, 2, v4
	v_or_b32_e32 v2, v2, v8
	v_lshl_add_u64 v[4:5], s[28:29], 0, v[162:163]
	v_mul_hi_i32 v173, v168, s23
	v_mul_lo_u32 v172, v168, s23
	v_lshl_add_u64 v[170:171], v[2:3], 0, s[14:15]
	v_lshl_add_u64 v[176:177], v[4:5], 0, v[6:7]
	v_lshl_add_u64 v[4:5], s[24:25], 0, v[172:173]
	v_lshlrev_b64 v[2:3], 7, v[170:171]
	v_lshlrev_b32_e64 v225, v224, s3
	v_lshl_add_u64 v[2:3], v[4:5], 0, v[2:3]
	v_or_b32_e32 v169, v225, v8
	v_readfirstlane_b32 s0, v2
	v_lshlrev_b32_e32 v2, v224, v161
	v_sub_u32_e32 v2, v169, v2
	v_readfirstlane_b32 s1, v3
	v_ashrrev_i32_e32 v3, 31, v2
	v_sub_u32_e32 v4, v2, v225
	v_cmp_lt_i32_e32 vcc, v2, v225
	v_lshlrev_b32_e32 v6, v224, v199
	v_sub_u32_e32 v6, v169, v6
	v_cndmask_b32_e32 v3, 0, v3, vcc
	v_cndmask_b32_e32 v2, v4, v2, vcc
	v_cndmask_b32_e32 v5, v177, v175, vcc
	v_cndmask_b32_e32 v4, v176, v174, vcc
	v_lshlrev_b64 v[2:3], 13, v[2:3]
	v_lshl_add_u64 v[2:3], v[4:5], 0, v[2:3]
	v_lshl_add_u64 v[2:3], v[2:3], 0, v[166:167]
	v_add_co_u32_e32 v4, vcc, s33, v2
	v_ashrrev_i32_e32 v7, 31, v6
	s_nop 0
	v_addc_co_u32_e32 v5, vcc, 0, v3, vcc
	v_sub_u32_e32 v8, v6, v225
	v_cmp_lt_i32_e32 vcc, v6, v225
	global_load_dwordx2 v[34:35], v254, s[0:1]
	global_load_dwordx4 v[94:97], v[2:3], off nt
	s_nop 0
	global_load_dwordx4 v[2:5], v[4:5], off nt
	v_cndmask_b32_e32 v7, 0, v7, vcc
	v_cndmask_b32_e32 v6, v8, v6, vcc
	v_cndmask_b32_e32 v9, v177, v175, vcc
	v_cndmask_b32_e32 v8, v176, v174, vcc
	v_lshlrev_b64 v[6:7], 13, v[6:7]
	v_lshl_add_u64 v[6:7], v[8:9], 0, v[6:7]
	v_lshl_add_u64 v[6:7], v[6:7], 0, v[166:167]
	v_add_co_u32_e32 v8, vcc, s33, v6
	v_mov_b32_e32 v232, 0
	s_nop 0
	v_addc_co_u32_e32 v9, vcc, 0, v7, vcc
	global_load_dwordx4 v[30:33], v[6:7], off nt
	global_load_dwordx4 v[66:69], v[8:9], off nt
	v_lshlrev_b32_e32 v6, v224, v201
	v_sub_u32_e32 v6, v169, v6
	v_ashrrev_i32_e32 v7, 31, v6
	v_sub_u32_e32 v8, v6, v225
	v_cmp_lt_i32_e32 vcc, v6, v225
	v_lshlrev_b64 v[178:179], 10, v[170:171]
	v_mov_b32_e32 v162, 0xff800000
	v_cndmask_b32_e32 v7, 0, v7, vcc
	v_cndmask_b32_e32 v6, v8, v6, vcc
	v_cndmask_b32_e32 v9, v177, v175, vcc
	v_cndmask_b32_e32 v8, v176, v174, vcc
	v_lshlrev_b64 v[6:7], 13, v[6:7]
	v_lshl_add_u64 v[6:7], v[8:9], 0, v[6:7]
	v_lshl_add_u64 v[6:7], v[6:7], 0, v[166:167]
	v_add_co_u32_e32 v8, vcc, s33, v6
	s_movk_i32 s4, 0xffe0
	s_nop 0
	v_addc_co_u32_e32 v9, vcc, 0, v7, vcc
	global_load_dwordx4 v[26:29], v[6:7], off nt
	global_load_dwordx4 v[70:73], v[8:9], off nt
	v_lshlrev_b32_e32 v6, v224, v204
	v_sub_u32_e32 v6, v169, v6
	v_ashrrev_i32_e32 v7, 31, v6
	v_sub_u32_e32 v8, v6, v225
	v_cmp_lt_i32_e32 vcc, v6, v225
	v_mov_b32_e32 v186, 0
	v_mov_b32_e32 v187, v232
	v_cndmask_b32_e32 v7, 0, v7, vcc
	v_cndmask_b32_e32 v6, v8, v6, vcc
	v_cndmask_b32_e32 v9, v177, v175, vcc
	v_cndmask_b32_e32 v8, v176, v174, vcc
	v_lshlrev_b64 v[6:7], 13, v[6:7]
	v_lshl_add_u64 v[6:7], v[8:9], 0, v[6:7]
	v_lshl_add_u64 v[6:7], v[6:7], 0, v[166:167]
	v_add_co_u32_e32 v8, vcc, s33, v6
	v_mov_b32_e32 v184, 0
	s_nop 0
	v_addc_co_u32_e32 v9, vcc, 0, v7, vcc
	global_load_dwordx4 v[22:25], v[6:7], off nt
	global_load_dwordx4 v[74:77], v[8:9], off nt
	v_lshlrev_b32_e32 v6, v224, v205
	v_sub_u32_e32 v6, v169, v6
	v_ashrrev_i32_e32 v7, 31, v6
	v_sub_u32_e32 v8, v6, v225
	v_cmp_lt_i32_e32 vcc, v6, v225
	v_mov_b32_e32 v185, v232
	s_waitcnt vmcnt(0)
; __device__ __forceinline__ float alibi_slope2(int g, int h) { return exp2f(-8.f * (float)(g * 16 + h + 1) / 48.f) * LOG2E; }
; __device__ __forceinline__ void attn_sample(Frame& F, int i_lo, int i_hi) {
;     ...
;         const float sl2 = alibi_slope2(grp, h) * (float)dil;
;         float mx = -INFINITY, lsum = 0.f; f32x4 o = (f32x4){0.f, 0.f, 0.f, 0.f};
	v_and_b32_e32 v180, 0xffff0000, v34
	v_cndmask_b32_e32 v7, 0, v7, vcc
	v_cndmask_b32_e32 v6, v8, v6, vcc
	v_cndmask_b32_e32 v9, v177, v175, vcc
	v_cndmask_b32_e32 v8, v176, v174, vcc
	v_lshlrev_b64 v[6:7], 13, v[6:7]
	v_lshl_add_u64 v[6:7], v[8:9], 0, v[6:7]
	v_lshl_add_u64 v[6:7], v[6:7], 0, v[166:167]
	v_add_co_u32_e32 v8, vcc, s33, v6
	v_lshlrev_b32_e32 v182, 16, v34
	s_nop 0
	v_addc_co_u32_e32 v9, vcc, 0, v7, vcc
	global_load_dwordx4 v[18:21], v[6:7], off nt
	global_load_dwordx4 v[78:81], v[8:9], off nt
	v_lshlrev_b32_e32 v6, v224, v206
	v_sub_u32_e32 v6, v169, v6
	v_ashrrev_i32_e32 v7, 31, v6
	v_sub_u32_e32 v8, v6, v225
	v_cmp_lt_i32_e32 vcc, v6, v225
	v_lshlrev_b32_e32 v181, 16, v35
	v_and_b32_e32 v183, 0xffff0000, v35
	v_cndmask_b32_e32 v7, 0, v7, vcc
	v_cndmask_b32_e32 v6, v8, v6, vcc
	v_cndmask_b32_e32 v9, v177, v175, vcc
	v_cndmask_b32_e32 v8, v176, v174, vcc
	v_lshlrev_b64 v[6:7], 13, v[6:7]
	v_lshl_add_u64 v[6:7], v[8:9], 0, v[6:7]
	v_lshl_add_u64 v[6:7], v[6:7], 0, v[166:167]
	v_add_co_u32_e32 v8, vcc, s33, v6
	v_mov_b32_e32 v190, v95
	s_nop 0
	v_addc_co_u32_e32 v9, vcc, 0, v7, vcc
	global_load_dwordx4 v[14:17], v[6:7], off nt
	global_load_dwordx4 v[82:85], v[8:9], off nt
	v_lshlrev_b32_e32 v6, v224, v207
	v_sub_u32_e32 v6, v169, v6
	v_ashrrev_i32_e32 v7, 31, v6
	v_sub_u32_e32 v8, v6, v225
	v_cmp_lt_i32_e32 vcc, v6, v225
	v_mov_b32_e32 v191, v96
	v_mov_b32_e32 v95, v97
	v_cndmask_b32_e32 v7, 0, v7, vcc
	v_cndmask_b32_e32 v6, v8, v6, vcc
	v_cndmask_b32_e32 v9, v177, v175, vcc
	v_cndmask_b32_e32 v8, v176, v174, vcc
	v_lshlrev_b64 v[6:7], 13, v[6:7]
	v_lshl_add_u64 v[6:7], v[8:9], 0, v[6:7]
	v_lshl_add_u64 v[6:7], v[6:7], 0, v[166:167]
	v_add_co_u32_e32 v8, vcc, s33, v6
	v_mov_b32_e32 v188, v31
	s_nop 0
	v_addc_co_u32_e32 v9, vcc, 0, v7, vcc
	global_load_dwordx4 v[10:13], v[6:7], off nt
	global_load_dwordx4 v[86:89], v[8:9], off nt
	v_lshlrev_b32_e32 v6, v224, v208
	v_sub_u32_e32 v6, v169, v6
	v_ashrrev_i32_e32 v7, 31, v6
	v_sub_u32_e32 v8, v6, v225
	v_cmp_lt_i32_e32 vcc, v6, v225
	v_mov_b32_e32 v189, v32
	v_mov_b32_e32 v31, v33
	v_cndmask_b32_e32 v7, 0, v7, vcc
	v_cndmask_b32_e32 v6, v8, v6, vcc
	v_cndmask_b32_e32 v9, v177, v175, vcc
	v_cndmask_b32_e32 v8, v176, v174, vcc
	v_lshlrev_b64 v[6:7], 13, v[6:7]
	v_lshl_add_u64 v[6:7], v[8:9], 0, v[6:7]
	v_lshl_add_u64 v[36:37], v[6:7], 0, v[166:167]
	global_load_dwordx4 v[6:9], v[36:37], off nt
	v_add_co_u32_e32 v36, vcc, s33, v36
	v_mov_b32_e32 v32, v27
	s_nop 0
	v_addc_co_u32_e32 v37, vcc, 0, v37, vcc
	global_load_dwordx4 v[90:93], v[36:37], off nt
	v_lshl_add_u32 v36, v168, 4, v197
	v_cvt_f32_i32_e32 v36, v36
	v_lshlrev_b32_e64 v37, v224, 1
	v_mov_b32_e32 v33, v28
	v_mov_b32_e32 v27, v29
	v_mul_f32_e32 v36, 0xc1000000, v36
	v_div_scale_f32 v38, s[0:1], s26, s26, v36
	v_rcp_f32_e32 v39, v38
	v_mov_b32_e32 v28, v23
	v_mov_b32_e32 v29, v24
	v_mov_b32_e32 v23, v25
	v_fma_f32 v34, -v38, v39, 1.0
	v_fmac_f32_e32 v39, v34, v39
	v_div_scale_f32 v34, vcc, v36, s26, v36
	v_mul_f32_e32 v35, v34, v39
	v_fma_f32 v40, -v38, v35, v34
	v_fmac_f32_e32 v35, v40, v39
	v_fma_f32 v34, -v38, v35, v34
	v_div_fmas_f32 v34, v34, v39, v35
	v_div_fixup_f32 v34, v34, s26, v36
	v_cmp_gt_f32_e32 vcc, s27, v34
	s_waitcnt vmcnt(7)
	v_mov_b32_e32 v24, v19
	v_mov_b32_e32 v25, v20
	v_cndmask_b32_e32 v35, 0, v214, vcc
	v_add_f32_e32 v34, v34, v35
	v_exp_f32_e32 v34, v34
	v_cvt_f32_u32_e32 v35, v37
	v_cndmask_b32_e32 v36, 0, v215, vcc
	v_cmp_lt_i32_e32 vcc, v217, v218
	v_ldexp_f32 v34, v34, v36
	v_mul_f32_e32 v34, 0x3fb8aa3b, v34
	v_mul_f32_e32 v227, v34, v35
	v_cndmask_b32_e32 v34, v216, v217, vcc
	v_cmp_lt_i32_e32 vcc, v219, v218
	v_lshlrev_b32_e32 v228, 2, v34
	v_mov_b32_e32 v19, v21
	v_cndmask_b32_e32 v34, v216, v219, vcc
	v_cmp_lt_i32_e32 vcc, v220, v218
	v_lshlrev_b32_e32 v229, 2, v34
	s_waitcnt vmcnt(5)
	v_mov_b32_e32 v20, v15
	v_cndmask_b32_e32 v34, v216, v220, vcc
	v_cmp_lt_i32_e32 vcc, v221, v218
	v_lshlrev_b32_e32 v230, 2, v34
	v_mov_b32_e32 v21, v16
	v_cndmask_b32_e32 v34, v216, v221, vcc
	v_cmp_lt_i32_e32 vcc, v222, v218
	v_lshlrev_b32_e32 v231, 2, v34
	v_mov_b32_e32 v15, v17
	v_cndmask_b32_e32 v34, v216, v222, vcc
	v_lshlrev_b32_e32 v226, 2, v34
	s_waitcnt vmcnt(3)
	v_mov_b32_e32 v16, v11
	v_mov_b32_e32 v17, v12
	v_mov_b32_e32 v11, v13
	s_waitcnt vmcnt(1)
	v_mov_b32_e32 v12, v7
	v_mov_b32_e32 v13, v8
	v_mov_b32_e32 v7, v9

; #define LAS __attribute__((address_space(3)))
; #define WG_BAR() asm volatile("s_waitcnt lgkmcnt(0)\n\ts_barrier" ::: "memory")
; #define SEAM(k) do { if (PROBE_STRETCH == (k)) { const unsigned long long dt_ = __builtin_amdgcn_s_memrealtime() - tph; while (__builtin_amdgcn_s_memrealtime() - tph < 5ull * dt_) __builtin_amdgcn_s_sleep(8); } \
;     if (IN(k) && IN((k) + 1)) { xcd_barrier(bar); if (PROBE_DUP & (1u << 23)) xcd_barrier(bar); } tph = __builtin_amdgcn_s_memrealtime(); } while (0)
; __device__ __forceinline__ void attn_prompt(Frame& F) {
;     LAS unsigned char* L = F.lds; const int tid = F.tid, lane = F.lane, w = F.wave, r = lane & 15, g4 = lane >> 4;
;     __syncthreads();
;     for (int e = tid; e < 6 * AT_SLOT / 16; e += 512) *(LAS v4u*)(L + e * 16) = (v4u){0u, 0u, 0u, 0u};
;     WG_BAR();
;     const __amdgpu_buffer_rsrc_t wsr = __builtin_amdgcn_make_buffer_rsrc((void*)F.ws, (short)0, (int)WS_END, 0x00020000);
; __global__ void __launch_bounds__(512, 2) mega_fwd(Args args) {
;     ...
;     if (IN(9)) { attn_prompt(F); } SEAM(9);
.LBB0_1628:
	s_or_b64 exec, exec, s[0:1]
	s_waitcnt lgkmcnt(0)
	s_barrier
	s_cmpk_lt_i32 s2, 0x300
	s_cselect_b64 s[4:5], -1, 0
	s_cmpk_gt_i32 s2, 0x2ff
	s_cselect_b64 s[0:1], -1, 0
	s_and_b64 vcc, exec, s[4:5]
	v_writelane_b32 v245, s6, 29
	s_nop 1
	v_writelane_b32 v245, s7, 30
	s_cmpk_eq_u32 s44, 0x100
	s_cbranch_scc1 .Lp9n_entry
	s_cbranch_vccz .LBB0_1631
	s_ashr_i32 s3, s2, 8
	s_and_b32 s10, s2, 0xff
	s_cmp_gt_i32 s3, 1
	s_cbranch_scc0 .LBB0_1632
	s_lshl_b32 s9, s10, 2
	s_bfe_u32 s8, s2, 0x60002
	s_mov_b32 s7, -1
	s_cbranch_execz .LBB0_1633
	s_branch .LBB0_1634

; #define LAS __attribute__((address_space(3)))
; #define WG_BAR() asm volatile("s_waitcnt lgkmcnt(0)\n\ts_barrier" ::: "memory")
; #define ATT_ADV(ui, s) do { ++(s); if ((s) >= att_unit_steps(F.bid + (ui) * F.G)) { (s) = 0; ++(ui); } } while (0)
; __device__ __forceinline__ void attn_prompt(Frame& F) {
;     LAS unsigned char* L = F.lds; const int tid = F.tid, lane = F.lane, w = F.wave, r = lane & 15, g4 = lane >> 4;
;     __syncthreads();
;     for (int e = tid; e < 6 * AT_SLOT / 16; e += 512) *(LAS v4u*)(L + e * 16) = (v4u){0u, 0u, 0u, 0u};
;     WG_BAR();
;     const __amdgpu_buffer_rsrc_t wsr = __builtin_amdgcn_make_buffer_rsrc((void*)F.ws, (short)0, (int)WS_END, 0x00020000);
;     v4u kA[2], vA[2], kB[2], vB[2]; bf16x8 qA[2], qB[2];
; #pragma unroll
;     for (int i = 0; i < 2; ++i) { kA[i] = vA[i] = kB[i] = vB[i] = (v4u){0u, 0u, 0u, 0u}; qA[i] = qB[i] = (bf16x8){0, 0, 0, 0, 0, 0, 0, 0}; }
;     int cui = 0, cs = 0, pui = 0, ps = 0, nstep = 0; bool running = true;
;     ATT_LOAD(pui, ps, kA, vA, qA); ATT_ADV(pui, ps);
;     ATT_LOAD(pui, ps, kB, vB, qB); ATT_ADV(pui, ps);
.LBB0_1647:
	s_movk_i32 s0, 0x90
	v_readlane_b32 s4, v245, 0
	v_mul_lo_u32 v100, v2, s0
	v_lshrrev_b32_e32 v2, 3, v3
	s_cmpk_lt_u32 s4, 0x200
	v_mul_lo_u32 v101, v2, s0
	s_cselect_b64 s[20:21], -1, 0
	s_and_b32 s0, s4, 0xfffffe00
	s_cmpk_eq_i32 s0, 0x200
	s_cselect_b64 s[0:1], -1, 0
	v_writelane_b32 v245, s0, 13
	s_and_b32 s3, s33, 0x70
	v_or_b32_e32 v3, s3, v94
	v_writelane_b32 v245, s1, 14
	v_mul_u32_u24_e32 v3, 0x90, v3
	v_readlane_b32 s5, v245, 8
	s_add_i32 s0, s5, 1
	s_lshl_b32 s1, s0, 4
	s_cmpk_lt_u32 s4, 0x1c0
	s_cselect_b64 s[24:25], -1, 0
	s_and_b32 s0, s0, 0x7fffff8
	s_cmp_eq_u32 s0, 8
	s_cselect_b64 s[6:7], -1, 0
	s_and_b32 s0, s1, 0x70
	v_add3_u32 v104, 0, v3, v98
	v_or_b32_e32 v3, s0, v94
	s_add_i32 s0, s5, 2
	s_lshl_b32 s1, s0, 4
	s_cmpk_lt_u32 s4, 0x180
	s_cselect_b64 s[36:37], -1, 0
	s_and_b32 s0, s0, 0x7fffff8
	v_writelane_b32 v245, s6, 27
	s_cmp_eq_u32 s0, 8
	v_mul_u32_u24_e32 v3, 0x90, v3
	v_writelane_b32 v245, s7, 28
	s_cselect_b64 s[6:7], -1, 0
	s_and_b32 s0, s1, 0x70
	v_add3_u32 v105, 0, v3, v98
	v_or_b32_e32 v3, s0, v94
	s_add_i32 s0, s5, 3
	s_lshl_b32 s1, s0, 4
	s_cmpk_lt_u32 s4, 0x140
	s_cselect_b64 s[40:41], -1, 0
	s_and_b32 s0, s0, 0x7fffff8
	v_writelane_b32 v245, s6, 19
	s_cmp_eq_u32 s0, 8
	v_mul_u32_u24_e32 v3, 0x90, v3
	v_writelane_b32 v245, s7, 20
	s_cselect_b64 s[6:7], -1, 0
	s_and_b32 s0, s1, 0x70
	v_add3_u32 v106, 0, v3, v98
	v_or_b32_e32 v3, s0, v94
	s_add_i32 s0, s5, 4
	s_lshl_b32 s1, s0, 4
	s_cmpk_lt_u32 s4, 0x100
	s_cselect_b64 s[54:55], -1, 0
	s_and_b32 s0, s0, 0x7fffff8
	v_writelane_b32 v245, s6, 15
	s_cmp_eq_u32 s0, 8
	v_mul_u32_u24_e32 v3, 0x90, v3
	v_writelane_b32 v245, s7, 16
	s_cselect_b64 s[6:7], -1, 0
	s_and_b32 s0, s1, 0x70
	v_add3_u32 v107, 0, v3, v98
	v_or_b32_e32 v3, s0, v94
	s_add_i32 s0, s5, 5
	s_lshl_b32 s1, s0, 4
	s_cmpk_lt_u32 s4, 0xc0
	s_cselect_b64 s[58:59], -1, 0
	s_and_b32 s0, s0, 0x7fffff8
	v_writelane_b32 v245, s6, 17
	s_cmp_eq_u32 s0, 8
	v_mul_u32_u24_e32 v3, 0x90, v3
	v_writelane_b32 v245, s7, 18
	s_cselect_b64 s[6:7], -1, 0
	s_and_b32 s0, s1, 0x70
	v_add3_u32 v108, 0, v3, v98
	v_or_b32_e32 v3, s0, v94
	s_add_i32 s0, s5, 6
	s_lshl_b32 s1, s0, 4
	s_cmpk_lt_u32 s4, 0x80
	s_cselect_b64 s[62:63], -1, 0
	s_and_b32 s0, s0, 0x7fffff8
	s_cmp_eq_u32 s0, 8
	v_mul_u32_u24_e32 v3, 0x90, v3
	s_cselect_b64 s[64:65], -1, 0
	s_and_b32 s0, s1, 0x70
	v_add3_u32 v109, 0, v3, v98
	v_or_b32_e32 v3, s0, v94
	s_add_i32 s0, s5, 7
	s_lshl_b32 s1, s0, 4
	s_cmp_lt_u32 s4, 64
	s_cselect_b64 s[66:67], -1, 0
	s_and_b32 s0, s0, 0x7fffff8
	s_cmp_eq_u32 s0, 8
	v_mul_u32_u24_e32 v3, 0x90, v3
	s_cselect_b64 s[68:69], -1, 0
	s_and_b32 s0, s1, 0x70
	v_add3_u32 v110, 0, v3, v98
	v_or_b32_e32 v3, s0, v94
	s_add_i32 s0, s5, 8
	s_lshl_b32 s1, s0, 4
	s_and_b32 s0, s0, 0x7fffff8
	s_cmp_eq_u32 s0, 8
	v_mul_u32_u24_e32 v3, 0x90, v3
	s_cselect_b64 s[70:71], -1, 0
	s_and_b32 s0, s1, 0x70
	v_add3_u32 v111, 0, v3, v98
	v_or_b32_e32 v3, s0, v94
	v_lshrrev_b32_e32 v2, 2, v160
	v_mul_u32_u24_e32 v3, 0x90, v3
	v_and_b32_e32 v102, 12, v2
	v_writelane_b32 v245, s6, 23
	v_add3_u32 v112, 0, v3, v98
	v_or_b32_e32 v3, 0x80, v94
	v_writelane_b32 v245, s7, 24
	s_movk_i32 s6, 0x80
	v_sub_u32_e32 v4, v3, v102
	s_movk_i32 s4, 0x81
	v_cmp_gt_u32_e64 s[0:1], s6, v4
	v_cmp_gt_u32_e64 s[6:7], s4, v4
	s_movk_i32 s4, 0x82
	v_cmp_gt_u32_e64 s[8:9], s4, v4
	s_movk_i32 s4, 0x83
	v_cmp_gt_u32_e64 s[10:11], s4, v4
	s_add_i32 s4, s33, 16
	v_or_b32_e32 v5, s3, v2
	s_and_b32 s3, s4, 0x7fffff80
	v_lshlrev_b32_e32 v4, 3, v160
	s_cmpk_eq_i32 s3, 0x80
	v_and_b32_e32 v4, 24, v4
	v_mul_u32_u24_e32 v5, 0x90, v5
	s_cselect_b64 s[72:73], -1, 0
	s_and_b32 s3, s4, 0x70
	v_add3_u32 v113, 0, v5, v4
	v_or_b32_e32 v5, s3, v2
	s_add_i32 s3, s33, 32
	s_add_i32 s4, s33, 48
	s_and_b32 s5, s3, 0x7fffff80
	s_cmpk_eq_i32 s5, 0x80
	v_mul_u32_u24_e32 v5, 0x90, v5
	s_cselect_b64 s[74:75], -1, 0
	s_and_b32 s3, s3, 0x70
	v_add3_u32 v114, 0, v5, v4
	v_or_b32_e32 v5, s3, v2
	s_and_b32 s3, s4, 0x7fffff80
	s_cmpk_eq_i32 s3, 0x80
	v_mul_u32_u24_e32 v5, 0x90, v5
	s_cselect_b64 s[76:77], -1, 0
	s_and_b32 s3, s4, 0x70
	v_add3_u32 v115, 0, v5, v4
	v_or_b32_e32 v5, s3, v2
	s_add_i32 s3, s33, 64
	s_add_i32 s4, s33, 0x50
	s_and_b32 s5, s3, 0x7fffff80
	s_cmpk_eq_i32 s5, 0x80
	v_mul_u32_u24_e32 v5, 0x90, v5
	s_cselect_b64 s[78:79], -1, 0
	s_and_b32 s3, s3, 0x70
	v_add3_u32 v116, 0, v5, v4
	v_or_b32_e32 v5, s3, v2
	s_and_b32 s3, s4, 0x7fffff80
	s_cmpk_eq_i32 s3, 0x80
	v_mul_u32_u24_e32 v5, 0x90, v5
	s_cselect_b64 s[80:81], -1, 0
	s_and_b32 s3, s4, 0x70
	v_add3_u32 v117, 0, v5, v4
	v_or_b32_e32 v5, s3, v2
	s_add_i32 s3, s33, 0x60
	s_add_i32 s4, s33, 0x70
	s_and_b32 s5, s3, 0x7fffff80
	s_cmpk_eq_i32 s5, 0x80
	v_mul_u32_u24_e32 v5, 0x90, v5
	s_cselect_b64 s[82:83], -1, 0
	s_and_b32 s3, s3, 0x70
	v_add3_u32 v118, 0, v5, v4
	v_or_b32_e32 v5, s3, v2
	s_and_b32 s3, s4, 0x7fffff80
	s_cmpk_eq_i32 s3, 0x80
	v_mul_u32_u24_e32 v5, 0x90, v5
	s_cselect_b64 s[84:85], -1, 0
	s_and_b32 s3, s4, 0x70
	v_add3_u32 v119, 0, v5, v4
	v_or_b32_e32 v5, s3, v2
	s_add_i32 s3, s33, 0x90
	s_and_b32 s4, s3, 0x7fffff80
	s_cmpk_eq_i32 s4, 0x80
	s_cselect_b64 s[86:87], -1, 0
	s_and_b32 s3, s3, 0x70
	v_or_b32_e32 v2, s3, v2
	v_mul_u32_u24_e32 v2, 0x90, v2
	v_mul_u32_u24_e32 v5, 0x90, v5
	v_add3_u32 v121, 0, v2, v4
	v_mbcnt_lo_u32_b32 v2, -1, 0
	s_mov_b32 s93, 3
	s_mov_b32 s92, 2
	v_cvt_f32_ubyte0_e32 v103, v102
	s_mov_b32 s22, 0
	s_mov_b32 s56, 1
	v_add3_u32 v120, 0, v5, v4
	v_lshlrev_b32_e32 v122, 1, v102
	v_cmp_gt_u32_e64 s[12:13], 16, v160
	v_cvt_f32_ubyte0_e32 v123, v3
	v_add_u32_e32 v124, 0, v95
	v_add_u32_e32 v125, 0x12000, v101
	v_add_u32_e32 v126, 0x4800, v101
	v_add_u32_e32 v127, 0x12000, v100
	v_add_u32_e32 v128, 0x4800, v100
	v_mov_b32_e32 v60, 0
	s_mov_b32 s95, 0x42400000
	v_mov_b32_e32 v129, 0x42800000
	v_mov_b32_e32 v130, 0xff800000
	v_mbcnt_hi_u32_b32 v131, -1, v2
	v_mov_b32_e32 v132, 0
	s_mov_b32 s27, 0
	s_mov_b32 s23, 0
	s_mov_b32 s26, 2
	s_mov_b32 s47, 0
	s_waitcnt vmcnt(0)
; #define LAS __attribute__((address_space(3)))
; #define MFMA16(a, b, c) __builtin_amdgcn_mfma_f32_16x16x32_bf16((a), (b), (c), 0, 0, 0)
; __device__ __forceinline__ float alibi_slope2(int g, int h) { return exp2f(-8.f * (float)(g * 16 + h + 1) / 48.f) * LOG2E; }
; __device__ __forceinline__ void attn_tile(Frame& F, const __amdgpu_buffer_rsrc_t wsr, LAS unsigned char* L, int grp, int h, int seq, int blk, const bf16x8 (&qf)[2], int sl_prev, int sl_cur, int sl_next) {
;     const int lane = F.lane, w = F.wave, r = lane & 15, g4 = lane >> 4;
;     const int dsh = 2 * grp, q0 = blk * 128, qw0 = q0 + 16 * w;
;     ...
;     const float sl2 = alibi_slope2(grp, h) * (float)(1 << dsh);
;     const float b4 = sl2 * (float)(4 * g4);
;     f32x4 st[10];
; #pragma unroll
;     for (int Tg = 0; Tg < 3; ++Tg) {
;         bf16x8 kf[3][2];
; #pragma unroll
;         for (int i = 0; i < 3; ++i) { const int rb = 16 * w + 16 * (3 * Tg + i); const LAS unsigned char* kb = L + AT_K + SLOT3(rb >> 7) * AT_SLOT;
; #pragma unroll
;             for (int ks = 0; ks < 2; ++ks) kf[i][ks] = ldfrag(kb, (rb & 127) + r, P144, ks, g4); }
; #pragma unroll
;         for (int i = 0; i < 3; ++i) st[3 * Tg + i] = MFMA16(kf[i][0], qf[0], ((f32x4){b4, b4, b4, b4}));
; #pragma unroll
;         for (int i = 0; i < 3; ++i) st[3 * Tg + i] = MFMA16(kf[i][1], qf[1], st[3 * Tg + i]);
;     }
;     const int lo_ = max(r, 128 - qw0) - 4 * g4, hi_ = r + 128 - 4 * g4;
;     float mx = -INFINITY;
; #pragma unroll
;     for (int T = 0; T < 9; ++T)
; #pragma unroll
;         for (int e = 0; e < 4; ++e) { float y = __builtin_fmaf(sl2, (float)(16 * T + e), st[T][e]);
;             if ((16 * T + e) < lo_) y = -INFINITY;
;             if (T == 8) { if ((16 * T + e) > hi_) y = -INFINITY; }
;             st[T][e] = y; mx = fmaxf(mx, y); }
;     mx = fmaxf(mx, __shfl_xor(mx, 16)); mx = fmaxf(mx, __shfl_xor(mx, 32));
;     float lsum = 0.f;
; #pragma unroll
;     for (int T = 0; T < 9; ++T)
; #pragma unroll
;         for (int e = 0; e < 4; ++e) { const float p = __builtin_amdgcn_exp2f(st[T][e] - mx); st[T][e] = p; lsum += p; }
;     st[9] = (f32x4){0.f, 0.f, 0.f, 0.f};
;     lsum += __shfl_xor(lsum, 16); lsum += __shfl_xor(lsum, 32);
;     mx -= sl2 * (float)(r + 128);
	v_mov_b64_e32 v[2:3], v[18:19]
	v_mov_b64_e32 v[4:5], v[20:21]
	v_mov_b64_e32 v[6:7], v[22:23]
	v_mov_b64_e32 v[8:9], v[24:25]
	v_mov_b64_e32 v[246:247], v[10:11]
	v_mov_b64_e32 v[248:249], v[12:13]
	v_mov_b64_e32 v[250:251], v[14:15]
	v_mov_b64_e32 v[252:253], v[16:17]
	s_mov_b32 s98, 0
	v_and_b32_e32 v185, 15, v160
	v_lshrrev_b32_e32 v186, 4, v160
	v_lshlrev_b32_e32 v186, 2, v186
	v_mov_b32_e32 v191, 0xff800000
	v_mul_u32_u24_e32 v170, 0x90, v185
	v_lshl_add_u32 v170, v186, 2, v170
	v_lshrrev_b32_e32 v171, 2, v185
	v_add_u32_e32 v171, v171, v186
	v_mul_u32_u24_e32 v171, 0x90, v171
	v_and_b32_e32 v172, 3, v185
	v_lshl_add_u32 v171, v172, 3, v171
	v_cvt_f32_u32_e32 v172, v186
	v_add_f32_e32 v173, 1.0, v172
	v_add_f32_e32 v174, 2.0, v172
	v_add_f32_e32 v175, 1.0, v174
	v_add_u32_e32 v184, 0, v186
	v_cmp_lt_u32_e32 vcc, v184, v185
	s_nop 1
	v_cndmask_b32_e32 v176, 0, v191, vcc
	v_cmp_gt_u32_e32 vcc, v184, v185
	s_nop 1
	v_cndmask_b32_e32 v180, 0, v191, vcc
	v_add_u32_e32 v184, 1, v186
	v_cmp_lt_u32_e32 vcc, v184, v185
	s_nop 1
	v_cndmask_b32_e32 v177, 0, v191, vcc
	v_cmp_gt_u32_e32 vcc, v184, v185
	s_nop 1
	v_cndmask_b32_e32 v181, 0, v191, vcc
	v_add_u32_e32 v184, 2, v186
	v_cmp_lt_u32_e32 vcc, v184, v185
	s_nop 1
	v_cndmask_b32_e32 v178, 0, v191, vcc
	v_cmp_gt_u32_e32 vcc, v184, v185
	s_nop 1
	v_cndmask_b32_e32 v182, 0, v191, vcc
	v_add_u32_e32 v184, 3, v186
	v_cmp_lt_u32_e32 vcc, v184, v185
	s_nop 1
	v_cndmask_b32_e32 v179, 0, v191, vcc
	v_cmp_gt_u32_e32 vcc, v184, v185
	s_nop 1
	v_cndmask_b32_e32 v183, 0, v191, vcc
	v_add_u32_e32 v184, 0x80, v185
	v_cvt_f32_u32_e32 v184, v184
	v_subrev_u32_e32 v187, 24, v160
	v_min_u32_e32 v187, v160, v187
	v_mul_u32_u24_e32 v187, 0x900, v187
	v_lshlrev_b32_e32 v188, 1, v186
	v_xor_b32_e32 v189, 16, v160
	v_lshlrev_b32_e32 v189, 2, v189
	v_xor_b32_e32 v190, 32, v160
	v_lshlrev_b32_e32 v190, 2, v190
	s_branch .LBB0_1651

; __device__ __forceinline__ void attn_prompt(Frame& F) {
;     ...
;     while (running) {
;         ATT_STEP(kA, vA, qA);
;         if (!running) break;
;         ATT_STEP(kB, vB, qB);
;     }
.LBB0_1649:
	s_mov_b32 s57, s46
	s_mov_b32 s15, s60
	s_mov_b32 s61, s14
.LBB0_1650:
	s_and_b64 vcc, exec, s[4:5]
	s_mov_b32 s92, s34
	s_mov_b32 s56, s94
	s_mov_b32 s93, s49
	s_mov_b32 s22, s48
	s_mov_b32 s27, s43
	s_mov_b32 s23, s39
	s_mov_b32 s26, s16
	s_mov_b32 s47, s42
	s_mov_b32 s14, s61
	s_mov_b32 s60, s15
	s_mov_b32 s46, s57
	s_cbranch_vccnz .LBB0_1690

.LBB0_1657:
	s_mov_b64 s[4:5], -1
	v_readfirstlane_b32 s57, v0
	v_readfirstlane_b32 s15, v0
	v_readfirstlane_b32 s61, v0
	v_readfirstlane_b32 s42, v0
	v_readfirstlane_b32 s16, v0
	v_readfirstlane_b32 s39, v0
	v_readfirstlane_b32 s43, v0
	v_readfirstlane_b32 s48, v0
	v_readfirstlane_b32 s49, v0
	v_readfirstlane_b32 s94, v0
	s_andn2_b64 vcc, exec, s[34:35]
	v_readfirstlane_b32 s34, v0
	s_cbranch_vccnz .LBB0_1650
	s_bfe_u32 s99, s98, 0x10001
	s_bfe_u32 s100, s98, 0x10002
	s_bfe_u32 s101, s98, 0x10003
	s_add_u32 s99, s99, s101
	s_mul_i32 s99, s99, 5
	s_mul_i32 s100, s100, 6
	s_add_u32 s99, s99, s100
	s_cmp_eq_u32 s99, 16
	s_cbranch_scc1 .Lat_a16
	s_cmp_eq_u32 s99, 11
	s_cbranch_scc1 .Lat_a11
	s_cmp_eq_u32 s99, 10
	s_cbranch_scc1 .Lat_a10
	s_cmp_eq_u32 s99, 6
	s_cbranch_scc1 .Lat_a6
	s_cmp_eq_u32 s99, 5
	s_cbranch_scc1 .Lat_a5
	s_waitcnt vmcnt(0)
	s_branch .Lat_adone
.Lat_a16:
	s_waitcnt vmcnt(16)
	s_branch .Lat_adone
.Lat_a11:
	s_waitcnt vmcnt(11)
	s_branch .Lat_adone
.Lat_a10:
	s_waitcnt vmcnt(10)
	s_branch .Lat_adone
.Lat_a6:
	s_waitcnt vmcnt(6)
	s_branch .Lat_adone
.Lat_a5:
	s_waitcnt vmcnt(5)
.Lat_adone:
	s_andn2_b32 s98, s98, 3
	v_mov_b64_e32 v[18:19], v[2:3]
	v_mov_b64_e32 v[20:21], v[4:5]
	v_mov_b64_e32 v[22:23], v[6:7]
	v_mov_b64_e32 v[24:25], v[8:9]
	s_mul_hi_u32 s4, s47, 0xaaaaaaab
	s_lshr_b32 s43, s4, 1
	s_mul_i32 s4, s43, 0xd800
	s_cmp_gt_i32 s97, -1
	v_subrev_u32_e32 v6, s4, v100
	s_cselect_b64 vcc, -1, 0
	v_add_u32_e32 v90, v124, v132
	v_cndmask_b32_e32 v5, 0, v33, vcc
	v_cndmask_b32_e32 v4, 0, v32, vcc
	v_cndmask_b32_e32 v3, 0, v31, vcc
	v_cndmask_b32_e32 v2, 0, v30, vcc
	v_add_u32_e32 v6, v90, v6
	v_subrev_u32_e32 v7, s4, v101
	ds_write_b128 v6, v[2:5]
	v_cndmask_b32_e32 v5, 0, v29, vcc
	v_cndmask_b32_e32 v4, 0, v28, vcc
	v_cndmask_b32_e32 v3, 0, v27, vcc
	v_cndmask_b32_e32 v2, 0, v26, vcc
	ds_write_b128 v6, v[2:5] offset:55296
	v_cndmask_b32_e32 v5, 0, v41, vcc
	v_cndmask_b32_e32 v4, 0, v40, vcc
	v_cndmask_b32_e32 v3, 0, v39, vcc
	v_cndmask_b32_e32 v2, 0, v38, vcc
	v_add_u32_e32 v6, v90, v7
	ds_write_b128 v6, v[2:5]
	v_cndmask_b32_e32 v5, 0, v37, vcc
	v_cndmask_b32_e32 v4, 0, v36, vcc
	v_cndmask_b32_e32 v3, 0, v35, vcc
	v_cndmask_b32_e32 v2, 0, v34, vcc
	ds_write_b128 v6, v[2:5] offset:55296
	s_mul_i32 s39, s23, s44
	s_add_i32 s39, s39, s2
	s_waitcnt lgkmcnt(0)
	s_barrier
	s_cmpk_lt_i32 s39, 0x300
	s_cselect_b64 s[4:5], -1, 0
	s_cmpk_gt_i32 s39, 0x2ff
	s_cbranch_scc1 .LBB0_1664
	s_ashr_i32 s46, s39, 8
	s_and_b32 s15, s39, 0xff
	s_cmp_gt_i32 s46, 1
	s_mov_b64 s[34:35], -1
	s_cbranch_scc0 .LBB0_1661
	s_mul_hi_i32 s34, s26, 0x55555556
	s_lshr_b32 s35, s34, 31
	s_lshl_b32 s16, s15, 2
	s_add_i32 s34, s34, s35
	s_add_i32 s16, s16, s34
	s_mul_i32 s34, s34, 3
	s_not_b32 s34, s34
	s_ashr_i32 s42, s16, 4
	s_add_i32 s48, s34, s26
	s_mov_b64 s[34:35], 0

; #define LAS __attribute__((address_space(3)))
; #define MFMA16(a, b, c) __builtin_amdgcn_mfma_f32_16x16x32_bf16((a), (b), (c), 0, 0, 0)
; __device__ __forceinline__ float alibi_slope2(int g, int h) { return exp2f(-8.f * (float)(g * 16 + h + 1) / 48.f) * LOG2E; }
; __device__ __forceinline__ void attn_tile(Frame& F, const __amdgpu_buffer_rsrc_t wsr, LAS unsigned char* L, int grp, int h, int seq, int blk, const bf16x8 (&qf)[2], int sl_prev, int sl_cur, int sl_next) {
;     const int lane = F.lane, w = F.wave, r = lane & 15, g4 = lane >> 4;
;     const int dsh = 2 * grp, q0 = blk * 128, qw0 = q0 + 16 * w;
;     ...
;     const float sl2 = alibi_slope2(grp, h) * (float)(1 << dsh);
;     const float b4 = sl2 * (float)(4 * g4);
;     f32x4 st[10];
; #pragma unroll
;     for (int Tg = 0; Tg < 3; ++Tg) {
;         bf16x8 kf[3][2];
; #pragma unroll
;         for (int i = 0; i < 3; ++i) { const int rb = 16 * w + 16 * (3 * Tg + i); const LAS unsigned char* kb = L + AT_K + SLOT3(rb >> 7) * AT_SLOT;
; #pragma unroll
;             for (int ks = 0; ks < 2; ++ks) kf[i][ks] = ldfrag(kb, (rb & 127) + r, P144, ks, g4); }
; #pragma unroll
;         for (int i = 0; i < 3; ++i) st[3 * Tg + i] = MFMA16(kf[i][0], qf[0], ((f32x4){b4, b4, b4, b4}));
; #pragma unroll
;         for (int i = 0; i < 3; ++i) st[3 * Tg + i] = MFMA16(kf[i][1], qf[1], st[3 * Tg + i]);
;     }
;     const int lo_ = max(r, 128 - qw0) - 4 * g4, hi_ = r + 128 - 4 * g4;
;     float mx = -INFINITY;
; #pragma unroll
;     for (int T = 0; T < 9; ++T)
; #pragma unroll
;         for (int e = 0; e < 4; ++e) { float y = __builtin_fmaf(sl2, (float)(16 * T + e), st[T][e]);
;             if ((16 * T + e) < lo_) y = -INFINITY;
;             if (T == 8) { if ((16 * T + e) > hi_) y = -INFINITY; }
;             st[T][e] = y; mx = fmaxf(mx, y); }
.LBB0_1664:
	v_cmp_lt_i32_e32 vcc, -1, v136
	s_and_b64 s[4:5], s[4:5], vcc
	v_mov_b64_e32 v[2:3], v[18:19]
	s_andn2_b64 vcc, exec, s[4:5]
	v_mov_b64_e32 v[4:5], v[20:21]
	v_mov_b64_e32 v[6:7], v[22:23]
	v_mov_b64_e32 v[8:9], v[24:25]
	s_cbranch_vccnz .LBB0_1666
	s_lshl_b32 s4, s46, 1
	s_lshr_b32 s4, 0x1000, s4
	v_mul_lo_u32 v2, v137, s4
	v_lshlrev_b32_e32 v3, 7, v136
	v_add_u32_e32 v2, v3, v2
	v_lshlrev_b32_e32 v3, 7, v138
	s_mul_i32 s4, s46, 0x2100000
	v_or_b32_e32 v4, v3, v95
	v_add_u32_e32 v5, v2, v99
	s_add_i32 s5, s4, 0x16a00000
	v_lshl_add_u32 v5, v5, 11, v4
	s_mov_b32 s16, s30
	s_add_i32 s15, s4, 0x1cd00000
	buffer_load_dwordx4 v[30:33], v5, s[16:19], s5 offen
	buffer_load_dwordx4 v[26:29], v5, s[16:19], s15 offen
	v_add_u32_e32 v5, v2, v96
	v_add_lshl_u32 v2, v2, v97, 11
	v_lshl_add_u32 v4, v5, 11, v4
	s_add_i32 s4, s4, 0x10700000
	v_add3_u32 v6, v3, v98, v2
	buffer_load_dwordx4 v[38:41], v4, s[16:19], s5 offen
	buffer_load_dwordx4 v[34:37], v4, s[16:19], s15 offen
	s_nop 0
	buffer_load_dwordx4 v[2:5], v6, s[16:19], s4 offen
	s_nop 0
	buffer_load_dwordx4 v[6:9], v6, s[16:19], s4 offen offset:64
	s_bitset1_b32 s98, 0
.LBB0_1666:
	s_mul_hi_u32 s4, s56, 0xaaaaaaab
	s_lshr_b32 s42, s4, 1
	s_mul_i32 s4, s42, 3
	s_sub_i32 s48, s56, s4
	s_mul_hi_u32 s4, s92, 0xaaaaaaab
	s_lshr_b32 s4, s4, 1
	s_mul_i32 s4, s4, 3
	s_andn2_b64 vcc, exec, s[90:91]
	s_sub_i32 s49, s92, s4
	s_cbranch_vccnz .LBB0_1670
	s_lshl_b32 s4, s49, 3
	s_lshr_b32 s5, s33, 4
	s_add_i32 s4, s4, s5
	s_lshl_b32 s99, s4, 11
	s_or_b32 s99, s99, s96
	s_lshl_b32 s4, s45, 2
	s_or_b32 s99, s99, s4
	s_lshl_b32 s4, s97, 6
	s_or_b32 s99, s99, s4
	s_lshl_b32 s4, s3, 17
	s_or_b32 s99, s99, s4
	.p2align 6
.Lat_tile:
	s_bfe_u32 s34, s99, 0x5000b
	s_add_i32 s5, s34, 1
	s_add_i32 s15, s34, 2
	v_readlane_b32 s4, v187, s34
	v_readlane_b32 s5, v187, s5
	v_readlane_b32 s15, v187, s15
	v_add_u32_e32 v142, s4, v170
	v_add_u32_e32 v232, s4, v171
	v_add_u32_e32 v143, s5, v170
	v_add_u32_e32 v233, s5, v171
	v_add_u32_e32 v144, s15, v170
	v_add_u32_e32 v234, s15, v171
	ds_read_b128 v[62:65], v142
	ds_read_b128 v[66:69], v142 offset:64
	ds_read_b128 v[70:73], v143
	ds_read_b128 v[74:77], v143 offset:64
	ds_read_b128 v[78:81], v144
	ds_read_b128 v[82:85], v144 offset:64
	s_add_i32 s4, s34, 3
	s_add_i32 s5, s34, 4
	s_add_i32 s15, s34, 5
	v_readlane_b32 s4, v187, s4
	v_readlane_b32 s5, v187, s5
	v_readlane_b32 s15, v187, s15
	v_add_u32_e32 v145, s4, v170
	v_add_u32_e32 v235, s4, v171
	v_add_u32_e32 v146, s5, v170
	v_add_u32_e32 v236, s5, v171
	v_add_u32_e32 v147, s15, v170
	v_add_u32_e32 v237, s15, v171
	s_add_i32 s4, s34, 6
	s_add_i32 s5, s34, 7
	s_add_i32 s15, s34, 8
	v_readlane_b32 s4, v187, s4
	v_readlane_b32 s5, v187, s5
	v_readlane_b32 s15, v187, s15
	v_add_u32_e32 v148, s4, v170
	v_add_u32_e32 v238, s4, v171
	v_add_u32_e32 v149, s5, v170
	v_add_u32_e32 v239, s5, v171
	v_add_u32_e32 v150, s15, v170
	v_add_u32_e32 v240, s15, v171
	s_add_i32 s4, s34, 9
	v_readlane_b32 s4, v187, s4
	s_nop 1
	v_add_u32_e32 v241, s4, v171
	s_bfe_u32 s4, s99, 0x20000
	s_bfe_u32 s5, s99, 0x40002
	s_lshl_b32 s15, s4, 4
	s_add_i32 s15, s15, s5
	s_add_i32 s15, s15, 1
	v_cvt_f32_i32_e32 v58, s15
	s_lshl_b32 s15, s4, 1
	s_lshl_b32 s15, 1, s15
	v_mul_f32_e32 v58, 0xc1000000, v58
	v_div_scale_f32 v59, s[34:35], s95, s95, v58
	v_rcp_f32_e32 v61, v59
	v_cvt_f32_u32_e32 v87, s15
	v_fma_f32 v93, -v59, v61, 1.0
	v_fmac_f32_e32 v61, v93, v61
	v_div_scale_f32 v93, vcc, v58, s95, v58
	v_mul_f32_e32 v86, v93, v61
	v_fma_f32 v89, -v59, v86, v93
	v_fmac_f32_e32 v86, v89, v61
	v_fma_f32 v59, -v59, v86, v93
	v_div_fmas_f32 v59, v59, v61, v86
	v_div_fixup_f32 v58, v59, s95, v58
	v_exp_f32_e32 v58, v58
	s_nop 0
	v_mul_f32_e32 v58, 0x3fb8aa3b, v58
	v_mul_f32_e32 v88, v58, v87
	v_mov_b32_e32 v91, v88
	v_pk_fma_f32 v[192:193], v[172:173], v[88:89], v[176:177] op_sel_hi:[1,0,1]
	v_pk_fma_f32 v[194:195], v[174:175], v[88:89], v[178:179] op_sel_hi:[1,0,1]
	v_mul_f32_e32 v86, 0x41800000, v91
	v_pk_fma_f32 v[196:197], v[172:173], v[88:89], v[86:87] op_sel_hi:[1,0,0]
	v_pk_fma_f32 v[198:199], v[174:175], v[88:89], v[86:87] op_sel_hi:[1,0,0]
	v_mul_f32_e32 v86, 0x42000000, v91
	v_pk_fma_f32 v[200:201], v[172:173], v[88:89], v[86:87] op_sel_hi:[1,0,0]
	v_pk_fma_f32 v[202:203], v[174:175], v[88:89], v[86:87] op_sel_hi:[1,0,0]
	v_mul_f32_e32 v86, 0x42400000, v91
	v_pk_fma_f32 v[204:205], v[172:173], v[88:89], v[86:87] op_sel_hi:[1,0,0]
	v_pk_fma_f32 v[206:207], v[174:175], v[88:89], v[86:87] op_sel_hi:[1,0,0]
	v_mul_f32_e32 v86, 0x42800000, v91
	v_pk_fma_f32 v[208:209], v[172:173], v[88:89], v[86:87] op_sel_hi:[1,0,0]
	v_pk_fma_f32 v[210:211], v[174:175], v[88:89], v[86:87] op_sel_hi:[1,0,0]
	v_mul_f32_e32 v86, 0x42a00000, v91
	v_pk_fma_f32 v[212:213], v[172:173], v[88:89], v[86:87] op_sel_hi:[1,0,0]
	v_pk_fma_f32 v[214:215], v[174:175], v[88:89], v[86:87] op_sel_hi:[1,0,0]
	v_mul_f32_e32 v86, 0x42c00000, v91
	v_pk_fma_f32 v[216:217], v[172:173], v[88:89], v[86:87] op_sel_hi:[1,0,0]
	v_pk_fma_f32 v[218:219], v[174:175], v[88:89], v[86:87] op_sel_hi:[1,0,0]
	v_mul_f32_e32 v86, 0x42e00000, v91
	v_pk_fma_f32 v[220:221], v[172:173], v[88:89], v[86:87] op_sel_hi:[1,0,0]
	v_pk_fma_f32 v[222:223], v[174:175], v[88:89], v[86:87] op_sel_hi:[1,0,0]
	v_mul_f32_e32 v86, 0x43000000, v91
	v_pk_add_f32 v[242:243], v[180:181], v[86:87] op_sel_hi:[1,0]
	v_pk_add_f32 v[92:93], v[182:183], v[86:87] op_sel_hi:[1,0]
	v_pk_fma_f32 v[224:225], v[172:173], v[88:89], v[242:243] op_sel_hi:[1,0,1]
	v_pk_fma_f32 v[226:227], v[174:175], v[88:89], v[92:93] op_sel_hi:[1,0,1]
	s_bfe_u32 s4, s99, 0x50006
	s_cmp_lg_u32 s4, 0
	s_cbranch_scc1 .Lat_nofirst
	s_lshr_b32 s5, s33, 4
	s_sub_i32 s5, 8, s5
	s_cmp_le_u32 s5, 0
	s_cbranch_scc1 .Lat_nofirst
	v_mov_b32_e32 v192, v191
	v_mov_b32_e32 v193, v191
	v_mov_b32_e32 v194, v191
	v_mov_b32_e32 v195, v191
	s_cmp_le_u32 s5, 1
	s_cbranch_scc1 .Lat_nofirst
	v_mov_b32_e32 v196, v191
	v_mov_b32_e32 v197, v191
	v_mov_b32_e32 v198, v191
	v_mov_b32_e32 v199, v191
	s_cmp_le_u32 s5, 2
	s_cbranch_scc1 .Lat_nofirst
	v_mov_b32_e32 v200, v191
	v_mov_b32_e32 v201, v191
	v_mov_b32_e32 v202, v191
	v_mov_b32_e32 v203, v191
	s_cmp_le_u32 s5, 3
	s_cbranch_scc1 .Lat_nofirst
	v_mov_b32_e32 v204, v191
	v_mov_b32_e32 v205, v191
	v_mov_b32_e32 v206, v191
	v_mov_b32_e32 v207, v191
	s_cmp_le_u32 s5, 4
	s_cbranch_scc1 .Lat_nofirst
	v_mov_b32_e32 v208, v191
	v_mov_b32_e32 v209, v191
	v_mov_b32_e32 v210, v191
	v_mov_b32_e32 v211, v191
	s_cmp_le_u32 s5, 5
	s_cbranch_scc1 .Lat_nofirst
	v_mov_b32_e32 v212, v191
	v_mov_b32_e32 v213, v191
	v_mov_b32_e32 v214, v191
	v_mov_b32_e32 v215, v191
	s_cmp_le_u32 s5, 6
	s_cbranch_scc1 .Lat_nofirst
	v_mov_b32_e32 v216, v191
	v_mov_b32_e32 v217, v191
	v_mov_b32_e32 v218, v191
	v_mov_b32_e32 v219, v191
	s_cmp_le_u32 s5, 7
	s_cbranch_scc1 .Lat_nofirst
	v_mov_b32_e32 v220, v191
	v_mov_b32_e32 v221, v191
	v_mov_b32_e32 v222, v191
	v_mov_b32_e32 v223, v191
; #define LAS __attribute__((address_space(3)))
; __device__ __forceinline__ void attn_tile(Frame& F, const __amdgpu_buffer_rsrc_t wsr, LAS unsigned char* L, int grp, int h, int seq, int blk, const bf16x8 (&qf)[2], int sl_prev, int sl_cur, int sl_next) {
;     ...
;     for (int Tg = 0; Tg < 3; ++Tg) {
;         bf16x8 kf[3][2];
; #pragma unroll
;         for (int i = 0; i < 3; ++i) { const int rb = 16 * w + 16 * (3 * Tg + i); const LAS unsigned char* kb = L + AT_K + SLOT3(rb >> 7) * AT_SLOT;
; #pragma unroll
;             for (int ks = 0; ks < 2; ++ks) kf[i][ks] = ldfrag(kb, (rb & 127) + r, P144, ks, g4); }
; #pragma unroll
;         for (int i = 0; i < 3; ++i) st[3 * Tg + i] = MFMA16(kf[i][0], qf[0], ((f32x4){b4, b4, b4, b4}));
; #pragma unroll
;         for (int i = 0; i < 3; ++i) st[3 * Tg + i] = MFMA16(kf[i][1], qf[1], st[3 * Tg + i]);
;     }
;     const int lo_ = max(r, 128 - qw0) - 4 * g4, hi_ = r + 128 - 4 * g4;
;     float mx = -INFINITY;
; #pragma unroll
;     for (int T = 0; T < 9; ++T)
; #pragma unroll
;         for (int e = 0; e < 4; ++e) { float y = __builtin_fmaf(sl2, (float)(16 * T + e), st[T][e]);
;             if ((16 * T + e) < lo_) y = -INFINITY;
;             if (T == 8) { if ((16 * T + e) > hi_) y = -INFINITY; }
;             st[T][e] = y; mx = fmaxf(mx, y); }
;     mx = fmaxf(mx, __shfl_xor(mx, 16)); mx = fmaxf(mx, __shfl_xor(mx, 32));
;     float lsum = 0.f;
; #pragma unroll
;     for (int T = 0; T < 9; ++T)
; #pragma unroll
;         for (int e = 0; e < 4; ++e) { const float p = __builtin_amdgcn_exp2f(st[T][e] - mx); st[T][e] = p; lsum += p; }
;     st[9] = (f32x4){0.f, 0.f, 0.f, 0.f};
;     lsum += __shfl_xor(lsum, 16); lsum += __shfl_xor(lsum, 32);
;     mx -= sl2 * (float)(r + 128);
;     f32x4 oa[4];
; #pragma unroll
;     for (int dt = 0; dt < 4; ++dt) oa[dt] = (f32x4){0.f, 0.f, 0.f, 0.f};
; #pragma unroll
;     for (int u = 0; u < 5; ++u) {
;         const v4u pw = (v4u){pk2(st[2 * u][0], st[2 * u][1]), pk2(st[2 * u][2], st[2 * u][3]), pk2(st[2 * u + 1][0], st[2 * u + 1][1]), pk2(st[2 * u + 1][2], st[2 * u + 1][3])};
;         const bf16x8 pf = __builtin_bit_cast(bf16x8, pw);
;         const int v0 = 16 * w + 32 * u, v1 = v0 + 16;
;         const LAS unsigned char* vlo = L + AT_V + SLOT3(v0 >> 7) * AT_SLOT + ((v0 & 127) + 4 * g4 + (r >> 2)) * P144 + 8 * (r & 3);
.Lat_nofirst:
	s_nop 0
	s_waitcnt lgkmcnt(4)
	v_mfma_f32_16x16x32_bf16 v[192:195], v[62:65], v[18:21], v[192:195]
	v_mfma_f32_16x16x32_bf16 v[192:195], v[66:69], v[22:25], v[192:195]
	ds_read_b128 v[62:65], v145
	ds_read_b128 v[66:69], v145 offset:64
	s_waitcnt lgkmcnt(4)
	v_mfma_f32_16x16x32_bf16 v[196:199], v[70:73], v[18:21], v[196:199]
	v_mfma_f32_16x16x32_bf16 v[196:199], v[74:77], v[22:25], v[196:199]
	ds_read_b128 v[70:73], v146
	ds_read_b128 v[74:77], v146 offset:64
	s_waitcnt lgkmcnt(4)
	v_mfma_f32_16x16x32_bf16 v[200:203], v[78:81], v[18:21], v[200:203]
	v_mfma_f32_16x16x32_bf16 v[200:203], v[82:85], v[22:25], v[200:203]
	ds_read_b128 v[78:81], v147
	ds_read_b128 v[82:85], v147 offset:64
	s_waitcnt lgkmcnt(4)
	v_mfma_f32_16x16x32_bf16 v[204:207], v[62:65], v[18:21], v[204:207]
	v_mfma_f32_16x16x32_bf16 v[204:207], v[66:69], v[22:25], v[204:207]
	ds_read_b128 v[62:65], v148
	ds_read_b128 v[66:69], v148 offset:64
	s_waitcnt lgkmcnt(4)
	v_mfma_f32_16x16x32_bf16 v[208:211], v[70:73], v[18:21], v[208:211]
	v_mfma_f32_16x16x32_bf16 v[208:211], v[74:77], v[22:25], v[208:211]
	ds_read_b128 v[70:73], v149
	ds_read_b128 v[74:77], v149 offset:64
	s_waitcnt lgkmcnt(4)
	v_mfma_f32_16x16x32_bf16 v[212:215], v[78:81], v[18:21], v[212:215]
	v_mfma_f32_16x16x32_bf16 v[212:215], v[82:85], v[22:25], v[212:215]
	ds_read_b128 v[78:81], v150
	ds_read_b128 v[82:85], v150 offset:64
	s_waitcnt lgkmcnt(4)
	v_mfma_f32_16x16x32_bf16 v[216:219], v[62:65], v[18:21], v[216:219]
	v_mfma_f32_16x16x32_bf16 v[216:219], v[66:69], v[22:25], v[216:219]
	s_waitcnt lgkmcnt(2)
	v_mfma_f32_16x16x32_bf16 v[220:223], v[70:73], v[18:21], v[220:223]
	v_mfma_f32_16x16x32_bf16 v[220:223], v[74:77], v[22:25], v[220:223]
	s_waitcnt lgkmcnt(0)
	v_mfma_f32_16x16x32_bf16 v[224:227], v[78:81], v[18:21], v[224:227]
	v_mfma_f32_16x16x32_bf16 v[224:227], v[82:85], v[22:25], v[224:227]
	ds_read_b64_tr_b16 v[62:63], v232 offset:55296
	ds_read_b64_tr_b16 v[64:65], v233 offset:55296
	ds_read_b64_tr_b16 v[66:67], v232 offset:55328
	ds_read_b64_tr_b16 v[68:69], v233 offset:55328
	ds_read_b64_tr_b16 v[70:71], v232 offset:55360
	ds_read_b64_tr_b16 v[72:73], v233 offset:55360
	ds_read_b64_tr_b16 v[74:75], v232 offset:55392
	ds_read_b64_tr_b16 v[76:77], v233 offset:55392
	v_max3_f32 v86, v192, v193, v194
	v_max3_f32 v86, v86, v195, v196
	v_max3_f32 v86, v86, v197, v198
	v_max3_f32 v86, v86, v199, v200
	v_max3_f32 v86, v86, v201, v202
	v_max3_f32 v86, v86, v203, v204
	v_max3_f32 v86, v86, v205, v206
	v_max3_f32 v86, v86, v207, v208
	v_max3_f32 v86, v86, v209, v210
	v_max3_f32 v86, v86, v211, v212
	v_max3_f32 v86, v86, v213, v214
	v_max3_f32 v86, v86, v215, v216
	v_max3_f32 v86, v86, v217, v218
	v_max3_f32 v86, v86, v219, v220
	v_max3_f32 v86, v86, v221, v222
	v_max3_f32 v86, v86, v223, v224
	v_max3_f32 v86, v86, v225, v226
	v_max_f32_e32 v86, v86, v227
	ds_bpermute_b32 v58, v189, v86
	s_waitcnt lgkmcnt(0)
	v_max_f32_e32 v86, v86, v58
	ds_bpermute_b32 v58, v190, v86
	s_waitcnt lgkmcnt(0)
	v_max_f32_e32 v86, v86, v58
	v_mov_b32_e32 v254, 0
	v_mov_b32_e32 v255, 0
	v_pk_add_f32 v[192:193], v[192:193], v[86:87] op_sel_hi:[1,0] neg_lo:[0,1] neg_hi:[0,1]
	v_pk_add_f32 v[194:195], v[194:195], v[86:87] op_sel_hi:[1,0] neg_lo:[0,1] neg_hi:[0,1]
	v_pk_add_f32 v[196:197], v[196:197], v[86:87] op_sel_hi:[1,0] neg_lo:[0,1] neg_hi:[0,1]
	v_pk_add_f32 v[198:199], v[198:199], v[86:87] op_sel_hi:[1,0] neg_lo:[0,1] neg_hi:[0,1]
	v_pk_add_f32 v[200:201], v[200:201], v[86:87] op_sel_hi:[1,0] neg_lo:[0,1] neg_hi:[0,1]
	v_pk_add_f32 v[202:203], v[202:203], v[86:87] op_sel_hi:[1,0] neg_lo:[0,1] neg_hi:[0,1]
	v_pk_add_f32 v[204:205], v[204:205], v[86:87] op_sel_hi:[1,0] neg_lo:[0,1] neg_hi:[0,1]
	v_pk_add_f32 v[206:207], v[206:207], v[86:87] op_sel_hi:[1,0] neg_lo:[0,1] neg_hi:[0,1]
	v_pk_add_f32 v[208:209], v[208:209], v[86:87] op_sel_hi:[1,0] neg_lo:[0,1] neg_hi:[0,1]
	v_pk_add_f32 v[210:211], v[210:211], v[86:87] op_sel_hi:[1,0] neg_lo:[0,1] neg_hi:[0,1]
	v_pk_add_f32 v[212:213], v[212:213], v[86:87] op_sel_hi:[1,0] neg_lo:[0,1] neg_hi:[0,1]
	v_pk_add_f32 v[214:215], v[214:215], v[86:87] op_sel_hi:[1,0] neg_lo:[0,1] neg_hi:[0,1]
	v_pk_add_f32 v[216:217], v[216:217], v[86:87] op_sel_hi:[1,0] neg_lo:[0,1] neg_hi:[0,1]
	v_pk_add_f32 v[218:219], v[218:219], v[86:87] op_sel_hi:[1,0] neg_lo:[0,1] neg_hi:[0,1]
	v_pk_add_f32 v[220:221], v[220:221], v[86:87] op_sel_hi:[1,0] neg_lo:[0,1] neg_hi:[0,1]
	v_pk_add_f32 v[222:223], v[222:223], v[86:87] op_sel_hi:[1,0] neg_lo:[0,1] neg_hi:[0,1]
	v_pk_add_f32 v[224:225], v[224:225], v[86:87] op_sel_hi:[1,0] neg_lo:[0,1] neg_hi:[0,1]
	v_pk_add_f32 v[226:227], v[226:227], v[86:87] op_sel_hi:[1,0] neg_lo:[0,1] neg_hi:[0,1]
	v_exp_f32_e32 v192, v192
	v_exp_f32_e32 v193, v193
	v_exp_f32_e32 v194, v194
	v_exp_f32_e32 v195, v195
	v_exp_f32_e32 v196, v196
	v_exp_f32_e32 v197, v197
	v_exp_f32_e32 v198, v198
	v_exp_f32_e32 v199, v199
	v_pk_add_f32 v[254:255], v[254:255], v[192:193]
	v_pk_add_f32 v[254:255], v[254:255], v[194:195]
	v_cvt_pk_bf16_f32 v142, v192, v193
	v_cvt_pk_bf16_f32 v143, v194, v195
	v_exp_f32_e32 v200, v200
	v_exp_f32_e32 v201, v201
	v_exp_f32_e32 v202, v202
	v_exp_f32_e32 v203, v203
	v_pk_add_f32 v[254:255], v[254:255], v[196:197]
	v_pk_add_f32 v[254:255], v[254:255], v[198:199]
	v_cvt_pk_bf16_f32 v144, v196, v197
	v_cvt_pk_bf16_f32 v145, v198, v199
	v_exp_f32_e32 v204, v204
	v_exp_f32_e32 v205, v205
	v_exp_f32_e32 v206, v206
	v_exp_f32_e32 v207, v207
	v_pk_add_f32 v[254:255], v[254:255], v[200:201]
	v_pk_add_f32 v[254:255], v[254:255], v[202:203]
	v_cvt_pk_bf16_f32 v146, v200, v201
	v_cvt_pk_bf16_f32 v147, v202, v203
	v_exp_f32_e32 v208, v208
	v_exp_f32_e32 v209, v209
; #define LAS __attribute__((address_space(3)))
; __device__ __forceinline__ unsigned pk2(float lo, float hi) { f32x2 v = {lo, hi}; bf16x2_t b = __builtin_convertvector(v, bf16x2_t); return __builtin_bit_cast(unsigned, b); }
; #define MFMA16(a, b, c) __builtin_amdgcn_mfma_f32_16x16x32_bf16((a), (b), (c), 0, 0, 0)
; __device__ __forceinline__ s16x4 tr16(const LAS unsigned char* p) { return __builtin_bit_cast(s16x4, __builtin_amdgcn_ds_read_tr16_b64_v4i16((LAS s16x4*)p)); }
; __device__ __forceinline__ void attn_tile(Frame& F, const __amdgpu_buffer_rsrc_t wsr, LAS unsigned char* L, int grp, int h, int seq, int blk, const bf16x8 (&qf)[2], int sl_prev, int sl_cur, int sl_next) {
;     ...
;     for (int T = 0; T < 9; ++T)
; #pragma unroll
;         for (int e = 0; e < 4; ++e) { const float p = __builtin_amdgcn_exp2f(st[T][e] - mx); st[T][e] = p; lsum += p; }
;     st[9] = (f32x4){0.f, 0.f, 0.f, 0.f};
;     lsum += __shfl_xor(lsum, 16); lsum += __shfl_xor(lsum, 32);
;     mx -= sl2 * (float)(r + 128);
;     f32x4 oa[4];
; #pragma unroll
;     for (int dt = 0; dt < 4; ++dt) oa[dt] = (f32x4){0.f, 0.f, 0.f, 0.f};
; #pragma unroll
;     for (int u = 0; u < 5; ++u) {
;         const v4u pw = (v4u){pk2(st[2 * u][0], st[2 * u][1]), pk2(st[2 * u][2], st[2 * u][3]), pk2(st[2 * u + 1][0], st[2 * u + 1][1]), pk2(st[2 * u + 1][2], st[2 * u + 1][3])};
;         const bf16x8 pf = __builtin_bit_cast(bf16x8, pw);
;         const int v0 = 16 * w + 32 * u, v1 = v0 + 16;
;         const LAS unsigned char* vlo = L + AT_V + SLOT3(v0 >> 7) * AT_SLOT + ((v0 & 127) + 4 * g4 + (r >> 2)) * P144 + 8 * (r & 3);
;         const LAS unsigned char* vhi = L + AT_V + SLOT3(v1 >> 7) * AT_SLOT + ((v1 & 127) + 4 * g4 + (r >> 2)) * P144 + 8 * (r & 3);
; #pragma unroll
;         for (int dt = 0; dt < 4; ++dt) {
;             const s16x4 lo = tr16(vlo + 32 * dt), hi = tr16(vhi + 32 * dt);
;             const bf16x8 vf = (bf16x8){lo[0], lo[1], lo[2], lo[3], hi[0], hi[1], hi[2], hi[3]};
;             oa[dt] = MFMA16(vf, pf, oa[dt]);
;         }
;     }
	v_exp_f32_e32 v210, v210
	v_exp_f32_e32 v211, v211
	v_pk_add_f32 v[254:255], v[254:255], v[204:205]
	v_pk_add_f32 v[254:255], v[254:255], v[206:207]
	v_cvt_pk_bf16_f32 v148, v204, v205
	v_cvt_pk_bf16_f32 v149, v206, v207
	v_exp_f32_e32 v212, v212
	v_exp_f32_e32 v213, v213
	v_exp_f32_e32 v214, v214
	v_exp_f32_e32 v215, v215
	v_pk_add_f32 v[254:255], v[254:255], v[208:209]
	v_pk_add_f32 v[254:255], v[254:255], v[210:211]
	v_cvt_pk_bf16_f32 v150, v208, v209
	v_cvt_pk_bf16_f32 v151, v210, v211
	v_exp_f32_e32 v216, v216
	v_exp_f32_e32 v217, v217
	v_exp_f32_e32 v218, v218
	v_exp_f32_e32 v219, v219
	v_pk_add_f32 v[254:255], v[254:255], v[212:213]
	v_pk_add_f32 v[254:255], v[254:255], v[214:215]
	v_cvt_pk_bf16_f32 v152, v212, v213
	v_cvt_pk_bf16_f32 v153, v214, v215
	v_exp_f32_e32 v220, v220
	v_exp_f32_e32 v221, v221
	v_exp_f32_e32 v222, v222
	v_exp_f32_e32 v223, v223
	v_pk_add_f32 v[254:255], v[254:255], v[216:217]
	v_pk_add_f32 v[254:255], v[254:255], v[218:219]
	v_cvt_pk_bf16_f32 v154, v216, v217
	v_cvt_pk_bf16_f32 v155, v218, v219
	v_exp_f32_e32 v224, v224
	v_exp_f32_e32 v225, v225
	v_exp_f32_e32 v226, v226
	v_exp_f32_e32 v227, v227
	v_pk_add_f32 v[254:255], v[254:255], v[220:221]
	v_pk_add_f32 v[254:255], v[254:255], v[222:223]
	v_cvt_pk_bf16_f32 v156, v220, v221
	v_cvt_pk_bf16_f32 v157, v222, v223
	s_nop 0
	v_pk_add_f32 v[254:255], v[254:255], v[224:225]
	v_pk_add_f32 v[254:255], v[254:255], v[226:227]
	v_cvt_pk_bf16_f32 v162, v224, v225
	v_cvt_pk_bf16_f32 v163, v226, v227
	v_mov_b32_e32 v164, 0
	v_mov_b32_e32 v165, 0
	v_add_f32_e32 v89, v254, v255
	ds_read_b64_tr_b16 v[208:209], v234 offset:55296
	ds_read_b64_tr_b16 v[210:211], v235 offset:55296
	ds_read_b64_tr_b16 v[212:213], v234 offset:55328
	ds_read_b64_tr_b16 v[214:215], v235 offset:55328
	ds_read_b64_tr_b16 v[216:217], v234 offset:55360
	ds_read_b64_tr_b16 v[218:219], v235 offset:55360
	ds_read_b64_tr_b16 v[220:221], v234 offset:55392
	ds_read_b64_tr_b16 v[222:223], v235 offset:55392
	ds_bpermute_b32 v58, v189, v89
	s_waitcnt lgkmcnt(0)
	v_add_f32_e32 v89, v89, v58
	ds_bpermute_b32 v58, v190, v89
	v_mfma_f32_16x16x32_bf16 v[192:195], v[62:65], v[142:145], 0
	v_mfma_f32_16x16x32_bf16 v[196:199], v[66:69], v[142:145], 0
	v_mfma_f32_16x16x32_bf16 v[200:203], v[70:73], v[142:145], 0
	v_mfma_f32_16x16x32_bf16 v[204:207], v[74:77], v[142:145], 0
	ds_read_b64_tr_b16 v[62:63], v236 offset:55296
	ds_read_b64_tr_b16 v[64:65], v237 offset:55296
	ds_read_b64_tr_b16 v[66:67], v236 offset:55328
	ds_read_b64_tr_b16 v[68:69], v237 offset:55328
	ds_read_b64_tr_b16 v[70:71], v236 offset:55360
	ds_read_b64_tr_b16 v[72:73], v237 offset:55360
	ds_read_b64_tr_b16 v[74:75], v236 offset:55392
	ds_read_b64_tr_b16 v[76:77], v237 offset:55392
	s_waitcnt lgkmcnt(8)
	v_add_f32_e32 v89, v89, v58
	v_mfma_f32_16x16x32_bf16 v[192:195], v[208:211], v[146:149], v[192:195]
	v_mfma_f32_16x16x32_bf16 v[196:199], v[212:215], v[146:149], v[196:199]
	v_mfma_f32_16x16x32_bf16 v[200:203], v[216:219], v[146:149], v[200:203]
	v_mfma_f32_16x16x32_bf16 v[204:207], v[220:223], v[146:149], v[204:207]
	ds_read_b64_tr_b16 v[208:209], v238 offset:55296
	ds_read_b64_tr_b16 v[210:211], v239 offset:55296
	ds_read_b64_tr_b16 v[212:213], v238 offset:55328
	ds_read_b64_tr_b16 v[214:215], v239 offset:55328
	ds_read_b64_tr_b16 v[216:217], v238 offset:55360
	ds_read_b64_tr_b16 v[218:219], v239 offset:55360
	ds_read_b64_tr_b16 v[220:221], v238 offset:55392
	ds_read_b64_tr_b16 v[222:223], v239 offset:55392
	s_waitcnt lgkmcnt(8)
; __device__ __forceinline__ unsigned pk2(float lo, float hi) { f32x2 v = {lo, hi}; bf16x2_t b = __builtin_convertvector(v, bf16x2_t); return __builtin_bit_cast(unsigned, b); }
; #define MFMA16(a, b, c) __builtin_amdgcn_mfma_f32_16x16x32_bf16((a), (b), (c), 0, 0, 0)
; __device__ __forceinline__ s16x4 tr16(const LAS unsigned char* p) { return __builtin_bit_cast(s16x4, __builtin_amdgcn_ds_read_tr16_b64_v4i16((LAS s16x4*)p)); }
; __device__ __forceinline__ void attn_tile(Frame& F, const __amdgpu_buffer_rsrc_t wsr, LAS unsigned char* L, int grp, int h, int seq, int blk, const bf16x8 (&qf)[2], int sl_prev, int sl_cur, int sl_next) {
;     ...
; #pragma unroll
;         for (int dt = 0; dt < 4; ++dt) {
;             const s16x4 lo = tr16(vlo + 32 * dt), hi = tr16(vhi + 32 * dt);
;             const bf16x8 vf = (bf16x8){lo[0], lo[1], lo[2], lo[3], hi[0], hi[1], hi[2], hi[3]};
;             oa[dt] = MFMA16(vf, pf, oa[dt]);
;         }
;     }
;     const float inv = 1.f / lsum;
;     const int m = qw0 + r, res = seq & ((1 << dsh) - 1), b = seq >> dsh;
;     const unsigned nrow = (unsigned)(b * SEQ + (m << dsh) + res);
;     const unsigned ob = (nrow * DM + h * 64 + 4 * g4) * 2u; const int obase = (int)(unsigned)(WS_OG + (size_t)grp * QKV_STRIDE);
; #pragma unroll
;     for (int dt = 0; dt < 4; ++dt) __builtin_amdgcn_raw_buffer_store_b64((v2u){pk2(oa[dt][0] * inv, oa[dt][1] * inv), pk2(oa[dt][2] * inv, oa[dt][3] * inv)}, wsr, (int)(ob + 32u * dt), obase, 0);
;     if (g4 == 0) __builtin_amdgcn_raw_buffer_store_b32(__float_as_uint((mx + __log2f(lsum)) * LN2), wsr, (int)((((unsigned)grp * MT + nrow) * 16 + h) * 4u), (int)(unsigned)WS_LSE, 0);
	v_mfma_f32_16x16x32_bf16 v[192:195], v[62:65], v[150:153], v[192:195]
	v_mfma_f32_16x16x32_bf16 v[196:199], v[66:69], v[150:153], v[196:199]
	v_mfma_f32_16x16x32_bf16 v[200:203], v[70:73], v[150:153], v[200:203]
	v_mfma_f32_16x16x32_bf16 v[204:207], v[74:77], v[150:153], v[204:207]
	ds_read_b64_tr_b16 v[62:63], v240 offset:55296
	ds_read_b64_tr_b16 v[64:65], v241 offset:55296
	ds_read_b64_tr_b16 v[66:67], v240 offset:55328
	ds_read_b64_tr_b16 v[68:69], v241 offset:55328
	ds_read_b64_tr_b16 v[70:71], v240 offset:55360
	ds_read_b64_tr_b16 v[72:73], v241 offset:55360
	ds_read_b64_tr_b16 v[74:75], v240 offset:55392
	ds_read_b64_tr_b16 v[76:77], v241 offset:55392
	s_waitcnt lgkmcnt(8)
	v_mfma_f32_16x16x32_bf16 v[192:195], v[208:211], v[154:157], v[192:195]
	v_mfma_f32_16x16x32_bf16 v[196:199], v[212:215], v[154:157], v[196:199]
	v_mfma_f32_16x16x32_bf16 v[200:203], v[216:219], v[154:157], v[200:203]
	v_mfma_f32_16x16x32_bf16 v[204:207], v[220:223], v[154:157], v[204:207]
	s_waitcnt lgkmcnt(0)
	v_mfma_f32_16x16x32_bf16 v[192:195], v[62:65], v[162:165], v[192:195]
	v_mfma_f32_16x16x32_bf16 v[196:199], v[66:69], v[162:165], v[196:199]
	v_mfma_f32_16x16x32_bf16 v[200:203], v[70:73], v[162:165], v[200:203]
	v_mfma_f32_16x16x32_bf16 v[204:207], v[74:77], v[162:165], v[204:207]
	v_div_scale_f32 v58, s[34:35], v89, v89, 1.0
	v_rcp_f32_e32 v59, v58
	s_bfe_u32 s4, s99, 0x20000
	v_fma_f32 v61, -v58, v59, 1.0
	v_fmac_f32_e32 v59, v61, v59
	v_div_scale_f32 v61, vcc, 1.0, v89, 1.0
	v_mul_f32_e32 v92, v61, v59
	v_fma_f32 v93, -v58, v92, v61
	v_fmac_f32_e32 v92, v93, v59
	v_fma_f32 v58, -v58, v92, v61
	v_div_fmas_f32 v58, v58, v59, v92
	v_div_fixup_f32 v92, v58, v89, 1.0
	s_lshl_b32 s5, s4, 1
	s_bfe_u32 s15, s99, 0x80011
	s_lshr_b32 s34, s15, s5
	s_lshl_b32 s34, s34, 12
	s_bfm_b32 s35, s5, 0
	s_and_b32 s35, s35, s15
	s_add_i32 s34, s34, s35
	s_bfe_u32 s35, s99, 0x50006
	s_lshl_b32 s35, s35, 7
	s_add_i32 s35, s35, s33
	v_add_u32_e32 v58, s35, v185
	v_lshlrev_b32_e32 v58, s5, v58
	v_add_u32_e32 v58, s34, v58
	s_bfe_u32 s5, s99, 0x40002
	s_lshl_b32 s15, s5, 7
	v_add_u32_e32 v59, s15, v188
	v_lshl_add_u32 v59, v58, 11, v59
	s_mul_i32 s15, s4, 0x2100000
	s_add_i32 s15, s15, 0x23000000
	s_mov_b32 s16, s30
	v_pk_mul_f32 v[192:193], v[192:193], v[92:93] op_sel_hi:[1,0]
	v_pk_mul_f32 v[194:195], v[194:195], v[92:93] op_sel_hi:[1,0]
	v_pk_mul_f32 v[196:197], v[196:197], v[92:93] op_sel_hi:[1,0]
	v_pk_mul_f32 v[198:199], v[198:199], v[92:93] op_sel_hi:[1,0]
	v_pk_mul_f32 v[200:201], v[200:201], v[92:93] op_sel_hi:[1,0]
	v_pk_mul_f32 v[202:203], v[202:203], v[92:93] op_sel_hi:[1,0]
	v_pk_mul_f32 v[204:205], v[204:205], v[92:93] op_sel_hi:[1,0]
	v_pk_mul_f32 v[206:207], v[206:207], v[92:93] op_sel_hi:[1,0]
	v_cvt_pk_bf16_f32 v192, v192, v193
	v_cvt_pk_bf16_f32 v193, v194, v195
	v_cvt_pk_bf16_f32 v196, v196, v197
	v_cvt_pk_bf16_f32 v197, v198, v199
	v_cvt_pk_bf16_f32 v200, v200, v201
	v_cvt_pk_bf16_f32 v201, v202, v203
	v_cvt_pk_bf16_f32 v204, v204, v205
	v_cvt_pk_bf16_f32 v205, v206, v207
	buffer_store_dwordx2 v[192:193], v59, s[16:19], s15 offen
	buffer_store_dwordx2 v[196:197], v59, s[16:19], s15 offen offset:32
	buffer_store_dwordx2 v[200:201], v59, s[16:19], s15 offen offset:64
	buffer_store_dwordx2 v[204:205], v59, s[16:19], s15 offen offset:96
	v_log_f32_e32 v61, v89
	v_fma_f32 v86, -v91, v184, v86
	s_mul_i32 s15, s4, 0x4100
	v_add_u32_e32 v58, s15, v58
	v_add_f32_e32 v61, v86, v61
	s_lshl_b32 s15, s5, 2
	v_mul_f32_e32 v61, 0x3f317218, v61
	v_lshl_add_u32 v58, v58, 6, s15
	s_mov_b32 s15, 0x29300000
	s_mov_b64 exec, 0xffff
	buffer_store_dword v61, v58, s[16:19], s15 offen
	s_mov_b64 exec, -1
	s_bitcmp1_b32 s99, 26
	s_cbranch_scc1 .Lp9n_retA
	s_bitcmp1_b32 s99, 27
	s_cbranch_scc1 .Lp9n_retB
	s_bitcmp1_b32 s99, 28
	s_cbranch_scc1 .Lp9n_retC
	s_bitcmp1_b32 s99, 16
	s_cbranch_scc1 .Lat_retB
	s_bitset1_b32 s98, 1

.LBB0_1676:
	s_andn2_b64 vcc, exec, s[4:5]
	s_cbranch_vccnz .LBB0_1648
	s_bfe_u32 s99, s98, 0x10003
	s_bfe_u32 s100, s98, 0x10000
	s_bfe_u32 s101, s98, 0x10001
	s_add_u32 s99, s99, s101
	s_mul_i32 s99, s99, 5
	s_mul_i32 s100, s100, 6
	s_add_u32 s99, s99, s100
	s_cmp_eq_u32 s99, 16
	s_cbranch_scc1 .Lat_b16
	s_cmp_eq_u32 s99, 11
	s_cbranch_scc1 .Lat_b11
	s_cmp_eq_u32 s99, 10
	s_cbranch_scc1 .Lat_b10
	s_cmp_eq_u32 s99, 6
	s_cbranch_scc1 .Lat_b6
	s_cmp_eq_u32 s99, 5
	s_cbranch_scc1 .Lat_b5
	s_waitcnt vmcnt(0)
	s_branch .Lat_bdone

.Lat_bdone:
	s_andn2_b32 s98, s98, 12
	v_mov_b64_e32 v[10:11], v[246:247]
	v_mov_b64_e32 v[12:13], v[248:249]
	v_mov_b64_e32 v[14:15], v[250:251]
	v_mov_b64_e32 v[16:17], v[252:253]
	s_add_i32 s26, s26, 1
	s_cmpk_gt_i32 s39, 0x1ff
	s_cselect_b32 s4, 12, 9
	s_mul_i32 s42, s42, 0xd800
	s_cmp_ge_i32 s26, s4
	v_subrev_u32_e32 v25, s42, v128
	v_cmp_lt_i32_e32 vcc, -1, v139
	s_cselect_b64 s[4:5], -1, 0
	v_subrev_u32_e32 v24, s42, v127
	v_cndmask_b32_e32 v21, 0, v49, vcc
	v_cndmask_b32_e32 v20, 0, v48, vcc
	v_cndmask_b32_e32 v19, 0, v47, vcc
	v_cndmask_b32_e32 v18, 0, v46, vcc
	v_add_u32_e32 v25, v90, v25
	s_and_b64 s[34:35], s[4:5], exec
	v_subrev_u32_e32 v23, s42, v126
	ds_write_b128 v25, v[18:21]
	v_cndmask_b32_e32 v21, 0, v45, vcc
	v_cndmask_b32_e32 v20, 0, v44, vcc
	v_cndmask_b32_e32 v19, 0, v43, vcc
	v_cndmask_b32_e32 v18, 0, v42, vcc
	v_add_u32_e32 v24, v90, v24
	s_cselect_b32 s26, 0, s26
	s_cmp_lg_u64 s[4:5], 0
	v_subrev_u32_e32 v22, s42, v125
	ds_write_b128 v24, v[18:21]
	v_cndmask_b32_e32 v21, 0, v57, vcc
	v_cndmask_b32_e32 v20, 0, v56, vcc
	v_cndmask_b32_e32 v19, 0, v55, vcc
	v_cndmask_b32_e32 v18, 0, v54, vcc
	v_add_u32_e32 v23, v90, v23
	s_addc_u32 s23, s23, 0
	ds_write_b128 v23, v[18:21]
	v_cndmask_b32_e32 v21, 0, v53, vcc
	v_cndmask_b32_e32 v20, 0, v52, vcc
	v_cndmask_b32_e32 v19, 0, v51, vcc
	v_cndmask_b32_e32 v18, 0, v50, vcc
	v_add_u32_e32 v22, v90, v22
	ds_write_b128 v22, v[18:21]
	s_mul_i32 s39, s23, s44
	s_add_i32 s39, s39, s2
	s_waitcnt lgkmcnt(0)
	s_barrier
	s_cmpk_lt_i32 s39, 0x300
	s_cselect_b64 s[4:5], -1, 0
	s_cmpk_gt_i32 s39, 0x2ff
	s_cbranch_scc1 .LBB0_1683
	s_ashr_i32 s14, s39, 8
	s_and_b32 s15, s39, 0xff
	s_cmp_gt_i32 s14, 1
	s_mov_b64 s[34:35], -1
	s_cbranch_scc0 .LBB0_1680
	s_mul_hi_i32 s34, s26, 0x55555556
	s_lshr_b32 s35, s34, 31
	s_lshl_b32 s16, s15, 2
	s_add_i32 s34, s34, s35
	s_add_i32 s16, s16, s34
	s_mul_i32 s34, s34, 3
	s_not_b32 s34, s34
	s_ashr_i32 s42, s16, 4
	s_add_i32 s43, s34, s26
	s_mov_b64 s[34:35], 0

.LBB0_1683:
	v_cmp_lt_i32_e32 vcc, -1, v133
	s_and_b64 s[4:5], s[4:5], vcc
	v_mov_b64_e32 v[24:25], v[16:17]
	s_andn2_b64 vcc, exec, s[4:5]
	v_mov_b64_e32 v[22:23], v[14:15]
	v_mov_b64_e32 v[20:21], v[12:13]
	v_mov_b64_e32 v[18:19], v[10:11]
	s_cbranch_vccnz .LBB0_1685
	s_lshl_b32 s4, s14, 1
	s_lshr_b32 s4, 0x1000, s4
	v_mul_lo_u32 v18, v134, s4
	v_lshlrev_b32_e32 v19, 7, v133
	v_add_u32_e32 v18, v19, v18
	v_lshlrev_b32_e32 v19, 7, v135
	s_mul_i32 s4, s14, 0x2100000
	v_or_b32_e32 v20, v19, v95
	v_add_u32_e32 v21, v18, v99
	s_add_i32 s5, s4, 0x16a00000
	v_lshl_add_u32 v21, v21, 11, v20
	s_mov_b32 s16, s30
	s_add_i32 s15, s4, 0x1cd00000
	buffer_load_dwordx4 v[46:49], v21, s[16:19], s5 offen
	buffer_load_dwordx4 v[42:45], v21, s[16:19], s15 offen
	v_add_u32_e32 v21, v18, v96
	v_add_lshl_u32 v18, v18, v97, 11
	v_lshl_add_u32 v20, v21, 11, v20
	s_add_i32 s4, s4, 0x10700000
	v_add3_u32 v22, v19, v98, v18
	buffer_load_dwordx4 v[54:57], v20, s[16:19], s5 offen
	buffer_load_dwordx4 v[50:53], v20, s[16:19], s15 offen
	s_nop 0
	buffer_load_dwordx4 v[246:249], v22, s[16:19], s4 offen
	s_nop 0
	buffer_load_dwordx4 v[250:253], v22, s[16:19], s4 offen offset:64
	s_bitset1_b32 s98, 2
.LBB0_1685:
	s_andn2_b64 vcc, exec, s[88:89]
	s_cbranch_vccnz .LBB0_1689
	v_readfirstlane_b32 s4, v139
	v_readfirstlane_b32 s5, v141
	v_readfirstlane_b32 s15, v140
	s_nop 1
	s_add_i32 s16, s48, s49
	s_sub_i32 s16, 3, s16
	s_lshl_b32 s16, s16, 3
	s_lshr_b32 s34, s33, 4
	s_add_i32 s16, s16, s34
	s_lshl_b32 s99, s16, 11
	s_or_b32 s99, s99, s60
	s_lshl_b32 s5, s5, 2
	s_or_b32 s99, s99, s5
	s_lshl_b32 s4, s4, 6
	s_or_b32 s99, s99, s4
	s_lshl_b32 s15, s15, 17
	s_or_b32 s99, s99, s15
	s_bitset1_b32 s99, 16
	v_mov_b64_e32 v[18:19], v[10:11]
	v_mov_b64_e32 v[20:21], v[12:13]
	v_mov_b64_e32 v[22:23], v[14:15]
	v_mov_b64_e32 v[24:25], v[16:17]
	s_branch .Lat_tile
.Lat_retB:
	s_bitset1_b32 s98, 3

; #define LAS __attribute__((address_space(3)))
; #define WG_BAR() asm volatile("s_waitcnt lgkmcnt(0)\n\ts_barrier" ::: "memory")
; #define ATT_ADV(ui, s) do { ++(s); if ((s) >= att_unit_steps(F.bid + (ui) * F.G)) { (s) = 0; ++(ui); } } while (0)
; __device__ __forceinline__ void attn_prompt(Frame& F) {
;     LAS unsigned char* L = F.lds; const int tid = F.tid, lane = F.lane, w = F.wave, r = lane & 15, g4 = lane >> 4;
;     __syncthreads();
;     for (int e = tid; e < 6 * AT_SLOT / 16; e += 512) *(LAS v4u*)(L + e * 16) = (v4u){0u, 0u, 0u, 0u};
;     WG_BAR();
;     const __amdgpu_buffer_rsrc_t wsr = __builtin_amdgcn_make_buffer_rsrc((void*)F.ws, (short)0, (int)WS_END, 0x00020000);
;     v4u kA[2], vA[2], kB[2], vB[2]; bf16x8 qA[2], qB[2];
; #pragma unroll
;     for (int i = 0; i < 2; ++i) { kA[i] = vA[i] = kB[i] = vB[i] = (v4u){0u, 0u, 0u, 0u}; qA[i] = qB[i] = (bf16x8){0, 0, 0, 0, 0, 0, 0, 0}; }
;     int cui = 0, cs = 0, pui = 0, ps = 0, nstep = 0; bool running = true;
;     ATT_LOAD(pui, ps, kA, vA, qA); ATT_ADV(pui, ps);
;     ATT_LOAD(pui, ps, kB, vB, qB); ATT_ADV(pui, ps);
.Lp9n_entry:
	v_readfirstlane_b32 s33, v0
	s_mov_b32 s16, s30
	s_and_b32 s17, s31, 0xffff
	s_mov_b32 s18, 0x2b800000
	s_mov_b32 s19, 0x20000
	s_mov_b32 s95, 0x42400000
	s_lshr_b32 s33, s33, 6
	s_lshl_b32 s33, s33, 4
	v_and_b32_e32 v185, 15, v160
	v_lshrrev_b32_e32 v186, 4, v160
	v_lshlrev_b32_e32 v186, 2, v186
	v_mov_b32_e32 v191, 0xff800000
	v_mul_u32_u24_e32 v170, 0x90, v185
	v_lshl_add_u32 v170, v186, 2, v170
	v_lshrrev_b32_e32 v171, 2, v185
	v_add_u32_e32 v171, v171, v186
	v_mul_u32_u24_e32 v171, 0x90, v171
	v_and_b32_e32 v172, 3, v185
	v_lshl_add_u32 v171, v172, 3, v171
	v_cvt_f32_u32_e32 v172, v186
	v_add_f32_e32 v173, 1.0, v172
	v_add_f32_e32 v174, 2.0, v172
	v_add_f32_e32 v175, 1.0, v174
	v_add_u32_e32 v184, 0, v186
	v_cmp_lt_u32_e32 vcc, v184, v185
	s_nop 1
	v_cndmask_b32_e32 v176, 0, v191, vcc
	v_cmp_gt_u32_e32 vcc, v184, v185
	s_nop 1
	v_cndmask_b32_e32 v180, 0, v191, vcc
	v_add_u32_e32 v184, 1, v186
	v_cmp_lt_u32_e32 vcc, v184, v185
	s_nop 1
	v_cndmask_b32_e32 v177, 0, v191, vcc
	v_cmp_gt_u32_e32 vcc, v184, v185
	s_nop 1
	v_cndmask_b32_e32 v181, 0, v191, vcc
	v_add_u32_e32 v184, 2, v186
	v_cmp_lt_u32_e32 vcc, v184, v185
	s_nop 1
	v_cndmask_b32_e32 v178, 0, v191, vcc
	v_cmp_gt_u32_e32 vcc, v184, v185
	s_nop 1
	v_cndmask_b32_e32 v182, 0, v191, vcc
	v_add_u32_e32 v184, 3, v186
	v_cmp_lt_u32_e32 vcc, v184, v185
	s_nop 1
	v_cndmask_b32_e32 v179, 0, v191, vcc
	v_cmp_gt_u32_e32 vcc, v184, v185
	s_nop 1
	v_cndmask_b32_e32 v183, 0, v191, vcc
	v_add_u32_e32 v184, 0x80, v185
	v_cvt_f32_u32_e32 v184, v184
	v_subrev_u32_e32 v187, 24, v160
	v_min_u32_e32 v187, v160, v187
	v_mul_u32_u24_e32 v187, 0x900, v187
	v_lshlrev_b32_e32 v188, 1, v186
	v_xor_b32_e32 v189, 16, v160
	v_lshlrev_b32_e32 v189, 2, v189
	v_xor_b32_e32 v190, 32, v160
	v_lshlrev_b32_e32 v190, 2, v190
	v_lshrrev_b32_e32 v105, 3, v0
	v_and_b32_e32 v106, 7, v0
	v_mul_u32_u24_e32 v100, 0x90, v105
	v_lshl_add_u32 v100, v106, 4, v100
	v_lshlrev_b32_e32 v101, 4, v0
	v_add_u32_e32 v102, 0x2000, v101
	v_add_u32_e32 v103, s33, v185
	v_lshlrev_b32_e32 v103, 7, v103
	v_lshl_add_u32 v103, v186, 2, v103
	v_mov_b32_e32 v108, 0x80000000
	s_lshr_b32 s21, s2, 2
	s_and_b32 s22, s21, 15
	s_lshr_b32 s23, s21, 4
	s_and_b32 s24, s2, 3
	s_lshl_b32 s24, s24, 3
	s_lshl_b32 s25, s22, 2
	s_lshl_b32 s26, s23, 12
	s_or_b32 s25, s25, s26
	s_lshl_b32 s26, s24, 6
	s_or_b32 s25, s25, s26
	s_cmp_lg_u32 s24, 0
	s_cselect_b32 s26, 0x200000, 0
	s_or_b32 s26, s25, s26
	v_writelane_b32 v104, s26, 0
	s_add_i32 s26, s25, 3145792
	v_writelane_b32 v104, s26, 1
	s_add_i32 s26, s25, 3145856
	v_writelane_b32 v104, s26, 2
	s_add_i32 s26, s25, 3145920
	v_writelane_b32 v104, s26, 3
	s_add_i32 s26, s25, 3145984
	v_writelane_b32 v104, s26, 4
	s_add_i32 s26, s25, 3146048
	v_writelane_b32 v104, s26, 5
	s_add_i32 s26, s25, 3146112
	v_writelane_b32 v104, s26, 6
	s_add_i32 s26, s25, 3146176
	v_writelane_b32 v104, s26, 7
	s_add_i32 s26, s25, 3146240
	v_writelane_b32 v104, s26, 8
	s_and_b32 s22, s2, 15
	s_lshr_b32 s23, s2, 4
	s_lshl_b32 s25, s22, 2
	s_lshl_b32 s26, s23, 12
	s_or_b32 s25, s25, s26
	s_or_b32 s25, s25, 1
	v_writelane_b32 v104, s25, 9
	s_add_i32 s26, s25, 3145792
	v_writelane_b32 v104, s26, 10
	s_add_i32 s26, s25, 3145856
	v_writelane_b32 v104, s26, 11
	s_add_i32 s26, s25, 3145920
	v_writelane_b32 v104, s26, 12
	s_add_i32 s26, s25, 3145984
	v_writelane_b32 v104, s26, 13
	s_add_i32 s26, s25, 3146048
	v_writelane_b32 v104, s26, 14
	s_add_i32 s26, s25, 3146112
	v_writelane_b32 v104, s26, 15
	s_add_i32 s26, s25, 3146176
	v_writelane_b32 v104, s26, 16
	s_add_i32 s26, s25, 3146240
	v_writelane_b32 v104, s26, 17
	s_and_b32 s22, s2, 3
	s_lshl_b32 s22, s22, 2
	s_lshr_b32 s23, s2, 2
	s_lshl_b32 s26, s23, 12
	s_add_i32 s25, s22, 0
	s_lshl_b32 s25, s25, 2
	s_or_b32 s25, s25, s26
	s_or_b32 s25, s25, 2
	v_writelane_b32 v104, s25, 18
	s_add_i32 s27, s25, 3145792
	v_writelane_b32 v104, s27, 19
	s_add_i32 s27, s25, 3145856
	v_writelane_b32 v104, s27, 20
	s_add_i32 s25, s22, 1
	s_lshl_b32 s25, s25, 2
	s_or_b32 s25, s25, s26
	s_or_b32 s25, s25, 2
	v_writelane_b32 v104, s25, 21
	s_add_i32 s27, s25, 3145792
	v_writelane_b32 v104, s27, 22
	s_add_i32 s27, s25, 3145856
	v_writelane_b32 v104, s27, 23
	s_add_i32 s25, s22, 2
	s_lshl_b32 s25, s25, 2
	s_or_b32 s25, s25, s26
	s_or_b32 s25, s25, 2
	v_writelane_b32 v104, s25, 24
	s_add_i32 s27, s25, 3145792
	v_writelane_b32 v104, s27, 25
	s_add_i32 s27, s25, 3145856
	v_writelane_b32 v104, s27, 26
	s_add_i32 s25, s22, 3
	s_lshl_b32 s25, s25, 2
	s_or_b32 s25, s25, s26
	s_or_b32 s25, s25, 2
	v_writelane_b32 v104, s25, 27
	s_add_i32 s27, s25, 3145792
	v_writelane_b32 v104, s27, 28
	s_add_i32 s27, s25, 3145856
	v_writelane_b32 v104, s27, 29
	s_mov_b32 s25, 0
	v_writelane_b32 v104, s25, 30
	v_writelane_b32 v104, s25, 31
	v_writelane_b32 v104, s25, 32
	s_nop 1
	v_readlane_b32 s23, v104, 0
	s_nop 3
	s_bfe_u32 s36, s23, 0x20000
	s_bfe_u32 s37, s23, 0x40002
	s_bfe_u32 s38, s23, 0x60006
	s_bfe_u32 s39, s23, 0x8000c
	s_lshl_b32 s40, s36, 1
	s_lshr_b32 s40, 0x1000, s40
	s_mul_i32 s39, s39, s40
	s_add_i32 s38, s38, -1
	s_lshl_b32 s38, s38, 7
	s_add_i32 s39, s39, s38
	s_lshl_b32 s39, s39, 7
	s_mul_i32 s37, s37, 0x208000
	s_add_i32 s39, s39, s37
	s_bitcmp1_b32 s23, 21
	s_cselect_b32 s39, s39, 0x80000000
	s_mul_i32 s36, s36, 0x2100000
	s_add_i32 s40, s36, 0x16a00000
	s_add_i32 s41, s36, 0x1cd00000
	s_add_i32 s42, s36, 0x10700000
	v_add_u32_e32 v105, s39, v101
	v_add_u32_e32 v106, s39, v102
	v_add_u32_e32 v107, s39, v103
	buffer_load_dwordx4 v[26:29], v105, s[16:19], s40 offen
	buffer_load_dwordx4 v[30:33], v105, s[16:19], s41 offen
	buffer_load_dwordx4 v[34:37], v106, s[16:19], s40 offen
	buffer_load_dwordx4 v[38:41], v106, s[16:19], s41 offen
; #define ATT_ADV(ui, s) do { ++(s); if ((s) >= att_unit_steps(F.bid + (ui) * F.G)) { (s) = 0; ++(ui); } } while (0)
; __device__ __forceinline__ void attn_prompt(Frame& F) {
;     ...
;     ATT_LOAD(pui, ps, kA, vA, qA); ATT_ADV(pui, ps);
;     ATT_LOAD(pui, ps, kB, vB, qB); ATT_ADV(pui, ps);
;     while (running) {
	buffer_load_dwordx4 v[2:5], v107, s[16:19], s42 offen
	buffer_load_dwordx4 v[6:9], v107, s[16:19], s42 offen offset:64
	buffer_store_dword v108, v108, s[16:19], 0 offen
	buffer_store_dword v108, v108, s[16:19], 0 offen
	buffer_store_dword v108, v108, s[16:19], 0 offen
	buffer_store_dword v108, v108, s[16:19], 0 offen
	buffer_store_dword v108, v108, s[16:19], 0 offen
	v_readlane_b32 s23, v104, 1
	s_nop 3
	s_bfe_u32 s36, s23, 0x20000
	s_bfe_u32 s37, s23, 0x40002
	s_bfe_u32 s38, s23, 0x60006
	s_bfe_u32 s39, s23, 0x8000c
	s_lshl_b32 s40, s36, 1
	s_lshr_b32 s40, 0x1000, s40
	s_mul_i32 s39, s39, s40
	s_add_i32 s38, s38, -1
	s_lshl_b32 s38, s38, 7
	s_add_i32 s39, s39, s38
	s_lshl_b32 s39, s39, 7
	s_mul_i32 s37, s37, 0x208000
	s_add_i32 s39, s39, s37
	s_bitcmp1_b32 s23, 21
	s_cselect_b32 s39, s39, 0x80000000
	s_mul_i32 s36, s36, 0x2100000
	s_add_i32 s40, s36, 0x16a00000
	s_add_i32 s41, s36, 0x1cd00000
	s_add_i32 s42, s36, 0x10700000
	v_add_u32_e32 v105, s39, v101
	v_add_u32_e32 v106, s39, v102
	v_add_u32_e32 v107, s39, v103
	buffer_load_dwordx4 v[42:45], v105, s[16:19], s40 offen
	buffer_load_dwordx4 v[46:49], v105, s[16:19], s41 offen
	buffer_load_dwordx4 v[50:53], v106, s[16:19], s40 offen
	buffer_load_dwordx4 v[54:57], v106, s[16:19], s41 offen
	buffer_load_dwordx4 v[10:13], v107, s[16:19], s42 offen
	buffer_load_dwordx4 v[14:17], v107, s[16:19], s42 offen offset:64
	buffer_store_dword v108, v108, s[16:19], 0 offen
	buffer_store_dword v108, v108, s[16:19], 0 offen
	buffer_store_dword v108, v108, s[16:19], 0 offen
	buffer_store_dword v108, v108, s[16:19], 0 offen
	buffer_store_dword v108, v108, s[16:19], 0 offen
	v_readlane_b32 s23, v104, 2
	s_nop 3
	s_bfe_u32 s36, s23, 0x20000
	s_bfe_u32 s37, s23, 0x40002
	s_bfe_u32 s38, s23, 0x60006
	s_bfe_u32 s39, s23, 0x8000c
	s_lshl_b32 s40, s36, 1
	s_lshr_b32 s40, 0x1000, s40
	s_mul_i32 s39, s39, s40
	s_add_i32 s38, s38, -1
	s_lshl_b32 s38, s38, 7
	s_add_i32 s39, s39, s38
	s_lshl_b32 s39, s39, 7
	s_mul_i32 s37, s37, 0x208000
	s_add_i32 s39, s39, s37
	s_bitcmp1_b32 s23, 21
	s_cselect_b32 s39, s39, 0x80000000
	s_mul_i32 s36, s36, 0x2100000
	s_add_i32 s40, s36, 0x16a00000
	s_add_i32 s41, s36, 0x1cd00000
	s_add_i32 s42, s36, 0x10700000
	v_add_u32_e32 v105, s39, v101
	v_add_u32_e32 v106, s39, v102
	v_add_u32_e32 v107, s39, v103
	buffer_load_dwordx4 v[110:113], v105, s[16:19], s40 offen
	buffer_load_dwordx4 v[114:117], v105, s[16:19], s41 offen
	buffer_load_dwordx4 v[118:121], v106, s[16:19], s40 offen
	buffer_load_dwordx4 v[122:125], v106, s[16:19], s41 offen
	buffer_load_dwordx4 v[126:129], v107, s[16:19], s42 offen
	buffer_load_dwordx4 v[130:133], v107, s[16:19], s42 offen offset:64
	buffer_store_dword v108, v108, s[16:19], 0 offen
	buffer_store_dword v108, v108, s[16:19], 0 offen
	buffer_store_dword v108, v108, s[16:19], 0 offen
	buffer_store_dword v108, v108, s[16:19], 0 offen
	buffer_store_dword v108, v108, s[16:19], 0 offen
	s_mov_b32 s20, 0
	s_mov_b32 s21, 0
	.p2align 6
; #define LAS __attribute__((address_space(3)))
; #define WG_BAR() asm volatile("s_waitcnt lgkmcnt(0)\n\ts_barrier" ::: "memory")
; #define ATT_ADV(ui, s) do { ++(s); if ((s) >= att_unit_steps(F.bid + (ui) * F.G)) { (s) = 0; ++(ui); } } while (0)
; __device__ __forceinline__ void attn_prompt(Frame& F) {
;     LAS unsigned char* L = F.lds; const int tid = F.tid, lane = F.lane, w = F.wave, r = lane & 15, g4 = lane >> 4;
;     __syncthreads();
;     for (int e = tid; e < 6 * AT_SLOT / 16; e += 512) *(LAS v4u*)(L + e * 16) = (v4u){0u, 0u, 0u, 0u};
;     WG_BAR();
;     const __amdgpu_buffer_rsrc_t wsr = __builtin_amdgcn_make_buffer_rsrc((void*)F.ws, (short)0, (int)WS_END, 0x00020000);
;     v4u kA[2], vA[2], kB[2], vB[2]; bf16x8 qA[2], qB[2];
; #pragma unroll
;     for (int i = 0; i < 2; ++i) { kA[i] = vA[i] = kB[i] = vB[i] = (v4u){0u, 0u, 0u, 0u}; qA[i] = qB[i] = (bf16x8){0, 0, 0, 0, 0, 0, 0, 0}; }
;     int cui = 0, cs = 0, pui = 0, ps = 0, nstep = 0; bool running = true;
;     ATT_LOAD(pui, ps, kA, vA, qA); ATT_ADV(pui, ps);
;     ATT_LOAD(pui, ps, kB, vB, qB); ATT_ADV(pui, ps);
;     while (running) {
;         ATT_STEP(kA, vA, qA);
;         if (!running) break;
;         ATT_STEP(kB, vB, qB);
;     }
.Lp9n_loop:
.Lp9n_stepA:
	s_add_i32 s23, s20, 3
	v_readlane_b32 s22, v104, s20
	v_readlane_b32 s23, v104, s23
	s_mul_i32 s24, s21, 0x4800
	s_waitcnt vmcnt(27)
	v_add_u32_e32 v109, s24, v100
	ds_write_b128 v109, v[26:29]
	ds_write_b128 v109, v[30:33] offset:55296
	ds_write_b128 v109, v[34:37] offset:9216
	ds_write_b128 v109, v[38:41] offset:64512
	v_mov_b64_e32 v[18:19], v[2:3]
	v_mov_b64_e32 v[20:21], v[4:5]
	v_mov_b64_e32 v[22:23], v[6:7]
	v_mov_b64_e32 v[24:25], v[8:9]
	s_waitcnt lgkmcnt(0)
	s_barrier
	s_bfe_u32 s36, s23, 0x20000
	s_bfe_u32 s37, s23, 0x40002
	s_bfe_u32 s38, s23, 0x60006
	s_bfe_u32 s39, s23, 0x8000c
	s_lshl_b32 s40, s36, 1
	s_lshr_b32 s40, 0x1000, s40
	s_mul_i32 s39, s39, s40
	s_add_i32 s38, s38, -1
	s_lshl_b32 s38, s38, 7
	s_add_i32 s39, s39, s38
	s_lshl_b32 s39, s39, 7
	s_mul_i32 s37, s37, 0x208000
	s_add_i32 s39, s39, s37
	s_bitcmp1_b32 s23, 21
	s_cselect_b32 s39, s39, 0x80000000
	s_mul_i32 s36, s36, 0x2100000
	s_add_i32 s40, s36, 0x16a00000
	s_add_i32 s41, s36, 0x1cd00000
	s_add_i32 s42, s36, 0x10700000
	v_add_u32_e32 v105, s39, v101
	v_add_u32_e32 v106, s39, v102
	v_add_u32_e32 v107, s39, v103
	buffer_load_dwordx4 v[26:29], v105, s[16:19], s40 offen
	buffer_load_dwordx4 v[30:33], v105, s[16:19], s41 offen
	buffer_load_dwordx4 v[34:37], v106, s[16:19], s40 offen
	buffer_load_dwordx4 v[38:41], v106, s[16:19], s41 offen
	buffer_load_dwordx4 v[2:5], v107, s[16:19], s42 offen
	buffer_load_dwordx4 v[6:9], v107, s[16:19], s42 offen offset:64
	s_bitcmp1_b32 s22, 20
	s_cbranch_scc0 .Lp9n_nocompA
	s_and_b32 s99, s22, 63
	s_bfe_u32 s4, s22, 0x60006
	s_add_i32 s4, s4, -1
	s_lshl_b32 s4, s4, 6
	s_or_b32 s99, s99, s4
	s_add_i32 s4, s21, -1
	s_cmp_lt_i32 s4, 0
	s_cselect_b32 s4, 2, s4
	s_lshl_b32 s4, s4, 3
	s_lshr_b32 s5, s33, 4
	s_add_i32 s4, s4, s5
	s_lshl_b32 s4, s4, 11
	s_or_b32 s99, s99, s4
	s_bfe_u32 s4, s22, 0x8000c
	s_lshl_b32 s4, s4, 17
	s_or_b32 s99, s99, s4
	s_bitset1_b32 s99, 26
	s_branch .Lat_tile
.Lp9n_nocompA:
	buffer_store_dword v108, v108, s[16:19], 0 offen
	buffer_store_dword v108, v108, s[16:19], 0 offen
	buffer_store_dword v108, v108, s[16:19], 0 offen
	buffer_store_dword v108, v108, s[16:19], 0 offen
	buffer_store_dword v108, v108, s[16:19], 0 offen
.Lp9n_retA:
	s_add_i32 s20, s20, 1
	s_add_i32 s21, s21, 1
	s_cmp_eq_u32 s21, 3
	s_cselect_b32 s21, 0, s21
.Lp9n_stepB:
	s_add_i32 s23, s20, 3
	v_readlane_b32 s22, v104, s20
	v_readlane_b32 s23, v104, s23
	s_mul_i32 s24, s21, 0x4800
	s_waitcnt vmcnt(27)
	v_add_u32_e32 v109, s24, v100
	ds_write_b128 v109, v[42:45]
	ds_write_b128 v109, v[46:49] offset:55296
	ds_write_b128 v109, v[50:53] offset:9216
	ds_write_b128 v109, v[54:57] offset:64512
	v_mov_b64_e32 v[18:19], v[10:11]
	v_mov_b64_e32 v[20:21], v[12:13]
	v_mov_b64_e32 v[22:23], v[14:15]
	v_mov_b64_e32 v[24:25], v[16:17]
	s_waitcnt lgkmcnt(0)
	s_barrier
	s_bfe_u32 s36, s23, 0x20000
	s_bfe_u32 s37, s23, 0x40002
	s_bfe_u32 s38, s23, 0x60006
	s_bfe_u32 s39, s23, 0x8000c
	s_lshl_b32 s40, s36, 1
	s_lshr_b32 s40, 0x1000, s40
	s_mul_i32 s39, s39, s40
	s_add_i32 s38, s38, -1
	s_lshl_b32 s38, s38, 7
	s_add_i32 s39, s39, s38
	s_lshl_b32 s39, s39, 7
	s_mul_i32 s37, s37, 0x208000
	s_add_i32 s39, s39, s37
	s_bitcmp1_b32 s23, 21
	s_cselect_b32 s39, s39, 0x80000000
	s_mul_i32 s36, s36, 0x2100000
	s_add_i32 s40, s36, 0x16a00000
	s_add_i32 s41, s36, 0x1cd00000
	s_add_i32 s42, s36, 0x10700000
	v_add_u32_e32 v105, s39, v101
	v_add_u32_e32 v106, s39, v102
	v_add_u32_e32 v107, s39, v103
	buffer_load_dwordx4 v[42:45], v105, s[16:19], s40 offen
	buffer_load_dwordx4 v[46:49], v105, s[16:19], s41 offen
	buffer_load_dwordx4 v[50:53], v106, s[16:19], s40 offen
	buffer_load_dwordx4 v[54:57], v106, s[16:19], s41 offen
	buffer_load_dwordx4 v[10:13], v107, s[16:19], s42 offen
	buffer_load_dwordx4 v[14:17], v107, s[16:19], s42 offen offset:64
	s_bitcmp1_b32 s22, 20
	s_cbranch_scc0 .Lp9n_nocompB
	s_and_b32 s99, s22, 63
	s_bfe_u32 s4, s22, 0x60006
	s_add_i32 s4, s4, -1
	s_lshl_b32 s4, s4, 6
	s_or_b32 s99, s99, s4
	s_add_i32 s4, s21, -1
	s_cmp_lt_i32 s4, 0
	s_cselect_b32 s4, 2, s4
	s_lshl_b32 s4, s4, 3
	s_lshr_b32 s5, s33, 4
	s_add_i32 s4, s4, s5
	s_lshl_b32 s4, s4, 11
	s_or_b32 s99, s99, s4
	s_bfe_u32 s4, s22, 0x8000c
	s_lshl_b32 s4, s4, 17
	s_or_b32 s99, s99, s4
	s_bitset1_b32 s99, 27
	s_branch .Lat_tile

.Lp9n_stepC:
	s_add_i32 s23, s20, 3
	v_readlane_b32 s22, v104, s20
	v_readlane_b32 s23, v104, s23
	s_mul_i32 s24, s21, 0x4800
	s_waitcnt vmcnt(27)
	v_add_u32_e32 v109, s24, v100
	ds_write_b128 v109, v[110:113]
	ds_write_b128 v109, v[114:117] offset:55296
	ds_write_b128 v109, v[118:121] offset:9216
	ds_write_b128 v109, v[122:125] offset:64512
	v_mov_b64_e32 v[18:19], v[126:127]
	v_mov_b64_e32 v[20:21], v[128:129]
	v_mov_b64_e32 v[22:23], v[130:131]
	v_mov_b64_e32 v[24:25], v[132:133]
	s_waitcnt lgkmcnt(0)
	s_barrier
	s_bfe_u32 s36, s23, 0x20000
	s_bfe_u32 s37, s23, 0x40002
	s_bfe_u32 s38, s23, 0x60006
	s_bfe_u32 s39, s23, 0x8000c
	s_lshl_b32 s40, s36, 1
	s_lshr_b32 s40, 0x1000, s40
	s_mul_i32 s39, s39, s40
	s_add_i32 s38, s38, -1
	s_lshl_b32 s38, s38, 7
	s_add_i32 s39, s39, s38
	s_lshl_b32 s39, s39, 7
	s_mul_i32 s37, s37, 0x208000
	s_add_i32 s39, s39, s37
	s_bitcmp1_b32 s23, 21
	s_cselect_b32 s39, s39, 0x80000000
	s_mul_i32 s36, s36, 0x2100000
	s_add_i32 s40, s36, 0x16a00000
	s_add_i32 s41, s36, 0x1cd00000
	s_add_i32 s42, s36, 0x10700000
	v_add_u32_e32 v105, s39, v101
	v_add_u32_e32 v106, s39, v102
	v_add_u32_e32 v107, s39, v103
	buffer_load_dwordx4 v[110:113], v105, s[16:19], s40 offen
	buffer_load_dwordx4 v[114:117], v105, s[16:19], s41 offen
	buffer_load_dwordx4 v[118:121], v106, s[16:19], s40 offen
	buffer_load_dwordx4 v[122:125], v106, s[16:19], s41 offen
	buffer_load_dwordx4 v[126:129], v107, s[16:19], s42 offen
	buffer_load_dwordx4 v[130:133], v107, s[16:19], s42 offen offset:64
	s_bitcmp1_b32 s22, 20
	s_cbranch_scc0 .Lp9n_nocompC
	s_and_b32 s99, s22, 63
	s_bfe_u32 s4, s22, 0x60006
	s_add_i32 s4, s4, -1
	s_lshl_b32 s4, s4, 6
	s_or_b32 s99, s99, s4
	s_add_i32 s4, s21, -1
	s_cmp_lt_i32 s4, 0
	s_cselect_b32 s4, 2, s4
	s_lshl_b32 s4, s4, 3
	s_lshr_b32 s5, s33, 4
	s_add_i32 s4, s4, s5
	s_lshl_b32 s4, s4, 11
	s_or_b32 s99, s99, s4
	s_bfe_u32 s4, s22, 0x8000c
	s_lshl_b32 s4, s4, 17
	s_or_b32 s99, s99, s4
	s_bitset1_b32 s99, 28
	s_branch .Lat_tile

; __device__ __forceinline__ void attn_prompt(Frame& F) {
;     ...
;     while (running) {
;         ATT_STEP(kA, vA, qA);
;         if (!running) break;
;         ATT_STEP(kB, vB, qB);
;     }
;     __syncthreads();
.Lp9n_retC:
	s_add_i32 s20, s20, 1
	s_add_i32 s21, s21, 1
	s_cmp_eq_u32 s21, 3
	s_cselect_b32 s21, 0, s21
	s_cmp_lt_u32 s20, 30
	s_cbranch_scc1 .Lp9n_loop
.LBB0_1690:
	v_readlane_b32 s6, v245, 29
	v_readlane_b32 s7, v245, 30
	s_waitcnt vmcnt(0) lgkmcnt(0)
	s_barrier

; __global__ void __launch_bounds__(512, 2) mega_fwd(Args args) {
	.amdhsa_kernel _Z8mega_fwd4Args
		.amdhsa_group_segment_fixed_size 0
		.amdhsa_private_segment_fixed_size 0
		.amdhsa_kernarg_size 448
		.amdhsa_user_sgpr_count 2
		.amdhsa_user_sgpr_dispatch_ptr 0
		.amdhsa_user_sgpr_queue_ptr 0
		.amdhsa_user_sgpr_kernarg_segment_ptr 1
		.amdhsa_user_sgpr_dispatch_id 0
		.amdhsa_user_sgpr_kernarg_preload_length 0
		.amdhsa_user_sgpr_kernarg_preload_offset 0
		.amdhsa_user_sgpr_private_segment_size 0
		.amdhsa_uses_dynamic_stack 0
		.amdhsa_enable_private_segment 0
		.amdhsa_system_sgpr_workgroup_id_x 1
		.amdhsa_system_sgpr_workgroup_id_y 0
		.amdhsa_system_sgpr_workgroup_id_z 0
		.amdhsa_system_sgpr_workgroup_info 0
		.amdhsa_system_vgpr_workitem_id 0
		.amdhsa_next_free_vgpr 256
		.amdhsa_next_free_sgpr 102
		.amdhsa_accum_offset 256
		.amdhsa_reserve_vcc 1
		.amdhsa_float_round_mode_32 0
		.amdhsa_float_round_mode_16_64 0
		.amdhsa_float_denorm_mode_32 3
		.amdhsa_float_denorm_mode_16_64 3
		.amdhsa_dx10_clamp 1
		.amdhsa_ieee_mode 1
		.amdhsa_fp16_overflow 0
		.amdhsa_tg_split 0
		.amdhsa_exception_fp_ieee_invalid_op 0
		.amdhsa_exception_fp_denorm_src 0
		.amdhsa_exception_fp_ieee_div_zero 0
		.amdhsa_exception_fp_ieee_overflow 0
		.amdhsa_exception_fp_ieee_underflow 0
		.amdhsa_exception_fp_ieee_inexact 0
		.amdhsa_exception_int_div_zero 0
	.end_amdhsa_kernel

; __global__ void __launch_bounds__(512, 2) mega_fwd(Args args) {
amdhsa.kernels:
  - .agpr_count:     0
    .args:
      - .offset:         0
        .size:           192
        .value_kind:     by_value
      - .offset:         192
        .size:           4
        .value_kind:     hidden_block_count_x
      - .offset:         196
        .size:           4
        .value_kind:     hidden_block_count_y
      - .offset:         200
        .size:           4
        .value_kind:     hidden_block_count_z
      - .offset:         204
        .size:           2
        .value_kind:     hidden_group_size_x
      - .offset:         206
        .size:           2
        .value_kind:     hidden_group_size_y
      - .offset:         208
        .size:           2
        .value_kind:     hidden_group_size_z
      - .offset:         210
        .size:           2
        .value_kind:     hidden_remainder_x
      - .offset:         212
        .size:           2
        .value_kind:     hidden_remainder_y
      - .offset:         214
        .size:           2
        .value_kind:     hidden_remainder_z
      - .offset:         232
        .size:           8
        .value_kind:     hidden_global_offset_x
      - .offset:         240
        .size:           8
        .value_kind:     hidden_global_offset_y
      - .offset:         248
        .size:           8
        .value_kind:     hidden_global_offset_z
      - .offset:         256
        .size:           2
        .value_kind:     hidden_grid_dims
      - .offset:         312
        .size:           4
        .value_kind:     hidden_dynamic_lds_size
    .group_segment_fixed_size: 0
    .kernarg_segment_align: 8
    .kernarg_segment_size: 448
    .language:       OpenCL C
    .language_version:
      - 2
      - 0
    .max_flat_workgroup_size: 512
    .name:           _Z8mega_fwd4Args
    .private_segment_fixed_size: 0
    .sgpr_count:     108
    .sgpr_spill_count: 62
    .symbol:         _Z8mega_fwd4Args.kd
    .uniform_work_group_size: 1
    .uses_dynamic_stack: false
    .vgpr_count:     256
    .vgpr_spill_count: 0
    .wavefront_size: 64
